# fixup loop unrolled 16x with loads up front; scan compute body hand-scheduled with LDS operand prefetch
# speedup vs baseline: 1.0440x; 1.0440x over previous
; __device__ __forceinline__ float bf2f(unsigned b) { return __uint_as_float(b << 16); }
; __device__ void phase_fixup(const float* FS, const bf16_t* Q, bf16_t* Y, float* sm) {
;     ...
;         for (int sg = tg; sg < 2048; sg += 8) {
;             const int g = 2048 * j + sg; const int t = dir ? (L - 1 - g) : g;
;             const size_t o = ((size_t)dir * TCH + (size_t)seq * L + t) * 512 + h * 64 + v;
;             qw[v] = bf2f(Q[o]);
.LBB0_40:
	v_add_u32_e32 v168, s28, v84
	v_add_u32_e32 v168, 0x808, v168
	v_cndmask_b32_e64 v168, v83, v168, s[12:13]
	v_ashrrev_i32_e32 v169, 31, v168
	v_lshl_add_u64 v[168:169], s[52:53], 0, v[168:169]
	v_lshlrev_b64 v[104:105], 10, v[168:169]
	v_lshl_or_b32 v104, v62, 1, v104
	v_lshl_add_u64 v[170:171], s[26:27], 0, v[104:105]
	global_load_ushort v136, v[170:171], off
	v_add_u32_e32 v168, s28, v84
	v_add_u32_e32 v168, 0x810, v168
	v_add_u32_e32 v169, -8, v83
	v_cndmask_b32_e64 v168, v169, v168, s[12:13]
	v_ashrrev_i32_e32 v169, 31, v168
	v_lshl_add_u64 v[168:169], s[52:53], 0, v[168:169]
	v_lshlrev_b64 v[106:107], 10, v[168:169]
	v_lshl_or_b32 v106, v62, 1, v106
	v_lshl_add_u64 v[170:171], s[26:27], 0, v[106:107]
	global_load_ushort v137, v[170:171], off
	v_add_u32_e32 v168, s28, v84
	v_add_u32_e32 v168, 0x818, v168
	v_add_u32_e32 v169, -16, v83
	v_cndmask_b32_e64 v168, v169, v168, s[12:13]
	v_ashrrev_i32_e32 v169, 31, v168
	v_lshl_add_u64 v[168:169], s[52:53], 0, v[168:169]
	v_lshlrev_b64 v[108:109], 10, v[168:169]
	v_lshl_or_b32 v108, v62, 1, v108
	v_lshl_add_u64 v[170:171], s[26:27], 0, v[108:109]
	global_load_ushort v138, v[170:171], off
	v_add_u32_e32 v168, s28, v84
	v_add_u32_e32 v168, 0x820, v168
	v_add_u32_e32 v169, -24, v83
	v_cndmask_b32_e64 v168, v169, v168, s[12:13]
	v_ashrrev_i32_e32 v169, 31, v168
	v_lshl_add_u64 v[168:169], s[52:53], 0, v[168:169]
	v_lshlrev_b64 v[110:111], 10, v[168:169]
	v_lshl_or_b32 v110, v62, 1, v110
	v_lshl_add_u64 v[170:171], s[26:27], 0, v[110:111]
	global_load_ushort v139, v[170:171], off
	v_add_u32_e32 v168, s28, v84
	v_add_u32_e32 v168, 0x828, v168
	v_add_u32_e32 v169, -32, v83
	v_cndmask_b32_e64 v168, v169, v168, s[12:13]
	v_ashrrev_i32_e32 v169, 31, v168
	v_lshl_add_u64 v[168:169], s[52:53], 0, v[168:169]
	v_lshlrev_b64 v[112:113], 10, v[168:169]
	v_lshl_or_b32 v112, v62, 1, v112
	v_lshl_add_u64 v[170:171], s[26:27], 0, v[112:113]
	global_load_ushort v140, v[170:171], off
	v_add_u32_e32 v168, s28, v84
	v_add_u32_e32 v168, 0x830, v168
	v_add_u32_e32 v169, -40, v83
	v_cndmask_b32_e64 v168, v169, v168, s[12:13]
	v_ashrrev_i32_e32 v169, 31, v168
	v_lshl_add_u64 v[168:169], s[52:53], 0, v[168:169]
	v_lshlrev_b64 v[114:115], 10, v[168:169]
	v_lshl_or_b32 v114, v62, 1, v114
	v_lshl_add_u64 v[170:171], s[26:27], 0, v[114:115]
	global_load_ushort v141, v[170:171], off
	v_add_u32_e32 v168, s28, v84
	v_add_u32_e32 v168, 0x838, v168
	v_add_u32_e32 v169, -48, v83
	v_cndmask_b32_e64 v168, v169, v168, s[12:13]
	v_ashrrev_i32_e32 v169, 31, v168
	v_lshl_add_u64 v[168:169], s[52:53], 0, v[168:169]
	v_lshlrev_b64 v[116:117], 10, v[168:169]
	v_lshl_or_b32 v116, v62, 1, v116
	v_lshl_add_u64 v[170:171], s[26:27], 0, v[116:117]
	global_load_ushort v142, v[170:171], off
	v_add_u32_e32 v168, s28, v84
	v_add_u32_e32 v168, 0x840, v168
	v_add_u32_e32 v169, -56, v83
	v_cndmask_b32_e64 v168, v169, v168, s[12:13]
	v_ashrrev_i32_e32 v169, 31, v168
	v_lshl_add_u64 v[168:169], s[52:53], 0, v[168:169]
	v_lshlrev_b64 v[118:119], 10, v[168:169]
	v_lshl_or_b32 v118, v62, 1, v118
	v_lshl_add_u64 v[170:171], s[26:27], 0, v[118:119]
	global_load_ushort v143, v[170:171], off
	v_add_u32_e32 v168, s28, v84
	v_add_u32_e32 v168, 0x848, v168
	v_add_u32_e32 v169, -64, v83
	v_cndmask_b32_e64 v168, v169, v168, s[12:13]
	v_ashrrev_i32_e32 v169, 31, v168
	v_lshl_add_u64 v[168:169], s[52:53], 0, v[168:169]
	v_lshlrev_b64 v[120:121], 10, v[168:169]
	v_lshl_or_b32 v120, v62, 1, v120
	v_lshl_add_u64 v[170:171], s[26:27], 0, v[120:121]
	global_load_ushort v144, v[170:171], off
	v_add_u32_e32 v168, s28, v84
	v_add_u32_e32 v168, 0x850, v168
	v_add_u32_e32 v169, -72, v83
	v_cndmask_b32_e64 v168, v169, v168, s[12:13]
	v_ashrrev_i32_e32 v169, 31, v168
	v_lshl_add_u64 v[168:169], s[52:53], 0, v[168:169]
	v_lshlrev_b64 v[122:123], 10, v[168:169]
	v_lshl_or_b32 v122, v62, 1, v122
	v_lshl_add_u64 v[170:171], s[26:27], 0, v[122:123]
	global_load_ushort v145, v[170:171], off
	v_add_u32_e32 v168, s28, v84
	v_add_u32_e32 v168, 0x858, v168
	v_add_u32_e32 v169, -80, v83
	v_cndmask_b32_e64 v168, v169, v168, s[12:13]
	v_ashrrev_i32_e32 v169, 31, v168
	v_lshl_add_u64 v[168:169], s[52:53], 0, v[168:169]
	v_lshlrev_b64 v[124:125], 10, v[168:169]
	v_lshl_or_b32 v124, v62, 1, v124
	v_lshl_add_u64 v[170:171], s[26:27], 0, v[124:125]
	global_load_ushort v146, v[170:171], off
	v_add_u32_e32 v168, s28, v84
	v_add_u32_e32 v168, 0x860, v168
	v_add_u32_e32 v169, -88, v83
	v_cndmask_b32_e64 v168, v169, v168, s[12:13]
	v_ashrrev_i32_e32 v169, 31, v168
	v_lshl_add_u64 v[168:169], s[52:53], 0, v[168:169]
	v_lshlrev_b64 v[126:127], 10, v[168:169]
	v_lshl_or_b32 v126, v62, 1, v126
	v_lshl_add_u64 v[170:171], s[26:27], 0, v[126:127]
	global_load_ushort v147, v[170:171], off
	v_add_u32_e32 v168, s28, v84
	v_add_u32_e32 v168, 0x868, v168
	v_add_u32_e32 v169, -96, v83
	v_cndmask_b32_e64 v168, v169, v168, s[12:13]
	v_ashrrev_i32_e32 v169, 31, v168
	v_lshl_add_u64 v[168:169], s[52:53], 0, v[168:169]
	v_lshlrev_b64 v[128:129], 10, v[168:169]
	v_lshl_or_b32 v128, v62, 1, v128
	v_lshl_add_u64 v[170:171], s[26:27], 0, v[128:129]
	global_load_ushort v148, v[170:171], off
	v_add_u32_e32 v168, s28, v84
	v_add_u32_e32 v168, 0x870, v168
	v_add_u32_e32 v169, -104, v83
	v_cndmask_b32_e64 v168, v169, v168, s[12:13]
	v_ashrrev_i32_e32 v169, 31, v168
	v_lshl_add_u64 v[168:169], s[52:53], 0, v[168:169]
	v_lshlrev_b64 v[130:131], 10, v[168:169]
	v_lshl_or_b32 v130, v62, 1, v130
	v_lshl_add_u64 v[170:171], s[26:27], 0, v[130:131]
	global_load_ushort v149, v[170:171], off
	v_add_u32_e32 v168, s28, v84
	v_add_u32_e32 v168, 0x878, v168
	v_add_u32_e32 v169, -112, v83
	v_cndmask_b32_e64 v168, v169, v168, s[12:13]
; __device__ __forceinline__ bf16_t f2bf(float f) { unsigned u = __float_as_uint(f); u += 0x7FFFu + ((u >> 16) & 1u); return (bf16_t)(u >> 16); }
; __device__ __forceinline__ float bf2f(unsigned b) { return __uint_as_float(b << 16); }
; __device__ void phase_fixup(const float* FS, const bf16_t* Q, bf16_t* Y, float* sm) {
;     ...
;         for (int sg = tg; sg < 2048; sg += 8) {
;             const int g = 2048 * j + sg; const int t = dir ? (L - 1 - g) : g;
;             const size_t o = ((size_t)dir * TCH + (size_t)seq * L + t) * 512 + h * 64 + v;
;             qw[v] = bf2f(Q[o]);
;             __builtin_amdgcn_wave_barrier(); asm volatile("s_waitcnt lgkmcnt(0)" ::: "memory");
;             float acc = 0.f;
; #pragma unroll
;             for (int m4 = 0; m4 < 16; ++m4) { const f32x4 qq = *(const f32x4*)(qw + 4 * m4); acc += s0[4 * m4] * qq[0] + s0[4 * m4 + 1] * qq[1] + s0[4 * m4 + 2] * qq[2] + s0[4 * m4 + 3] * qq[3]; }
;             __builtin_amdgcn_wave_barrier();
;             Y[o] = f2bf(bf2f(Y[o]) + acc);
;         }
	v_ashrrev_i32_e32 v169, 31, v168
	v_lshl_add_u64 v[168:169], s[52:53], 0, v[168:169]
	v_lshlrev_b64 v[132:133], 10, v[168:169]
	v_lshl_or_b32 v132, v62, 1, v132
	v_lshl_add_u64 v[170:171], s[26:27], 0, v[132:133]
	global_load_ushort v150, v[170:171], off
	v_add_u32_e32 v168, s28, v84
	v_add_u32_e32 v168, 0x880, v168
	v_add_u32_e32 v169, -120, v83
	v_cndmask_b32_e64 v168, v169, v168, s[12:13]
	v_ashrrev_i32_e32 v169, 31, v168
	v_lshl_add_u64 v[168:169], s[52:53], 0, v[168:169]
	v_lshlrev_b64 v[134:135], 10, v[168:169]
	v_lshl_or_b32 v134, v62, 1, v134
	v_lshl_add_u64 v[170:171], s[26:27], 0, v[134:135]
	global_load_ushort v151, v[170:171], off
	v_lshl_add_u64 v[170:171], s[34:35], 0, v[104:105]
	global_load_ushort v152, v[170:171], off
	v_lshl_add_u64 v[170:171], s[34:35], 0, v[106:107]
	global_load_ushort v153, v[170:171], off
	v_lshl_add_u64 v[170:171], s[34:35], 0, v[108:109]
	global_load_ushort v154, v[170:171], off
	v_lshl_add_u64 v[170:171], s[34:35], 0, v[110:111]
	global_load_ushort v155, v[170:171], off
	v_lshl_add_u64 v[170:171], s[34:35], 0, v[112:113]
	global_load_ushort v156, v[170:171], off
	v_lshl_add_u64 v[170:171], s[34:35], 0, v[114:115]
	global_load_ushort v157, v[170:171], off
	v_lshl_add_u64 v[170:171], s[34:35], 0, v[116:117]
	global_load_ushort v158, v[170:171], off
	v_lshl_add_u64 v[170:171], s[34:35], 0, v[118:119]
	global_load_ushort v159, v[170:171], off
	v_lshl_add_u64 v[170:171], s[34:35], 0, v[120:121]
	global_load_ushort v160, v[170:171], off
	v_lshl_add_u64 v[170:171], s[34:35], 0, v[122:123]
	global_load_ushort v161, v[170:171], off
	v_lshl_add_u64 v[170:171], s[34:35], 0, v[124:125]
	global_load_ushort v162, v[170:171], off
	v_lshl_add_u64 v[170:171], s[34:35], 0, v[126:127]
	global_load_ushort v163, v[170:171], off
	v_lshl_add_u64 v[170:171], s[34:35], 0, v[128:129]
	global_load_ushort v164, v[170:171], off
	v_lshl_add_u64 v[170:171], s[34:35], 0, v[130:131]
	global_load_ushort v165, v[170:171], off
	v_lshl_add_u64 v[170:171], s[34:35], 0, v[132:133]
	global_load_ushort v166, v[170:171], off
	v_lshl_add_u64 v[170:171], s[34:35], 0, v[134:135]
	global_load_ushort v167, v[170:171], off
	v_add_u32_e32 v84, 128, v84
	s_movk_i32 s14, 0x7f7
	v_cmp_lt_i32_e64 s[14:15], s14, v84
	v_add_u32_e32 v83, -128, v83
	s_or_b64 s[54:55], s[14:15], s[54:55]
	s_waitcnt vmcnt(31)
	v_lshlrev_b32_e32 v85, 16, v136
	ds_write_b32 v78, v85 offset:33280
	s_waitcnt lgkmcnt(0)
	ds_read_b128 v[196:199], v77 offset:33280
	ds_read_b128 v[200:203], v77 offset:33296
	ds_read_b128 v[204:207], v77 offset:33312
	ds_read_b128 v[208:211], v77 offset:33328
	ds_read_b128 v[212:215], v77 offset:33344
	ds_read_b128 v[216:219], v77 offset:33360
	ds_read_b128 v[220:223], v77 offset:33376
	ds_read_b128 v[224:227], v77 offset:33392
	s_waitcnt lgkmcnt(4)
	v_mul_f32_e32 v86, v2, v196
	v_mul_f32_e32 v87, v3, v197
	v_mul_f32_e32 v88, v4, v198
	v_mul_f32_e32 v89, v5, v199
	v_fmac_f32_e32 v86, v6, v200
	v_fmac_f32_e32 v87, v7, v201
	v_fmac_f32_e32 v88, v8, v202
	v_fmac_f32_e32 v89, v9, v203
	v_fmac_f32_e32 v86, v18, v204
	v_fmac_f32_e32 v87, v19, v205
	v_fmac_f32_e32 v88, v20, v206
	v_fmac_f32_e32 v89, v21, v207
	v_fmac_f32_e32 v86, v22, v208
	v_fmac_f32_e32 v87, v23, v209
	v_fmac_f32_e32 v88, v24, v210
	v_fmac_f32_e32 v89, v25, v211
	ds_read_b128 v[228:231], v77 offset:33408
	ds_read_b128 v[232:235], v77 offset:33424
	ds_read_b128 v[236:239], v77 offset:33440
	ds_read_b128 v[240:243], v77 offset:33456
	s_waitcnt lgkmcnt(4)
	v_fmac_f32_e32 v86, v26, v212
	v_fmac_f32_e32 v87, v27, v213
	v_fmac_f32_e32 v88, v28, v214
	v_fmac_f32_e32 v89, v29, v215
	v_fmac_f32_e32 v86, v30, v216
	v_fmac_f32_e32 v87, v31, v217
	v_fmac_f32_e32 v88, v32, v218
	v_fmac_f32_e32 v89, v33, v219
	v_fmac_f32_e32 v86, v34, v220
	v_fmac_f32_e32 v87, v35, v221
	v_fmac_f32_e32 v88, v36, v222
	v_fmac_f32_e32 v89, v37, v223
	v_fmac_f32_e32 v86, v38, v224
	v_fmac_f32_e32 v87, v39, v225
	v_fmac_f32_e32 v88, v40, v226
	v_fmac_f32_e32 v89, v41, v227
	ds_read_b128 v[196:199], v77 offset:33472
	ds_read_b128 v[200:203], v77 offset:33488
	ds_read_b128 v[204:207], v77 offset:33504
	ds_read_b128 v[208:211], v77 offset:33520
	s_waitcnt lgkmcnt(4)
	v_fmac_f32_e32 v86, v42, v228
	v_fmac_f32_e32 v87, v43, v229
	v_fmac_f32_e32 v88, v44, v230
	v_fmac_f32_e32 v89, v45, v231
	v_fmac_f32_e32 v86, v46, v232
	v_fmac_f32_e32 v87, v47, v233
	v_fmac_f32_e32 v88, v48, v234
	v_fmac_f32_e32 v89, v49, v235
	v_fmac_f32_e32 v86, v74, v236
	v_fmac_f32_e32 v87, v58, v237
	v_fmac_f32_e32 v88, v60, v238
	v_fmac_f32_e32 v89, v72, v239
	v_fmac_f32_e32 v86, v75, v240
	v_fmac_f32_e32 v87, v59, v241
	v_fmac_f32_e32 v88, v61, v242
	v_fmac_f32_e32 v89, v73, v243
	s_waitcnt lgkmcnt(0)
	v_fmac_f32_e32 v86, v70, v196
	v_fmac_f32_e32 v87, v54, v197
	v_fmac_f32_e32 v88, v56, v198
	v_fmac_f32_e32 v89, v68, v199
	v_fmac_f32_e32 v86, v71, v200
	v_fmac_f32_e32 v87, v55, v201
	v_fmac_f32_e32 v88, v57, v202
	v_fmac_f32_e32 v89, v69, v203
	v_fmac_f32_e32 v86, v66, v204
	v_fmac_f32_e32 v87, v50, v205
	v_fmac_f32_e32 v88, v52, v206
	v_fmac_f32_e32 v89, v64, v207
	v_fmac_f32_e32 v86, v67, v208
	v_fmac_f32_e32 v87, v51, v209
	v_fmac_f32_e32 v88, v53, v210
	v_fmac_f32_e32 v89, v65, v211
	v_add_f32_e32 v86, v86, v87
	v_add_f32_e32 v88, v88, v89
	s_waitcnt vmcnt(15)
	v_lshlrev_b32_e32 v87, 16, v152
	v_add_f32_e32 v86, v86, v88
	v_lshl_add_u64 v[170:171], s[34:35], 0, v[104:105]
	v_add_f32_e32 v86, v86, v87
	v_bfe_u32 v87, v86, 16, 1
	v_add3_u32 v86, v86, v87, s46
	global_store_short_d16_hi v[170:171], v86, off
	s_waitcnt vmcnt(31)
	v_lshlrev_b32_e32 v85, 16, v137
	ds_write_b32 v78, v85 offset:33280
	s_waitcnt lgkmcnt(0)
; __device__ __forceinline__ bf16_t f2bf(float f) { unsigned u = __float_as_uint(f); u += 0x7FFFu + ((u >> 16) & 1u); return (bf16_t)(u >> 16); }
; __device__ __forceinline__ float bf2f(unsigned b) { return __uint_as_float(b << 16); }
; __device__ void phase_fixup(const float* FS, const bf16_t* Q, bf16_t* Y, float* sm) {
;     ...
;             qw[v] = bf2f(Q[o]);
;             __builtin_amdgcn_wave_barrier(); asm volatile("s_waitcnt lgkmcnt(0)" ::: "memory");
;             float acc = 0.f;
; #pragma unroll
;             for (int m4 = 0; m4 < 16; ++m4) { const f32x4 qq = *(const f32x4*)(qw + 4 * m4); acc += s0[4 * m4] * qq[0] + s0[4 * m4 + 1] * qq[1] + s0[4 * m4 + 2] * qq[2] + s0[4 * m4 + 3] * qq[3]; }
;             __builtin_amdgcn_wave_barrier();
;             Y[o] = f2bf(bf2f(Y[o]) + acc);
	ds_read_b128 v[196:199], v77 offset:33280
	ds_read_b128 v[200:203], v77 offset:33296
	ds_read_b128 v[204:207], v77 offset:33312
	ds_read_b128 v[208:211], v77 offset:33328
	ds_read_b128 v[212:215], v77 offset:33344
	ds_read_b128 v[216:219], v77 offset:33360
	ds_read_b128 v[220:223], v77 offset:33376
	ds_read_b128 v[224:227], v77 offset:33392
	s_waitcnt lgkmcnt(4)
	v_mul_f32_e32 v90, v2, v196
	v_mul_f32_e32 v91, v3, v197
	v_mul_f32_e32 v92, v4, v198
	v_mul_f32_e32 v93, v5, v199
	v_fmac_f32_e32 v90, v6, v200
	v_fmac_f32_e32 v91, v7, v201
	v_fmac_f32_e32 v92, v8, v202
	v_fmac_f32_e32 v93, v9, v203
	v_fmac_f32_e32 v90, v18, v204
	v_fmac_f32_e32 v91, v19, v205
	v_fmac_f32_e32 v92, v20, v206
	v_fmac_f32_e32 v93, v21, v207
	v_fmac_f32_e32 v90, v22, v208
	v_fmac_f32_e32 v91, v23, v209
	v_fmac_f32_e32 v92, v24, v210
	v_fmac_f32_e32 v93, v25, v211
	ds_read_b128 v[228:231], v77 offset:33408
	ds_read_b128 v[232:235], v77 offset:33424
	ds_read_b128 v[236:239], v77 offset:33440
	ds_read_b128 v[240:243], v77 offset:33456
	s_waitcnt lgkmcnt(4)
	v_fmac_f32_e32 v90, v26, v212
	v_fmac_f32_e32 v91, v27, v213
	v_fmac_f32_e32 v92, v28, v214
	v_fmac_f32_e32 v93, v29, v215
	v_fmac_f32_e32 v90, v30, v216
	v_fmac_f32_e32 v91, v31, v217
	v_fmac_f32_e32 v92, v32, v218
	v_fmac_f32_e32 v93, v33, v219
	v_fmac_f32_e32 v90, v34, v220
	v_fmac_f32_e32 v91, v35, v221
	v_fmac_f32_e32 v92, v36, v222
	v_fmac_f32_e32 v93, v37, v223
	v_fmac_f32_e32 v90, v38, v224
	v_fmac_f32_e32 v91, v39, v225
	v_fmac_f32_e32 v92, v40, v226
	v_fmac_f32_e32 v93, v41, v227
	ds_read_b128 v[196:199], v77 offset:33472
	ds_read_b128 v[200:203], v77 offset:33488
	ds_read_b128 v[204:207], v77 offset:33504
	ds_read_b128 v[208:211], v77 offset:33520
	s_waitcnt lgkmcnt(4)
	v_fmac_f32_e32 v90, v42, v228
	v_fmac_f32_e32 v91, v43, v229
	v_fmac_f32_e32 v92, v44, v230
	v_fmac_f32_e32 v93, v45, v231
	v_fmac_f32_e32 v90, v46, v232
	v_fmac_f32_e32 v91, v47, v233
	v_fmac_f32_e32 v92, v48, v234
	v_fmac_f32_e32 v93, v49, v235
	v_fmac_f32_e32 v90, v74, v236
	v_fmac_f32_e32 v91, v58, v237
	v_fmac_f32_e32 v92, v60, v238
	v_fmac_f32_e32 v93, v72, v239
	v_fmac_f32_e32 v90, v75, v240
	v_fmac_f32_e32 v91, v59, v241
	v_fmac_f32_e32 v92, v61, v242
	v_fmac_f32_e32 v93, v73, v243
	s_waitcnt lgkmcnt(0)
	v_fmac_f32_e32 v90, v70, v196
	v_fmac_f32_e32 v91, v54, v197
	v_fmac_f32_e32 v92, v56, v198
	v_fmac_f32_e32 v93, v68, v199
	v_fmac_f32_e32 v90, v71, v200
	v_fmac_f32_e32 v91, v55, v201
	v_fmac_f32_e32 v92, v57, v202
	v_fmac_f32_e32 v93, v69, v203
	v_fmac_f32_e32 v90, v66, v204
	v_fmac_f32_e32 v91, v50, v205
	v_fmac_f32_e32 v92, v52, v206
	v_fmac_f32_e32 v93, v64, v207
	v_fmac_f32_e32 v90, v67, v208
	v_fmac_f32_e32 v91, v51, v209
	v_fmac_f32_e32 v92, v53, v210
	v_fmac_f32_e32 v93, v65, v211
	v_add_f32_e32 v90, v90, v91
	v_add_f32_e32 v92, v92, v93
	s_waitcnt vmcnt(15)
	v_lshlrev_b32_e32 v91, 16, v153
	v_add_f32_e32 v90, v90, v92
	v_lshl_add_u64 v[170:171], s[34:35], 0, v[106:107]
	v_add_f32_e32 v90, v90, v91
	v_bfe_u32 v91, v90, 16, 1
	v_add3_u32 v90, v90, v91, s46
	global_store_short_d16_hi v[170:171], v90, off
	s_waitcnt vmcnt(31)
	v_lshlrev_b32_e32 v85, 16, v138
	ds_write_b32 v78, v85 offset:33280
	s_waitcnt lgkmcnt(0)
	ds_read_b128 v[196:199], v77 offset:33280
	ds_read_b128 v[200:203], v77 offset:33296
	ds_read_b128 v[204:207], v77 offset:33312
	ds_read_b128 v[208:211], v77 offset:33328
	ds_read_b128 v[212:215], v77 offset:33344
	ds_read_b128 v[216:219], v77 offset:33360
	ds_read_b128 v[220:223], v77 offset:33376
	ds_read_b128 v[224:227], v77 offset:33392
	s_waitcnt lgkmcnt(4)
	v_mul_f32_e32 v86, v2, v196
	v_mul_f32_e32 v87, v3, v197
	v_mul_f32_e32 v88, v4, v198
	v_mul_f32_e32 v89, v5, v199
	v_fmac_f32_e32 v86, v6, v200
	v_fmac_f32_e32 v87, v7, v201
	v_fmac_f32_e32 v88, v8, v202
	v_fmac_f32_e32 v89, v9, v203
	v_fmac_f32_e32 v86, v18, v204
	v_fmac_f32_e32 v87, v19, v205
	v_fmac_f32_e32 v88, v20, v206
	v_fmac_f32_e32 v89, v21, v207
	v_fmac_f32_e32 v86, v22, v208
	v_fmac_f32_e32 v87, v23, v209
	v_fmac_f32_e32 v88, v24, v210
	v_fmac_f32_e32 v89, v25, v211
	ds_read_b128 v[228:231], v77 offset:33408
	ds_read_b128 v[232:235], v77 offset:33424
	ds_read_b128 v[236:239], v77 offset:33440
	ds_read_b128 v[240:243], v77 offset:33456
	s_waitcnt lgkmcnt(4)
	v_fmac_f32_e32 v86, v26, v212
	v_fmac_f32_e32 v87, v27, v213
	v_fmac_f32_e32 v88, v28, v214
	v_fmac_f32_e32 v89, v29, v215
	v_fmac_f32_e32 v86, v30, v216
	v_fmac_f32_e32 v87, v31, v217
	v_fmac_f32_e32 v88, v32, v218
	v_fmac_f32_e32 v89, v33, v219
	v_fmac_f32_e32 v86, v34, v220
	v_fmac_f32_e32 v87, v35, v221
	v_fmac_f32_e32 v88, v36, v222
	v_fmac_f32_e32 v89, v37, v223
	v_fmac_f32_e32 v86, v38, v224
	v_fmac_f32_e32 v87, v39, v225
	v_fmac_f32_e32 v88, v40, v226
	v_fmac_f32_e32 v89, v41, v227
	ds_read_b128 v[196:199], v77 offset:33472
	ds_read_b128 v[200:203], v77 offset:33488
	ds_read_b128 v[204:207], v77 offset:33504
	ds_read_b128 v[208:211], v77 offset:33520
	s_waitcnt lgkmcnt(4)
	v_fmac_f32_e32 v86, v42, v228
	v_fmac_f32_e32 v87, v43, v229
	v_fmac_f32_e32 v88, v44, v230
	v_fmac_f32_e32 v89, v45, v231
	v_fmac_f32_e32 v86, v46, v232
	v_fmac_f32_e32 v87, v47, v233
	v_fmac_f32_e32 v88, v48, v234
	v_fmac_f32_e32 v89, v49, v235
	v_fmac_f32_e32 v86, v74, v236
	v_fmac_f32_e32 v87, v58, v237
	v_fmac_f32_e32 v88, v60, v238
	v_fmac_f32_e32 v89, v72, v239
	v_fmac_f32_e32 v86, v75, v240
	v_fmac_f32_e32 v87, v59, v241
	v_fmac_f32_e32 v88, v61, v242
	v_fmac_f32_e32 v89, v73, v243
	s_waitcnt lgkmcnt(0)
; __device__ __forceinline__ bf16_t f2bf(float f) { unsigned u = __float_as_uint(f); u += 0x7FFFu + ((u >> 16) & 1u); return (bf16_t)(u >> 16); }
; __device__ __forceinline__ float bf2f(unsigned b) { return __uint_as_float(b << 16); }
; __device__ void phase_fixup(const float* FS, const bf16_t* Q, bf16_t* Y, float* sm) {
;     ...
;             qw[v] = bf2f(Q[o]);
;             __builtin_amdgcn_wave_barrier(); asm volatile("s_waitcnt lgkmcnt(0)" ::: "memory");
;             float acc = 0.f;
; #pragma unroll
;             for (int m4 = 0; m4 < 16; ++m4) { const f32x4 qq = *(const f32x4*)(qw + 4 * m4); acc += s0[4 * m4] * qq[0] + s0[4 * m4 + 1] * qq[1] + s0[4 * m4 + 2] * qq[2] + s0[4 * m4 + 3] * qq[3]; }
;             __builtin_amdgcn_wave_barrier();
;             Y[o] = f2bf(bf2f(Y[o]) + acc);
	v_fmac_f32_e32 v86, v70, v196
	v_fmac_f32_e32 v87, v54, v197
	v_fmac_f32_e32 v88, v56, v198
	v_fmac_f32_e32 v89, v68, v199
	v_fmac_f32_e32 v86, v71, v200
	v_fmac_f32_e32 v87, v55, v201
	v_fmac_f32_e32 v88, v57, v202
	v_fmac_f32_e32 v89, v69, v203
	v_fmac_f32_e32 v86, v66, v204
	v_fmac_f32_e32 v87, v50, v205
	v_fmac_f32_e32 v88, v52, v206
	v_fmac_f32_e32 v89, v64, v207
	v_fmac_f32_e32 v86, v67, v208
	v_fmac_f32_e32 v87, v51, v209
	v_fmac_f32_e32 v88, v53, v210
	v_fmac_f32_e32 v89, v65, v211
	v_add_f32_e32 v86, v86, v87
	v_add_f32_e32 v88, v88, v89
	s_waitcnt vmcnt(15)
	v_lshlrev_b32_e32 v87, 16, v154
	v_add_f32_e32 v86, v86, v88
	v_lshl_add_u64 v[170:171], s[34:35], 0, v[108:109]
	v_add_f32_e32 v86, v86, v87
	v_bfe_u32 v87, v86, 16, 1
	v_add3_u32 v86, v86, v87, s46
	global_store_short_d16_hi v[170:171], v86, off
	s_waitcnt vmcnt(31)
	v_lshlrev_b32_e32 v85, 16, v139
	ds_write_b32 v78, v85 offset:33280
	s_waitcnt lgkmcnt(0)
	ds_read_b128 v[196:199], v77 offset:33280
	ds_read_b128 v[200:203], v77 offset:33296
	ds_read_b128 v[204:207], v77 offset:33312
	ds_read_b128 v[208:211], v77 offset:33328
	ds_read_b128 v[212:215], v77 offset:33344
	ds_read_b128 v[216:219], v77 offset:33360
	ds_read_b128 v[220:223], v77 offset:33376
	ds_read_b128 v[224:227], v77 offset:33392
	s_waitcnt lgkmcnt(4)
	v_mul_f32_e32 v90, v2, v196
	v_mul_f32_e32 v91, v3, v197
	v_mul_f32_e32 v92, v4, v198
	v_mul_f32_e32 v93, v5, v199
	v_fmac_f32_e32 v90, v6, v200
	v_fmac_f32_e32 v91, v7, v201
	v_fmac_f32_e32 v92, v8, v202
	v_fmac_f32_e32 v93, v9, v203
	v_fmac_f32_e32 v90, v18, v204
	v_fmac_f32_e32 v91, v19, v205
	v_fmac_f32_e32 v92, v20, v206
	v_fmac_f32_e32 v93, v21, v207
	v_fmac_f32_e32 v90, v22, v208
	v_fmac_f32_e32 v91, v23, v209
	v_fmac_f32_e32 v92, v24, v210
	v_fmac_f32_e32 v93, v25, v211
	ds_read_b128 v[228:231], v77 offset:33408
	ds_read_b128 v[232:235], v77 offset:33424
	ds_read_b128 v[236:239], v77 offset:33440
	ds_read_b128 v[240:243], v77 offset:33456
	s_waitcnt lgkmcnt(4)
	v_fmac_f32_e32 v90, v26, v212
	v_fmac_f32_e32 v91, v27, v213
	v_fmac_f32_e32 v92, v28, v214
	v_fmac_f32_e32 v93, v29, v215
	v_fmac_f32_e32 v90, v30, v216
	v_fmac_f32_e32 v91, v31, v217
	v_fmac_f32_e32 v92, v32, v218
	v_fmac_f32_e32 v93, v33, v219
	v_fmac_f32_e32 v90, v34, v220
	v_fmac_f32_e32 v91, v35, v221
	v_fmac_f32_e32 v92, v36, v222
	v_fmac_f32_e32 v93, v37, v223
	v_fmac_f32_e32 v90, v38, v224
	v_fmac_f32_e32 v91, v39, v225
	v_fmac_f32_e32 v92, v40, v226
	v_fmac_f32_e32 v93, v41, v227
	ds_read_b128 v[196:199], v77 offset:33472
	ds_read_b128 v[200:203], v77 offset:33488
	ds_read_b128 v[204:207], v77 offset:33504
	ds_read_b128 v[208:211], v77 offset:33520
	s_waitcnt lgkmcnt(4)
	v_fmac_f32_e32 v90, v42, v228
	v_fmac_f32_e32 v91, v43, v229
	v_fmac_f32_e32 v92, v44, v230
	v_fmac_f32_e32 v93, v45, v231
	v_fmac_f32_e32 v90, v46, v232
	v_fmac_f32_e32 v91, v47, v233
	v_fmac_f32_e32 v92, v48, v234
	v_fmac_f32_e32 v93, v49, v235
	v_fmac_f32_e32 v90, v74, v236
	v_fmac_f32_e32 v91, v58, v237
	v_fmac_f32_e32 v92, v60, v238
	v_fmac_f32_e32 v93, v72, v239
	v_fmac_f32_e32 v90, v75, v240
	v_fmac_f32_e32 v91, v59, v241
	v_fmac_f32_e32 v92, v61, v242
	v_fmac_f32_e32 v93, v73, v243
	s_waitcnt lgkmcnt(0)
	v_fmac_f32_e32 v90, v70, v196
	v_fmac_f32_e32 v91, v54, v197
	v_fmac_f32_e32 v92, v56, v198
	v_fmac_f32_e32 v93, v68, v199
	v_fmac_f32_e32 v90, v71, v200
	v_fmac_f32_e32 v91, v55, v201
	v_fmac_f32_e32 v92, v57, v202
	v_fmac_f32_e32 v93, v69, v203
	v_fmac_f32_e32 v90, v66, v204
	v_fmac_f32_e32 v91, v50, v205
	v_fmac_f32_e32 v92, v52, v206
	v_fmac_f32_e32 v93, v64, v207
	v_fmac_f32_e32 v90, v67, v208
	v_fmac_f32_e32 v91, v51, v209
	v_fmac_f32_e32 v92, v53, v210
	v_fmac_f32_e32 v93, v65, v211
	v_add_f32_e32 v90, v90, v91
	v_add_f32_e32 v92, v92, v93
	s_waitcnt vmcnt(15)
	v_lshlrev_b32_e32 v91, 16, v155
	v_add_f32_e32 v90, v90, v92
	v_lshl_add_u64 v[170:171], s[34:35], 0, v[110:111]
	v_add_f32_e32 v90, v90, v91
	v_bfe_u32 v91, v90, 16, 1
	v_add3_u32 v90, v90, v91, s46
	global_store_short_d16_hi v[170:171], v90, off
	s_waitcnt vmcnt(31)
	v_lshlrev_b32_e32 v85, 16, v140
	ds_write_b32 v78, v85 offset:33280
	s_waitcnt lgkmcnt(0)
	ds_read_b128 v[196:199], v77 offset:33280
	ds_read_b128 v[200:203], v77 offset:33296
	ds_read_b128 v[204:207], v77 offset:33312
	ds_read_b128 v[208:211], v77 offset:33328
	ds_read_b128 v[212:215], v77 offset:33344
	ds_read_b128 v[216:219], v77 offset:33360
	ds_read_b128 v[220:223], v77 offset:33376
	ds_read_b128 v[224:227], v77 offset:33392
	s_waitcnt lgkmcnt(4)
	v_mul_f32_e32 v86, v2, v196
	v_mul_f32_e32 v87, v3, v197
	v_mul_f32_e32 v88, v4, v198
	v_mul_f32_e32 v89, v5, v199
	v_fmac_f32_e32 v86, v6, v200
	v_fmac_f32_e32 v87, v7, v201
	v_fmac_f32_e32 v88, v8, v202
	v_fmac_f32_e32 v89, v9, v203
	v_fmac_f32_e32 v86, v18, v204
	v_fmac_f32_e32 v87, v19, v205
	v_fmac_f32_e32 v88, v20, v206
	v_fmac_f32_e32 v89, v21, v207
	v_fmac_f32_e32 v86, v22, v208
	v_fmac_f32_e32 v87, v23, v209
	v_fmac_f32_e32 v88, v24, v210
	v_fmac_f32_e32 v89, v25, v211
	ds_read_b128 v[228:231], v77 offset:33408
	ds_read_b128 v[232:235], v77 offset:33424
	ds_read_b128 v[236:239], v77 offset:33440
	ds_read_b128 v[240:243], v77 offset:33456
	s_waitcnt lgkmcnt(4)
	v_fmac_f32_e32 v86, v26, v212
	v_fmac_f32_e32 v87, v27, v213
	v_fmac_f32_e32 v88, v28, v214
	v_fmac_f32_e32 v89, v29, v215
	v_fmac_f32_e32 v86, v30, v216
	v_fmac_f32_e32 v87, v31, v217
	v_fmac_f32_e32 v88, v32, v218
	v_fmac_f32_e32 v89, v33, v219
	v_fmac_f32_e32 v86, v34, v220
	v_fmac_f32_e32 v87, v35, v221
	v_fmac_f32_e32 v88, v36, v222
	v_fmac_f32_e32 v89, v37, v223
	v_fmac_f32_e32 v86, v38, v224
	v_fmac_f32_e32 v87, v39, v225
	v_fmac_f32_e32 v88, v40, v226
	v_fmac_f32_e32 v89, v41, v227
	ds_read_b128 v[196:199], v77 offset:33472
	ds_read_b128 v[200:203], v77 offset:33488
	ds_read_b128 v[204:207], v77 offset:33504
	ds_read_b128 v[208:211], v77 offset:33520
	s_waitcnt lgkmcnt(4)
; __device__ __forceinline__ bf16_t f2bf(float f) { unsigned u = __float_as_uint(f); u += 0x7FFFu + ((u >> 16) & 1u); return (bf16_t)(u >> 16); }
; __device__ __forceinline__ float bf2f(unsigned b) { return __uint_as_float(b << 16); }
; __device__ void phase_fixup(const float* FS, const bf16_t* Q, bf16_t* Y, float* sm) {
;     ...
;             qw[v] = bf2f(Q[o]);
;             __builtin_amdgcn_wave_barrier(); asm volatile("s_waitcnt lgkmcnt(0)" ::: "memory");
;             float acc = 0.f;
; #pragma unroll
;             for (int m4 = 0; m4 < 16; ++m4) { const f32x4 qq = *(const f32x4*)(qw + 4 * m4); acc += s0[4 * m4] * qq[0] + s0[4 * m4 + 1] * qq[1] + s0[4 * m4 + 2] * qq[2] + s0[4 * m4 + 3] * qq[3]; }
;             __builtin_amdgcn_wave_barrier();
;             Y[o] = f2bf(bf2f(Y[o]) + acc);
	v_fmac_f32_e32 v86, v42, v228
	v_fmac_f32_e32 v87, v43, v229
	v_fmac_f32_e32 v88, v44, v230
	v_fmac_f32_e32 v89, v45, v231
	v_fmac_f32_e32 v86, v46, v232
	v_fmac_f32_e32 v87, v47, v233
	v_fmac_f32_e32 v88, v48, v234
	v_fmac_f32_e32 v89, v49, v235
	v_fmac_f32_e32 v86, v74, v236
	v_fmac_f32_e32 v87, v58, v237
	v_fmac_f32_e32 v88, v60, v238
	v_fmac_f32_e32 v89, v72, v239
	v_fmac_f32_e32 v86, v75, v240
	v_fmac_f32_e32 v87, v59, v241
	v_fmac_f32_e32 v88, v61, v242
	v_fmac_f32_e32 v89, v73, v243
	s_waitcnt lgkmcnt(0)
	v_fmac_f32_e32 v86, v70, v196
	v_fmac_f32_e32 v87, v54, v197
	v_fmac_f32_e32 v88, v56, v198
	v_fmac_f32_e32 v89, v68, v199
	v_fmac_f32_e32 v86, v71, v200
	v_fmac_f32_e32 v87, v55, v201
	v_fmac_f32_e32 v88, v57, v202
	v_fmac_f32_e32 v89, v69, v203
	v_fmac_f32_e32 v86, v66, v204
	v_fmac_f32_e32 v87, v50, v205
	v_fmac_f32_e32 v88, v52, v206
	v_fmac_f32_e32 v89, v64, v207
	v_fmac_f32_e32 v86, v67, v208
	v_fmac_f32_e32 v87, v51, v209
	v_fmac_f32_e32 v88, v53, v210
	v_fmac_f32_e32 v89, v65, v211
	v_add_f32_e32 v86, v86, v87
	v_add_f32_e32 v88, v88, v89
	s_waitcnt vmcnt(15)
	v_lshlrev_b32_e32 v87, 16, v156
	v_add_f32_e32 v86, v86, v88
	v_lshl_add_u64 v[170:171], s[34:35], 0, v[112:113]
	v_add_f32_e32 v86, v86, v87
	v_bfe_u32 v87, v86, 16, 1
	v_add3_u32 v86, v86, v87, s46
	global_store_short_d16_hi v[170:171], v86, off
	s_waitcnt vmcnt(31)
	v_lshlrev_b32_e32 v85, 16, v141
	ds_write_b32 v78, v85 offset:33280
	s_waitcnt lgkmcnt(0)
	ds_read_b128 v[196:199], v77 offset:33280
	ds_read_b128 v[200:203], v77 offset:33296
	ds_read_b128 v[204:207], v77 offset:33312
	ds_read_b128 v[208:211], v77 offset:33328
	ds_read_b128 v[212:215], v77 offset:33344
	ds_read_b128 v[216:219], v77 offset:33360
	ds_read_b128 v[220:223], v77 offset:33376
	ds_read_b128 v[224:227], v77 offset:33392
	s_waitcnt lgkmcnt(4)
	v_mul_f32_e32 v90, v2, v196
	v_mul_f32_e32 v91, v3, v197
	v_mul_f32_e32 v92, v4, v198
	v_mul_f32_e32 v93, v5, v199
	v_fmac_f32_e32 v90, v6, v200
	v_fmac_f32_e32 v91, v7, v201
	v_fmac_f32_e32 v92, v8, v202
	v_fmac_f32_e32 v93, v9, v203
	v_fmac_f32_e32 v90, v18, v204
	v_fmac_f32_e32 v91, v19, v205
	v_fmac_f32_e32 v92, v20, v206
	v_fmac_f32_e32 v93, v21, v207
	v_fmac_f32_e32 v90, v22, v208
	v_fmac_f32_e32 v91, v23, v209
	v_fmac_f32_e32 v92, v24, v210
	v_fmac_f32_e32 v93, v25, v211
	ds_read_b128 v[228:231], v77 offset:33408
	ds_read_b128 v[232:235], v77 offset:33424
	ds_read_b128 v[236:239], v77 offset:33440
	ds_read_b128 v[240:243], v77 offset:33456
	s_waitcnt lgkmcnt(4)
	v_fmac_f32_e32 v90, v26, v212
	v_fmac_f32_e32 v91, v27, v213
	v_fmac_f32_e32 v92, v28, v214
	v_fmac_f32_e32 v93, v29, v215
	v_fmac_f32_e32 v90, v30, v216
	v_fmac_f32_e32 v91, v31, v217
	v_fmac_f32_e32 v92, v32, v218
	v_fmac_f32_e32 v93, v33, v219
	v_fmac_f32_e32 v90, v34, v220
	v_fmac_f32_e32 v91, v35, v221
	v_fmac_f32_e32 v92, v36, v222
	v_fmac_f32_e32 v93, v37, v223
	v_fmac_f32_e32 v90, v38, v224
	v_fmac_f32_e32 v91, v39, v225
	v_fmac_f32_e32 v92, v40, v226
	v_fmac_f32_e32 v93, v41, v227
	ds_read_b128 v[196:199], v77 offset:33472
	ds_read_b128 v[200:203], v77 offset:33488
	ds_read_b128 v[204:207], v77 offset:33504
	ds_read_b128 v[208:211], v77 offset:33520
	s_waitcnt lgkmcnt(4)
	v_fmac_f32_e32 v90, v42, v228
	v_fmac_f32_e32 v91, v43, v229
	v_fmac_f32_e32 v92, v44, v230
	v_fmac_f32_e32 v93, v45, v231
	v_fmac_f32_e32 v90, v46, v232
	v_fmac_f32_e32 v91, v47, v233
	v_fmac_f32_e32 v92, v48, v234
	v_fmac_f32_e32 v93, v49, v235
	v_fmac_f32_e32 v90, v74, v236
	v_fmac_f32_e32 v91, v58, v237
	v_fmac_f32_e32 v92, v60, v238
	v_fmac_f32_e32 v93, v72, v239
	v_fmac_f32_e32 v90, v75, v240
	v_fmac_f32_e32 v91, v59, v241
	v_fmac_f32_e32 v92, v61, v242
	v_fmac_f32_e32 v93, v73, v243
	s_waitcnt lgkmcnt(0)
	v_fmac_f32_e32 v90, v70, v196
	v_fmac_f32_e32 v91, v54, v197
	v_fmac_f32_e32 v92, v56, v198
	v_fmac_f32_e32 v93, v68, v199
	v_fmac_f32_e32 v90, v71, v200
	v_fmac_f32_e32 v91, v55, v201
	v_fmac_f32_e32 v92, v57, v202
	v_fmac_f32_e32 v93, v69, v203
	v_fmac_f32_e32 v90, v66, v204
	v_fmac_f32_e32 v91, v50, v205
	v_fmac_f32_e32 v92, v52, v206
	v_fmac_f32_e32 v93, v64, v207
	v_fmac_f32_e32 v90, v67, v208
	v_fmac_f32_e32 v91, v51, v209
	v_fmac_f32_e32 v92, v53, v210
	v_fmac_f32_e32 v93, v65, v211
	v_add_f32_e32 v90, v90, v91
	v_add_f32_e32 v92, v92, v93
	s_waitcnt vmcnt(15)
	v_lshlrev_b32_e32 v91, 16, v157
	v_add_f32_e32 v90, v90, v92
	v_lshl_add_u64 v[170:171], s[34:35], 0, v[114:115]
	v_add_f32_e32 v90, v90, v91
	v_bfe_u32 v91, v90, 16, 1
	v_add3_u32 v90, v90, v91, s46
	global_store_short_d16_hi v[170:171], v90, off
	s_waitcnt vmcnt(31)
	v_lshlrev_b32_e32 v85, 16, v142
	ds_write_b32 v78, v85 offset:33280
	s_waitcnt lgkmcnt(0)
	ds_read_b128 v[196:199], v77 offset:33280
	ds_read_b128 v[200:203], v77 offset:33296
	ds_read_b128 v[204:207], v77 offset:33312
	ds_read_b128 v[208:211], v77 offset:33328
	ds_read_b128 v[212:215], v77 offset:33344
	ds_read_b128 v[216:219], v77 offset:33360
	ds_read_b128 v[220:223], v77 offset:33376
	ds_read_b128 v[224:227], v77 offset:33392
	s_waitcnt lgkmcnt(4)
	v_mul_f32_e32 v86, v2, v196
	v_mul_f32_e32 v87, v3, v197
	v_mul_f32_e32 v88, v4, v198
	v_mul_f32_e32 v89, v5, v199
	v_fmac_f32_e32 v86, v6, v200
	v_fmac_f32_e32 v87, v7, v201
	v_fmac_f32_e32 v88, v8, v202
	v_fmac_f32_e32 v89, v9, v203
	v_fmac_f32_e32 v86, v18, v204
	v_fmac_f32_e32 v87, v19, v205
	v_fmac_f32_e32 v88, v20, v206
	v_fmac_f32_e32 v89, v21, v207
	v_fmac_f32_e32 v86, v22, v208
	v_fmac_f32_e32 v87, v23, v209
	v_fmac_f32_e32 v88, v24, v210
	v_fmac_f32_e32 v89, v25, v211
	ds_read_b128 v[228:231], v77 offset:33408
	ds_read_b128 v[232:235], v77 offset:33424
	ds_read_b128 v[236:239], v77 offset:33440
	ds_read_b128 v[240:243], v77 offset:33456
	s_waitcnt lgkmcnt(4)
; __device__ __forceinline__ bf16_t f2bf(float f) { unsigned u = __float_as_uint(f); u += 0x7FFFu + ((u >> 16) & 1u); return (bf16_t)(u >> 16); }
; __device__ __forceinline__ float bf2f(unsigned b) { return __uint_as_float(b << 16); }
; __device__ void phase_fixup(const float* FS, const bf16_t* Q, bf16_t* Y, float* sm) {
;     ...
;             qw[v] = bf2f(Q[o]);
;             __builtin_amdgcn_wave_barrier(); asm volatile("s_waitcnt lgkmcnt(0)" ::: "memory");
;             float acc = 0.f;
; #pragma unroll
;             for (int m4 = 0; m4 < 16; ++m4) { const f32x4 qq = *(const f32x4*)(qw + 4 * m4); acc += s0[4 * m4] * qq[0] + s0[4 * m4 + 1] * qq[1] + s0[4 * m4 + 2] * qq[2] + s0[4 * m4 + 3] * qq[3]; }
;             __builtin_amdgcn_wave_barrier();
;             Y[o] = f2bf(bf2f(Y[o]) + acc);
	v_fmac_f32_e32 v86, v26, v212
	v_fmac_f32_e32 v87, v27, v213
	v_fmac_f32_e32 v88, v28, v214
	v_fmac_f32_e32 v89, v29, v215
	v_fmac_f32_e32 v86, v30, v216
	v_fmac_f32_e32 v87, v31, v217
	v_fmac_f32_e32 v88, v32, v218
	v_fmac_f32_e32 v89, v33, v219
	v_fmac_f32_e32 v86, v34, v220
	v_fmac_f32_e32 v87, v35, v221
	v_fmac_f32_e32 v88, v36, v222
	v_fmac_f32_e32 v89, v37, v223
	v_fmac_f32_e32 v86, v38, v224
	v_fmac_f32_e32 v87, v39, v225
	v_fmac_f32_e32 v88, v40, v226
	v_fmac_f32_e32 v89, v41, v227
	ds_read_b128 v[196:199], v77 offset:33472
	ds_read_b128 v[200:203], v77 offset:33488
	ds_read_b128 v[204:207], v77 offset:33504
	ds_read_b128 v[208:211], v77 offset:33520
	s_waitcnt lgkmcnt(4)
	v_fmac_f32_e32 v86, v42, v228
	v_fmac_f32_e32 v87, v43, v229
	v_fmac_f32_e32 v88, v44, v230
	v_fmac_f32_e32 v89, v45, v231
	v_fmac_f32_e32 v86, v46, v232
	v_fmac_f32_e32 v87, v47, v233
	v_fmac_f32_e32 v88, v48, v234
	v_fmac_f32_e32 v89, v49, v235
	v_fmac_f32_e32 v86, v74, v236
	v_fmac_f32_e32 v87, v58, v237
	v_fmac_f32_e32 v88, v60, v238
	v_fmac_f32_e32 v89, v72, v239
	v_fmac_f32_e32 v86, v75, v240
	v_fmac_f32_e32 v87, v59, v241
	v_fmac_f32_e32 v88, v61, v242
	v_fmac_f32_e32 v89, v73, v243
	s_waitcnt lgkmcnt(0)
	v_fmac_f32_e32 v86, v70, v196
	v_fmac_f32_e32 v87, v54, v197
	v_fmac_f32_e32 v88, v56, v198
	v_fmac_f32_e32 v89, v68, v199
	v_fmac_f32_e32 v86, v71, v200
	v_fmac_f32_e32 v87, v55, v201
	v_fmac_f32_e32 v88, v57, v202
	v_fmac_f32_e32 v89, v69, v203
	v_fmac_f32_e32 v86, v66, v204
	v_fmac_f32_e32 v87, v50, v205
	v_fmac_f32_e32 v88, v52, v206
	v_fmac_f32_e32 v89, v64, v207
	v_fmac_f32_e32 v86, v67, v208
	v_fmac_f32_e32 v87, v51, v209
	v_fmac_f32_e32 v88, v53, v210
	v_fmac_f32_e32 v89, v65, v211
	v_add_f32_e32 v86, v86, v87
	v_add_f32_e32 v88, v88, v89
	s_waitcnt vmcnt(15)
	v_lshlrev_b32_e32 v87, 16, v158
	v_add_f32_e32 v86, v86, v88
	v_lshl_add_u64 v[170:171], s[34:35], 0, v[116:117]
	v_add_f32_e32 v86, v86, v87
	v_bfe_u32 v87, v86, 16, 1
	v_add3_u32 v86, v86, v87, s46
	global_store_short_d16_hi v[170:171], v86, off
	s_waitcnt vmcnt(31)
	v_lshlrev_b32_e32 v85, 16, v143
	ds_write_b32 v78, v85 offset:33280
	s_waitcnt lgkmcnt(0)
	ds_read_b128 v[196:199], v77 offset:33280
	ds_read_b128 v[200:203], v77 offset:33296
	ds_read_b128 v[204:207], v77 offset:33312
	ds_read_b128 v[208:211], v77 offset:33328
	ds_read_b128 v[212:215], v77 offset:33344
	ds_read_b128 v[216:219], v77 offset:33360
	ds_read_b128 v[220:223], v77 offset:33376
	ds_read_b128 v[224:227], v77 offset:33392
	s_waitcnt lgkmcnt(4)
	v_mul_f32_e32 v90, v2, v196
	v_mul_f32_e32 v91, v3, v197
	v_mul_f32_e32 v92, v4, v198
	v_mul_f32_e32 v93, v5, v199
	v_fmac_f32_e32 v90, v6, v200
	v_fmac_f32_e32 v91, v7, v201
	v_fmac_f32_e32 v92, v8, v202
	v_fmac_f32_e32 v93, v9, v203
	v_fmac_f32_e32 v90, v18, v204
	v_fmac_f32_e32 v91, v19, v205
	v_fmac_f32_e32 v92, v20, v206
	v_fmac_f32_e32 v93, v21, v207
	v_fmac_f32_e32 v90, v22, v208
	v_fmac_f32_e32 v91, v23, v209
	v_fmac_f32_e32 v92, v24, v210
	v_fmac_f32_e32 v93, v25, v211
	ds_read_b128 v[228:231], v77 offset:33408
	ds_read_b128 v[232:235], v77 offset:33424
	ds_read_b128 v[236:239], v77 offset:33440
	ds_read_b128 v[240:243], v77 offset:33456
	s_waitcnt lgkmcnt(4)
	v_fmac_f32_e32 v90, v26, v212
	v_fmac_f32_e32 v91, v27, v213
	v_fmac_f32_e32 v92, v28, v214
	v_fmac_f32_e32 v93, v29, v215
	v_fmac_f32_e32 v90, v30, v216
	v_fmac_f32_e32 v91, v31, v217
	v_fmac_f32_e32 v92, v32, v218
	v_fmac_f32_e32 v93, v33, v219
	v_fmac_f32_e32 v90, v34, v220
	v_fmac_f32_e32 v91, v35, v221
	v_fmac_f32_e32 v92, v36, v222
	v_fmac_f32_e32 v93, v37, v223
	v_fmac_f32_e32 v90, v38, v224
	v_fmac_f32_e32 v91, v39, v225
	v_fmac_f32_e32 v92, v40, v226
	v_fmac_f32_e32 v93, v41, v227
	ds_read_b128 v[196:199], v77 offset:33472
	ds_read_b128 v[200:203], v77 offset:33488
	ds_read_b128 v[204:207], v77 offset:33504
	ds_read_b128 v[208:211], v77 offset:33520
	s_waitcnt lgkmcnt(4)
	v_fmac_f32_e32 v90, v42, v228
	v_fmac_f32_e32 v91, v43, v229
	v_fmac_f32_e32 v92, v44, v230
	v_fmac_f32_e32 v93, v45, v231
	v_fmac_f32_e32 v90, v46, v232
	v_fmac_f32_e32 v91, v47, v233
	v_fmac_f32_e32 v92, v48, v234
	v_fmac_f32_e32 v93, v49, v235
	v_fmac_f32_e32 v90, v74, v236
	v_fmac_f32_e32 v91, v58, v237
	v_fmac_f32_e32 v92, v60, v238
	v_fmac_f32_e32 v93, v72, v239
	v_fmac_f32_e32 v90, v75, v240
	v_fmac_f32_e32 v91, v59, v241
	v_fmac_f32_e32 v92, v61, v242
	v_fmac_f32_e32 v93, v73, v243
	s_waitcnt lgkmcnt(0)
	v_fmac_f32_e32 v90, v70, v196
	v_fmac_f32_e32 v91, v54, v197
	v_fmac_f32_e32 v92, v56, v198
	v_fmac_f32_e32 v93, v68, v199
	v_fmac_f32_e32 v90, v71, v200
	v_fmac_f32_e32 v91, v55, v201
	v_fmac_f32_e32 v92, v57, v202
	v_fmac_f32_e32 v93, v69, v203
	v_fmac_f32_e32 v90, v66, v204
	v_fmac_f32_e32 v91, v50, v205
	v_fmac_f32_e32 v92, v52, v206
	v_fmac_f32_e32 v93, v64, v207
	v_fmac_f32_e32 v90, v67, v208
	v_fmac_f32_e32 v91, v51, v209
	v_fmac_f32_e32 v92, v53, v210
	v_fmac_f32_e32 v93, v65, v211
	v_add_f32_e32 v90, v90, v91
	v_add_f32_e32 v92, v92, v93
	s_waitcnt vmcnt(15)
	v_lshlrev_b32_e32 v91, 16, v159
	v_add_f32_e32 v90, v90, v92
	v_lshl_add_u64 v[170:171], s[34:35], 0, v[118:119]
	v_add_f32_e32 v90, v90, v91
	v_bfe_u32 v91, v90, 16, 1
	v_add3_u32 v90, v90, v91, s46
	global_store_short_d16_hi v[170:171], v90, off
	s_waitcnt vmcnt(31)
	v_lshlrev_b32_e32 v85, 16, v144
	ds_write_b32 v78, v85 offset:33280
	s_waitcnt lgkmcnt(0)
	ds_read_b128 v[196:199], v77 offset:33280
	ds_read_b128 v[200:203], v77 offset:33296
	ds_read_b128 v[204:207], v77 offset:33312
	ds_read_b128 v[208:211], v77 offset:33328
	ds_read_b128 v[212:215], v77 offset:33344
	ds_read_b128 v[216:219], v77 offset:33360
	ds_read_b128 v[220:223], v77 offset:33376
	ds_read_b128 v[224:227], v77 offset:33392
	s_waitcnt lgkmcnt(4)
; __device__ __forceinline__ bf16_t f2bf(float f) { unsigned u = __float_as_uint(f); u += 0x7FFFu + ((u >> 16) & 1u); return (bf16_t)(u >> 16); }
; __device__ __forceinline__ float bf2f(unsigned b) { return __uint_as_float(b << 16); }
; __device__ void phase_fixup(const float* FS, const bf16_t* Q, bf16_t* Y, float* sm) {
;     ...
;             qw[v] = bf2f(Q[o]);
;             __builtin_amdgcn_wave_barrier(); asm volatile("s_waitcnt lgkmcnt(0)" ::: "memory");
;             float acc = 0.f;
; #pragma unroll
;             for (int m4 = 0; m4 < 16; ++m4) { const f32x4 qq = *(const f32x4*)(qw + 4 * m4); acc += s0[4 * m4] * qq[0] + s0[4 * m4 + 1] * qq[1] + s0[4 * m4 + 2] * qq[2] + s0[4 * m4 + 3] * qq[3]; }
;             __builtin_amdgcn_wave_barrier();
;             Y[o] = f2bf(bf2f(Y[o]) + acc);
	v_mul_f32_e32 v86, v2, v196
	v_mul_f32_e32 v87, v3, v197
	v_mul_f32_e32 v88, v4, v198
	v_mul_f32_e32 v89, v5, v199
	v_fmac_f32_e32 v86, v6, v200
	v_fmac_f32_e32 v87, v7, v201
	v_fmac_f32_e32 v88, v8, v202
	v_fmac_f32_e32 v89, v9, v203
	v_fmac_f32_e32 v86, v18, v204
	v_fmac_f32_e32 v87, v19, v205
	v_fmac_f32_e32 v88, v20, v206
	v_fmac_f32_e32 v89, v21, v207
	v_fmac_f32_e32 v86, v22, v208
	v_fmac_f32_e32 v87, v23, v209
	v_fmac_f32_e32 v88, v24, v210
	v_fmac_f32_e32 v89, v25, v211
	ds_read_b128 v[228:231], v77 offset:33408
	ds_read_b128 v[232:235], v77 offset:33424
	ds_read_b128 v[236:239], v77 offset:33440
	ds_read_b128 v[240:243], v77 offset:33456
	s_waitcnt lgkmcnt(4)
	v_fmac_f32_e32 v86, v26, v212
	v_fmac_f32_e32 v87, v27, v213
	v_fmac_f32_e32 v88, v28, v214
	v_fmac_f32_e32 v89, v29, v215
	v_fmac_f32_e32 v86, v30, v216
	v_fmac_f32_e32 v87, v31, v217
	v_fmac_f32_e32 v88, v32, v218
	v_fmac_f32_e32 v89, v33, v219
	v_fmac_f32_e32 v86, v34, v220
	v_fmac_f32_e32 v87, v35, v221
	v_fmac_f32_e32 v88, v36, v222
	v_fmac_f32_e32 v89, v37, v223
	v_fmac_f32_e32 v86, v38, v224
	v_fmac_f32_e32 v87, v39, v225
	v_fmac_f32_e32 v88, v40, v226
	v_fmac_f32_e32 v89, v41, v227
	ds_read_b128 v[196:199], v77 offset:33472
	ds_read_b128 v[200:203], v77 offset:33488
	ds_read_b128 v[204:207], v77 offset:33504
	ds_read_b128 v[208:211], v77 offset:33520
	s_waitcnt lgkmcnt(4)
	v_fmac_f32_e32 v86, v42, v228
	v_fmac_f32_e32 v87, v43, v229
	v_fmac_f32_e32 v88, v44, v230
	v_fmac_f32_e32 v89, v45, v231
	v_fmac_f32_e32 v86, v46, v232
	v_fmac_f32_e32 v87, v47, v233
	v_fmac_f32_e32 v88, v48, v234
	v_fmac_f32_e32 v89, v49, v235
	v_fmac_f32_e32 v86, v74, v236
	v_fmac_f32_e32 v87, v58, v237
	v_fmac_f32_e32 v88, v60, v238
	v_fmac_f32_e32 v89, v72, v239
	v_fmac_f32_e32 v86, v75, v240
	v_fmac_f32_e32 v87, v59, v241
	v_fmac_f32_e32 v88, v61, v242
	v_fmac_f32_e32 v89, v73, v243
	s_waitcnt lgkmcnt(0)
	v_fmac_f32_e32 v86, v70, v196
	v_fmac_f32_e32 v87, v54, v197
	v_fmac_f32_e32 v88, v56, v198
	v_fmac_f32_e32 v89, v68, v199
	v_fmac_f32_e32 v86, v71, v200
	v_fmac_f32_e32 v87, v55, v201
	v_fmac_f32_e32 v88, v57, v202
	v_fmac_f32_e32 v89, v69, v203
	v_fmac_f32_e32 v86, v66, v204
	v_fmac_f32_e32 v87, v50, v205
	v_fmac_f32_e32 v88, v52, v206
	v_fmac_f32_e32 v89, v64, v207
	v_fmac_f32_e32 v86, v67, v208
	v_fmac_f32_e32 v87, v51, v209
	v_fmac_f32_e32 v88, v53, v210
	v_fmac_f32_e32 v89, v65, v211
	v_add_f32_e32 v86, v86, v87
	v_add_f32_e32 v88, v88, v89
	s_waitcnt vmcnt(15)
	v_lshlrev_b32_e32 v87, 16, v160
	v_add_f32_e32 v86, v86, v88
	v_lshl_add_u64 v[170:171], s[34:35], 0, v[120:121]
	v_add_f32_e32 v86, v86, v87
	v_bfe_u32 v87, v86, 16, 1
	v_add3_u32 v86, v86, v87, s46
	global_store_short_d16_hi v[170:171], v86, off
	s_waitcnt vmcnt(31)
	v_lshlrev_b32_e32 v85, 16, v145
	ds_write_b32 v78, v85 offset:33280
	s_waitcnt lgkmcnt(0)
	ds_read_b128 v[196:199], v77 offset:33280
	ds_read_b128 v[200:203], v77 offset:33296
	ds_read_b128 v[204:207], v77 offset:33312
	ds_read_b128 v[208:211], v77 offset:33328
	ds_read_b128 v[212:215], v77 offset:33344
	ds_read_b128 v[216:219], v77 offset:33360
	ds_read_b128 v[220:223], v77 offset:33376
	ds_read_b128 v[224:227], v77 offset:33392
	s_waitcnt lgkmcnt(4)
	v_mul_f32_e32 v90, v2, v196
	v_mul_f32_e32 v91, v3, v197
	v_mul_f32_e32 v92, v4, v198
	v_mul_f32_e32 v93, v5, v199
	v_fmac_f32_e32 v90, v6, v200
	v_fmac_f32_e32 v91, v7, v201
	v_fmac_f32_e32 v92, v8, v202
	v_fmac_f32_e32 v93, v9, v203
	v_fmac_f32_e32 v90, v18, v204
	v_fmac_f32_e32 v91, v19, v205
	v_fmac_f32_e32 v92, v20, v206
	v_fmac_f32_e32 v93, v21, v207
	v_fmac_f32_e32 v90, v22, v208
	v_fmac_f32_e32 v91, v23, v209
	v_fmac_f32_e32 v92, v24, v210
	v_fmac_f32_e32 v93, v25, v211
	ds_read_b128 v[228:231], v77 offset:33408
	ds_read_b128 v[232:235], v77 offset:33424
	ds_read_b128 v[236:239], v77 offset:33440
	ds_read_b128 v[240:243], v77 offset:33456
	s_waitcnt lgkmcnt(4)
	v_fmac_f32_e32 v90, v26, v212
	v_fmac_f32_e32 v91, v27, v213
	v_fmac_f32_e32 v92, v28, v214
	v_fmac_f32_e32 v93, v29, v215
	v_fmac_f32_e32 v90, v30, v216
	v_fmac_f32_e32 v91, v31, v217
	v_fmac_f32_e32 v92, v32, v218
	v_fmac_f32_e32 v93, v33, v219
	v_fmac_f32_e32 v90, v34, v220
	v_fmac_f32_e32 v91, v35, v221
	v_fmac_f32_e32 v92, v36, v222
	v_fmac_f32_e32 v93, v37, v223
	v_fmac_f32_e32 v90, v38, v224
	v_fmac_f32_e32 v91, v39, v225
	v_fmac_f32_e32 v92, v40, v226
	v_fmac_f32_e32 v93, v41, v227
	ds_read_b128 v[196:199], v77 offset:33472
	ds_read_b128 v[200:203], v77 offset:33488
	ds_read_b128 v[204:207], v77 offset:33504
	ds_read_b128 v[208:211], v77 offset:33520
	s_waitcnt lgkmcnt(4)
	v_fmac_f32_e32 v90, v42, v228
	v_fmac_f32_e32 v91, v43, v229
	v_fmac_f32_e32 v92, v44, v230
	v_fmac_f32_e32 v93, v45, v231
	v_fmac_f32_e32 v90, v46, v232
	v_fmac_f32_e32 v91, v47, v233
	v_fmac_f32_e32 v92, v48, v234
	v_fmac_f32_e32 v93, v49, v235
	v_fmac_f32_e32 v90, v74, v236
	v_fmac_f32_e32 v91, v58, v237
	v_fmac_f32_e32 v92, v60, v238
	v_fmac_f32_e32 v93, v72, v239
	v_fmac_f32_e32 v90, v75, v240
	v_fmac_f32_e32 v91, v59, v241
	v_fmac_f32_e32 v92, v61, v242
	v_fmac_f32_e32 v93, v73, v243
	s_waitcnt lgkmcnt(0)
	v_fmac_f32_e32 v90, v70, v196
	v_fmac_f32_e32 v91, v54, v197
	v_fmac_f32_e32 v92, v56, v198
	v_fmac_f32_e32 v93, v68, v199
	v_fmac_f32_e32 v90, v71, v200
	v_fmac_f32_e32 v91, v55, v201
	v_fmac_f32_e32 v92, v57, v202
	v_fmac_f32_e32 v93, v69, v203
	v_fmac_f32_e32 v90, v66, v204
	v_fmac_f32_e32 v91, v50, v205
	v_fmac_f32_e32 v92, v52, v206
	v_fmac_f32_e32 v93, v64, v207
	v_fmac_f32_e32 v90, v67, v208
	v_fmac_f32_e32 v91, v51, v209
	v_fmac_f32_e32 v92, v53, v210
	v_fmac_f32_e32 v93, v65, v211
	v_add_f32_e32 v90, v90, v91
	v_add_f32_e32 v92, v92, v93
	s_waitcnt vmcnt(15)
; __device__ __forceinline__ bf16_t f2bf(float f) { unsigned u = __float_as_uint(f); u += 0x7FFFu + ((u >> 16) & 1u); return (bf16_t)(u >> 16); }
; __device__ __forceinline__ float bf2f(unsigned b) { return __uint_as_float(b << 16); }
; __device__ void phase_fixup(const float* FS, const bf16_t* Q, bf16_t* Y, float* sm) {
;     ...
;             qw[v] = bf2f(Q[o]);
;             __builtin_amdgcn_wave_barrier(); asm volatile("s_waitcnt lgkmcnt(0)" ::: "memory");
;             float acc = 0.f;
; #pragma unroll
;             for (int m4 = 0; m4 < 16; ++m4) { const f32x4 qq = *(const f32x4*)(qw + 4 * m4); acc += s0[4 * m4] * qq[0] + s0[4 * m4 + 1] * qq[1] + s0[4 * m4 + 2] * qq[2] + s0[4 * m4 + 3] * qq[3]; }
;             __builtin_amdgcn_wave_barrier();
;             Y[o] = f2bf(bf2f(Y[o]) + acc);
	v_lshlrev_b32_e32 v91, 16, v161
	v_add_f32_e32 v90, v90, v92
	v_lshl_add_u64 v[170:171], s[34:35], 0, v[122:123]
	v_add_f32_e32 v90, v90, v91
	v_bfe_u32 v91, v90, 16, 1
	v_add3_u32 v90, v90, v91, s46
	global_store_short_d16_hi v[170:171], v90, off
	s_waitcnt vmcnt(31)
	v_lshlrev_b32_e32 v85, 16, v146
	ds_write_b32 v78, v85 offset:33280
	s_waitcnt lgkmcnt(0)
	ds_read_b128 v[196:199], v77 offset:33280
	ds_read_b128 v[200:203], v77 offset:33296
	ds_read_b128 v[204:207], v77 offset:33312
	ds_read_b128 v[208:211], v77 offset:33328
	ds_read_b128 v[212:215], v77 offset:33344
	ds_read_b128 v[216:219], v77 offset:33360
	ds_read_b128 v[220:223], v77 offset:33376
	ds_read_b128 v[224:227], v77 offset:33392
	s_waitcnt lgkmcnt(4)
	v_mul_f32_e32 v86, v2, v196
	v_mul_f32_e32 v87, v3, v197
	v_mul_f32_e32 v88, v4, v198
	v_mul_f32_e32 v89, v5, v199
	v_fmac_f32_e32 v86, v6, v200
	v_fmac_f32_e32 v87, v7, v201
	v_fmac_f32_e32 v88, v8, v202
	v_fmac_f32_e32 v89, v9, v203
	v_fmac_f32_e32 v86, v18, v204
	v_fmac_f32_e32 v87, v19, v205
	v_fmac_f32_e32 v88, v20, v206
	v_fmac_f32_e32 v89, v21, v207
	v_fmac_f32_e32 v86, v22, v208
	v_fmac_f32_e32 v87, v23, v209
	v_fmac_f32_e32 v88, v24, v210
	v_fmac_f32_e32 v89, v25, v211
	ds_read_b128 v[228:231], v77 offset:33408
	ds_read_b128 v[232:235], v77 offset:33424
	ds_read_b128 v[236:239], v77 offset:33440
	ds_read_b128 v[240:243], v77 offset:33456
	s_waitcnt lgkmcnt(4)
	v_fmac_f32_e32 v86, v26, v212
	v_fmac_f32_e32 v87, v27, v213
	v_fmac_f32_e32 v88, v28, v214
	v_fmac_f32_e32 v89, v29, v215
	v_fmac_f32_e32 v86, v30, v216
	v_fmac_f32_e32 v87, v31, v217
	v_fmac_f32_e32 v88, v32, v218
	v_fmac_f32_e32 v89, v33, v219
	v_fmac_f32_e32 v86, v34, v220
	v_fmac_f32_e32 v87, v35, v221
	v_fmac_f32_e32 v88, v36, v222
	v_fmac_f32_e32 v89, v37, v223
	v_fmac_f32_e32 v86, v38, v224
	v_fmac_f32_e32 v87, v39, v225
	v_fmac_f32_e32 v88, v40, v226
	v_fmac_f32_e32 v89, v41, v227
	ds_read_b128 v[196:199], v77 offset:33472
	ds_read_b128 v[200:203], v77 offset:33488
	ds_read_b128 v[204:207], v77 offset:33504
	ds_read_b128 v[208:211], v77 offset:33520
	s_waitcnt lgkmcnt(4)
	v_fmac_f32_e32 v86, v42, v228
	v_fmac_f32_e32 v87, v43, v229
	v_fmac_f32_e32 v88, v44, v230
	v_fmac_f32_e32 v89, v45, v231
	v_fmac_f32_e32 v86, v46, v232
	v_fmac_f32_e32 v87, v47, v233
	v_fmac_f32_e32 v88, v48, v234
	v_fmac_f32_e32 v89, v49, v235
	v_fmac_f32_e32 v86, v74, v236
	v_fmac_f32_e32 v87, v58, v237
	v_fmac_f32_e32 v88, v60, v238
	v_fmac_f32_e32 v89, v72, v239
	v_fmac_f32_e32 v86, v75, v240
	v_fmac_f32_e32 v87, v59, v241
	v_fmac_f32_e32 v88, v61, v242
	v_fmac_f32_e32 v89, v73, v243
	s_waitcnt lgkmcnt(0)
	v_fmac_f32_e32 v86, v70, v196
	v_fmac_f32_e32 v87, v54, v197
	v_fmac_f32_e32 v88, v56, v198
	v_fmac_f32_e32 v89, v68, v199
	v_fmac_f32_e32 v86, v71, v200
	v_fmac_f32_e32 v87, v55, v201
	v_fmac_f32_e32 v88, v57, v202
	v_fmac_f32_e32 v89, v69, v203
	v_fmac_f32_e32 v86, v66, v204
	v_fmac_f32_e32 v87, v50, v205
	v_fmac_f32_e32 v88, v52, v206
	v_fmac_f32_e32 v89, v64, v207
	v_fmac_f32_e32 v86, v67, v208
	v_fmac_f32_e32 v87, v51, v209
	v_fmac_f32_e32 v88, v53, v210
	v_fmac_f32_e32 v89, v65, v211
	v_add_f32_e32 v86, v86, v87
	v_add_f32_e32 v88, v88, v89
	s_waitcnt vmcnt(15)
	v_lshlrev_b32_e32 v87, 16, v162
	v_add_f32_e32 v86, v86, v88
	v_lshl_add_u64 v[170:171], s[34:35], 0, v[124:125]
	v_add_f32_e32 v86, v86, v87
	v_bfe_u32 v87, v86, 16, 1
	v_add3_u32 v86, v86, v87, s46
	global_store_short_d16_hi v[170:171], v86, off
	s_waitcnt vmcnt(31)
	v_lshlrev_b32_e32 v85, 16, v147
	ds_write_b32 v78, v85 offset:33280
	s_waitcnt lgkmcnt(0)
	ds_read_b128 v[196:199], v77 offset:33280
	ds_read_b128 v[200:203], v77 offset:33296
	ds_read_b128 v[204:207], v77 offset:33312
	ds_read_b128 v[208:211], v77 offset:33328
	ds_read_b128 v[212:215], v77 offset:33344
	ds_read_b128 v[216:219], v77 offset:33360
	ds_read_b128 v[220:223], v77 offset:33376
	ds_read_b128 v[224:227], v77 offset:33392
	s_waitcnt lgkmcnt(4)
	v_mul_f32_e32 v90, v2, v196
	v_mul_f32_e32 v91, v3, v197
	v_mul_f32_e32 v92, v4, v198
	v_mul_f32_e32 v93, v5, v199
	v_fmac_f32_e32 v90, v6, v200
	v_fmac_f32_e32 v91, v7, v201
	v_fmac_f32_e32 v92, v8, v202
	v_fmac_f32_e32 v93, v9, v203
	v_fmac_f32_e32 v90, v18, v204
	v_fmac_f32_e32 v91, v19, v205
	v_fmac_f32_e32 v92, v20, v206
	v_fmac_f32_e32 v93, v21, v207
	v_fmac_f32_e32 v90, v22, v208
	v_fmac_f32_e32 v91, v23, v209
	v_fmac_f32_e32 v92, v24, v210
	v_fmac_f32_e32 v93, v25, v211
	ds_read_b128 v[228:231], v77 offset:33408
	ds_read_b128 v[232:235], v77 offset:33424
	ds_read_b128 v[236:239], v77 offset:33440
	ds_read_b128 v[240:243], v77 offset:33456
	s_waitcnt lgkmcnt(4)
	v_fmac_f32_e32 v90, v26, v212
	v_fmac_f32_e32 v91, v27, v213
	v_fmac_f32_e32 v92, v28, v214
	v_fmac_f32_e32 v93, v29, v215
	v_fmac_f32_e32 v90, v30, v216
	v_fmac_f32_e32 v91, v31, v217
	v_fmac_f32_e32 v92, v32, v218
	v_fmac_f32_e32 v93, v33, v219
	v_fmac_f32_e32 v90, v34, v220
	v_fmac_f32_e32 v91, v35, v221
	v_fmac_f32_e32 v92, v36, v222
	v_fmac_f32_e32 v93, v37, v223
	v_fmac_f32_e32 v90, v38, v224
	v_fmac_f32_e32 v91, v39, v225
	v_fmac_f32_e32 v92, v40, v226
	v_fmac_f32_e32 v93, v41, v227
	ds_read_b128 v[196:199], v77 offset:33472
	ds_read_b128 v[200:203], v77 offset:33488
	ds_read_b128 v[204:207], v77 offset:33504
	ds_read_b128 v[208:211], v77 offset:33520
	s_waitcnt lgkmcnt(4)
	v_fmac_f32_e32 v90, v42, v228
	v_fmac_f32_e32 v91, v43, v229
	v_fmac_f32_e32 v92, v44, v230
	v_fmac_f32_e32 v93, v45, v231
	v_fmac_f32_e32 v90, v46, v232
	v_fmac_f32_e32 v91, v47, v233
	v_fmac_f32_e32 v92, v48, v234
	v_fmac_f32_e32 v93, v49, v235
	v_fmac_f32_e32 v90, v74, v236
	v_fmac_f32_e32 v91, v58, v237
	v_fmac_f32_e32 v92, v60, v238
	v_fmac_f32_e32 v93, v72, v239
	v_fmac_f32_e32 v90, v75, v240
	v_fmac_f32_e32 v91, v59, v241
	v_fmac_f32_e32 v92, v61, v242
	v_fmac_f32_e32 v93, v73, v243
	s_waitcnt lgkmcnt(0)
; __device__ __forceinline__ bf16_t f2bf(float f) { unsigned u = __float_as_uint(f); u += 0x7FFFu + ((u >> 16) & 1u); return (bf16_t)(u >> 16); }
; __device__ __forceinline__ float bf2f(unsigned b) { return __uint_as_float(b << 16); }
; __device__ void phase_fixup(const float* FS, const bf16_t* Q, bf16_t* Y, float* sm) {
;     ...
;             qw[v] = bf2f(Q[o]);
;             __builtin_amdgcn_wave_barrier(); asm volatile("s_waitcnt lgkmcnt(0)" ::: "memory");
;             float acc = 0.f;
; #pragma unroll
;             for (int m4 = 0; m4 < 16; ++m4) { const f32x4 qq = *(const f32x4*)(qw + 4 * m4); acc += s0[4 * m4] * qq[0] + s0[4 * m4 + 1] * qq[1] + s0[4 * m4 + 2] * qq[2] + s0[4 * m4 + 3] * qq[3]; }
;             __builtin_amdgcn_wave_barrier();
;             Y[o] = f2bf(bf2f(Y[o]) + acc);
	v_fmac_f32_e32 v90, v70, v196
	v_fmac_f32_e32 v91, v54, v197
	v_fmac_f32_e32 v92, v56, v198
	v_fmac_f32_e32 v93, v68, v199
	v_fmac_f32_e32 v90, v71, v200
	v_fmac_f32_e32 v91, v55, v201
	v_fmac_f32_e32 v92, v57, v202
	v_fmac_f32_e32 v93, v69, v203
	v_fmac_f32_e32 v90, v66, v204
	v_fmac_f32_e32 v91, v50, v205
	v_fmac_f32_e32 v92, v52, v206
	v_fmac_f32_e32 v93, v64, v207
	v_fmac_f32_e32 v90, v67, v208
	v_fmac_f32_e32 v91, v51, v209
	v_fmac_f32_e32 v92, v53, v210
	v_fmac_f32_e32 v93, v65, v211
	v_add_f32_e32 v90, v90, v91
	v_add_f32_e32 v92, v92, v93
	s_waitcnt vmcnt(15)
	v_lshlrev_b32_e32 v91, 16, v163
	v_add_f32_e32 v90, v90, v92
	v_lshl_add_u64 v[170:171], s[34:35], 0, v[126:127]
	v_add_f32_e32 v90, v90, v91
	v_bfe_u32 v91, v90, 16, 1
	v_add3_u32 v90, v90, v91, s46
	global_store_short_d16_hi v[170:171], v90, off
	s_waitcnt vmcnt(31)
	v_lshlrev_b32_e32 v85, 16, v148
	ds_write_b32 v78, v85 offset:33280
	s_waitcnt lgkmcnt(0)
	ds_read_b128 v[196:199], v77 offset:33280
	ds_read_b128 v[200:203], v77 offset:33296
	ds_read_b128 v[204:207], v77 offset:33312
	ds_read_b128 v[208:211], v77 offset:33328
	ds_read_b128 v[212:215], v77 offset:33344
	ds_read_b128 v[216:219], v77 offset:33360
	ds_read_b128 v[220:223], v77 offset:33376
	ds_read_b128 v[224:227], v77 offset:33392
	s_waitcnt lgkmcnt(4)
	v_mul_f32_e32 v86, v2, v196
	v_mul_f32_e32 v87, v3, v197
	v_mul_f32_e32 v88, v4, v198
	v_mul_f32_e32 v89, v5, v199
	v_fmac_f32_e32 v86, v6, v200
	v_fmac_f32_e32 v87, v7, v201
	v_fmac_f32_e32 v88, v8, v202
	v_fmac_f32_e32 v89, v9, v203
	v_fmac_f32_e32 v86, v18, v204
	v_fmac_f32_e32 v87, v19, v205
	v_fmac_f32_e32 v88, v20, v206
	v_fmac_f32_e32 v89, v21, v207
	v_fmac_f32_e32 v86, v22, v208
	v_fmac_f32_e32 v87, v23, v209
	v_fmac_f32_e32 v88, v24, v210
	v_fmac_f32_e32 v89, v25, v211
	ds_read_b128 v[228:231], v77 offset:33408
	ds_read_b128 v[232:235], v77 offset:33424
	ds_read_b128 v[236:239], v77 offset:33440
	ds_read_b128 v[240:243], v77 offset:33456
	s_waitcnt lgkmcnt(4)
	v_fmac_f32_e32 v86, v26, v212
	v_fmac_f32_e32 v87, v27, v213
	v_fmac_f32_e32 v88, v28, v214
	v_fmac_f32_e32 v89, v29, v215
	v_fmac_f32_e32 v86, v30, v216
	v_fmac_f32_e32 v87, v31, v217
	v_fmac_f32_e32 v88, v32, v218
	v_fmac_f32_e32 v89, v33, v219
	v_fmac_f32_e32 v86, v34, v220
	v_fmac_f32_e32 v87, v35, v221
	v_fmac_f32_e32 v88, v36, v222
	v_fmac_f32_e32 v89, v37, v223
	v_fmac_f32_e32 v86, v38, v224
	v_fmac_f32_e32 v87, v39, v225
	v_fmac_f32_e32 v88, v40, v226
	v_fmac_f32_e32 v89, v41, v227
	ds_read_b128 v[196:199], v77 offset:33472
	ds_read_b128 v[200:203], v77 offset:33488
	ds_read_b128 v[204:207], v77 offset:33504
	ds_read_b128 v[208:211], v77 offset:33520
	s_waitcnt lgkmcnt(4)
	v_fmac_f32_e32 v86, v42, v228
	v_fmac_f32_e32 v87, v43, v229
	v_fmac_f32_e32 v88, v44, v230
	v_fmac_f32_e32 v89, v45, v231
	v_fmac_f32_e32 v86, v46, v232
	v_fmac_f32_e32 v87, v47, v233
	v_fmac_f32_e32 v88, v48, v234
	v_fmac_f32_e32 v89, v49, v235
	v_fmac_f32_e32 v86, v74, v236
	v_fmac_f32_e32 v87, v58, v237
	v_fmac_f32_e32 v88, v60, v238
	v_fmac_f32_e32 v89, v72, v239
	v_fmac_f32_e32 v86, v75, v240
	v_fmac_f32_e32 v87, v59, v241
	v_fmac_f32_e32 v88, v61, v242
	v_fmac_f32_e32 v89, v73, v243
	s_waitcnt lgkmcnt(0)
	v_fmac_f32_e32 v86, v70, v196
	v_fmac_f32_e32 v87, v54, v197
	v_fmac_f32_e32 v88, v56, v198
	v_fmac_f32_e32 v89, v68, v199
	v_fmac_f32_e32 v86, v71, v200
	v_fmac_f32_e32 v87, v55, v201
	v_fmac_f32_e32 v88, v57, v202
	v_fmac_f32_e32 v89, v69, v203
	v_fmac_f32_e32 v86, v66, v204
	v_fmac_f32_e32 v87, v50, v205
	v_fmac_f32_e32 v88, v52, v206
	v_fmac_f32_e32 v89, v64, v207
	v_fmac_f32_e32 v86, v67, v208
	v_fmac_f32_e32 v87, v51, v209
	v_fmac_f32_e32 v88, v53, v210
	v_fmac_f32_e32 v89, v65, v211
	v_add_f32_e32 v86, v86, v87
	v_add_f32_e32 v88, v88, v89
	s_waitcnt vmcnt(15)
	v_lshlrev_b32_e32 v87, 16, v164
	v_add_f32_e32 v86, v86, v88
	v_lshl_add_u64 v[170:171], s[34:35], 0, v[128:129]
	v_add_f32_e32 v86, v86, v87
	v_bfe_u32 v87, v86, 16, 1
	v_add3_u32 v86, v86, v87, s46
	global_store_short_d16_hi v[170:171], v86, off
	s_waitcnt vmcnt(31)
	v_lshlrev_b32_e32 v85, 16, v149
	ds_write_b32 v78, v85 offset:33280
	s_waitcnt lgkmcnt(0)
	ds_read_b128 v[196:199], v77 offset:33280
	ds_read_b128 v[200:203], v77 offset:33296
	ds_read_b128 v[204:207], v77 offset:33312
	ds_read_b128 v[208:211], v77 offset:33328
	ds_read_b128 v[212:215], v77 offset:33344
	ds_read_b128 v[216:219], v77 offset:33360
	ds_read_b128 v[220:223], v77 offset:33376
	ds_read_b128 v[224:227], v77 offset:33392
	s_waitcnt lgkmcnt(4)
	v_mul_f32_e32 v90, v2, v196
	v_mul_f32_e32 v91, v3, v197
	v_mul_f32_e32 v92, v4, v198
	v_mul_f32_e32 v93, v5, v199
	v_fmac_f32_e32 v90, v6, v200
	v_fmac_f32_e32 v91, v7, v201
	v_fmac_f32_e32 v92, v8, v202
	v_fmac_f32_e32 v93, v9, v203
	v_fmac_f32_e32 v90, v18, v204
	v_fmac_f32_e32 v91, v19, v205
	v_fmac_f32_e32 v92, v20, v206
	v_fmac_f32_e32 v93, v21, v207
	v_fmac_f32_e32 v90, v22, v208
	v_fmac_f32_e32 v91, v23, v209
	v_fmac_f32_e32 v92, v24, v210
	v_fmac_f32_e32 v93, v25, v211
	ds_read_b128 v[228:231], v77 offset:33408
	ds_read_b128 v[232:235], v77 offset:33424
	ds_read_b128 v[236:239], v77 offset:33440
	ds_read_b128 v[240:243], v77 offset:33456
	s_waitcnt lgkmcnt(4)
	v_fmac_f32_e32 v90, v26, v212
	v_fmac_f32_e32 v91, v27, v213
	v_fmac_f32_e32 v92, v28, v214
	v_fmac_f32_e32 v93, v29, v215
	v_fmac_f32_e32 v90, v30, v216
	v_fmac_f32_e32 v91, v31, v217
	v_fmac_f32_e32 v92, v32, v218
	v_fmac_f32_e32 v93, v33, v219
	v_fmac_f32_e32 v90, v34, v220
	v_fmac_f32_e32 v91, v35, v221
	v_fmac_f32_e32 v92, v36, v222
	v_fmac_f32_e32 v93, v37, v223
	v_fmac_f32_e32 v90, v38, v224
	v_fmac_f32_e32 v91, v39, v225
	v_fmac_f32_e32 v92, v40, v226
	v_fmac_f32_e32 v93, v41, v227
	ds_read_b128 v[196:199], v77 offset:33472
	ds_read_b128 v[200:203], v77 offset:33488
	ds_read_b128 v[204:207], v77 offset:33504
	ds_read_b128 v[208:211], v77 offset:33520
	s_waitcnt lgkmcnt(4)
; __device__ __forceinline__ bf16_t f2bf(float f) { unsigned u = __float_as_uint(f); u += 0x7FFFu + ((u >> 16) & 1u); return (bf16_t)(u >> 16); }
; __device__ __forceinline__ float bf2f(unsigned b) { return __uint_as_float(b << 16); }
; __device__ void phase_fixup(const float* FS, const bf16_t* Q, bf16_t* Y, float* sm) {
;     ...
;             qw[v] = bf2f(Q[o]);
;             __builtin_amdgcn_wave_barrier(); asm volatile("s_waitcnt lgkmcnt(0)" ::: "memory");
;             float acc = 0.f;
; #pragma unroll
;             for (int m4 = 0; m4 < 16; ++m4) { const f32x4 qq = *(const f32x4*)(qw + 4 * m4); acc += s0[4 * m4] * qq[0] + s0[4 * m4 + 1] * qq[1] + s0[4 * m4 + 2] * qq[2] + s0[4 * m4 + 3] * qq[3]; }
;             __builtin_amdgcn_wave_barrier();
;             Y[o] = f2bf(bf2f(Y[o]) + acc);
	v_fmac_f32_e32 v90, v42, v228
	v_fmac_f32_e32 v91, v43, v229
	v_fmac_f32_e32 v92, v44, v230
	v_fmac_f32_e32 v93, v45, v231
	v_fmac_f32_e32 v90, v46, v232
	v_fmac_f32_e32 v91, v47, v233
	v_fmac_f32_e32 v92, v48, v234
	v_fmac_f32_e32 v93, v49, v235
	v_fmac_f32_e32 v90, v74, v236
	v_fmac_f32_e32 v91, v58, v237
	v_fmac_f32_e32 v92, v60, v238
	v_fmac_f32_e32 v93, v72, v239
	v_fmac_f32_e32 v90, v75, v240
	v_fmac_f32_e32 v91, v59, v241
	v_fmac_f32_e32 v92, v61, v242
	v_fmac_f32_e32 v93, v73, v243
	s_waitcnt lgkmcnt(0)
	v_fmac_f32_e32 v90, v70, v196
	v_fmac_f32_e32 v91, v54, v197
	v_fmac_f32_e32 v92, v56, v198
	v_fmac_f32_e32 v93, v68, v199
	v_fmac_f32_e32 v90, v71, v200
	v_fmac_f32_e32 v91, v55, v201
	v_fmac_f32_e32 v92, v57, v202
	v_fmac_f32_e32 v93, v69, v203
	v_fmac_f32_e32 v90, v66, v204
	v_fmac_f32_e32 v91, v50, v205
	v_fmac_f32_e32 v92, v52, v206
	v_fmac_f32_e32 v93, v64, v207
	v_fmac_f32_e32 v90, v67, v208
	v_fmac_f32_e32 v91, v51, v209
	v_fmac_f32_e32 v92, v53, v210
	v_fmac_f32_e32 v93, v65, v211
	v_add_f32_e32 v90, v90, v91
	v_add_f32_e32 v92, v92, v93
	s_waitcnt vmcnt(15)
	v_lshlrev_b32_e32 v91, 16, v165
	v_add_f32_e32 v90, v90, v92
	v_lshl_add_u64 v[170:171], s[34:35], 0, v[130:131]
	v_add_f32_e32 v90, v90, v91
	v_bfe_u32 v91, v90, 16, 1
	v_add3_u32 v90, v90, v91, s46
	global_store_short_d16_hi v[170:171], v90, off
	s_waitcnt vmcnt(31)
	v_lshlrev_b32_e32 v85, 16, v150
	ds_write_b32 v78, v85 offset:33280
	s_waitcnt lgkmcnt(0)
	ds_read_b128 v[196:199], v77 offset:33280
	ds_read_b128 v[200:203], v77 offset:33296
	ds_read_b128 v[204:207], v77 offset:33312
	ds_read_b128 v[208:211], v77 offset:33328
	ds_read_b128 v[212:215], v77 offset:33344
	ds_read_b128 v[216:219], v77 offset:33360
	ds_read_b128 v[220:223], v77 offset:33376
	ds_read_b128 v[224:227], v77 offset:33392
	s_waitcnt lgkmcnt(4)
	v_mul_f32_e32 v86, v2, v196
	v_mul_f32_e32 v87, v3, v197
	v_mul_f32_e32 v88, v4, v198
	v_mul_f32_e32 v89, v5, v199
	v_fmac_f32_e32 v86, v6, v200
	v_fmac_f32_e32 v87, v7, v201
	v_fmac_f32_e32 v88, v8, v202
	v_fmac_f32_e32 v89, v9, v203
	v_fmac_f32_e32 v86, v18, v204
	v_fmac_f32_e32 v87, v19, v205
	v_fmac_f32_e32 v88, v20, v206
	v_fmac_f32_e32 v89, v21, v207
	v_fmac_f32_e32 v86, v22, v208
	v_fmac_f32_e32 v87, v23, v209
	v_fmac_f32_e32 v88, v24, v210
	v_fmac_f32_e32 v89, v25, v211
	ds_read_b128 v[228:231], v77 offset:33408
	ds_read_b128 v[232:235], v77 offset:33424
	ds_read_b128 v[236:239], v77 offset:33440
	ds_read_b128 v[240:243], v77 offset:33456
	s_waitcnt lgkmcnt(4)
	v_fmac_f32_e32 v86, v26, v212
	v_fmac_f32_e32 v87, v27, v213
	v_fmac_f32_e32 v88, v28, v214
	v_fmac_f32_e32 v89, v29, v215
	v_fmac_f32_e32 v86, v30, v216
	v_fmac_f32_e32 v87, v31, v217
	v_fmac_f32_e32 v88, v32, v218
	v_fmac_f32_e32 v89, v33, v219
	v_fmac_f32_e32 v86, v34, v220
	v_fmac_f32_e32 v87, v35, v221
	v_fmac_f32_e32 v88, v36, v222
	v_fmac_f32_e32 v89, v37, v223
	v_fmac_f32_e32 v86, v38, v224
	v_fmac_f32_e32 v87, v39, v225
	v_fmac_f32_e32 v88, v40, v226
	v_fmac_f32_e32 v89, v41, v227
	ds_read_b128 v[196:199], v77 offset:33472
	ds_read_b128 v[200:203], v77 offset:33488
	ds_read_b128 v[204:207], v77 offset:33504
	ds_read_b128 v[208:211], v77 offset:33520
	s_waitcnt lgkmcnt(4)
	v_fmac_f32_e32 v86, v42, v228
	v_fmac_f32_e32 v87, v43, v229
	v_fmac_f32_e32 v88, v44, v230
	v_fmac_f32_e32 v89, v45, v231
	v_fmac_f32_e32 v86, v46, v232
	v_fmac_f32_e32 v87, v47, v233
	v_fmac_f32_e32 v88, v48, v234
	v_fmac_f32_e32 v89, v49, v235
	v_fmac_f32_e32 v86, v74, v236
	v_fmac_f32_e32 v87, v58, v237
	v_fmac_f32_e32 v88, v60, v238
	v_fmac_f32_e32 v89, v72, v239
	v_fmac_f32_e32 v86, v75, v240
	v_fmac_f32_e32 v87, v59, v241
	v_fmac_f32_e32 v88, v61, v242
	v_fmac_f32_e32 v89, v73, v243
	s_waitcnt lgkmcnt(0)
; __device__ __forceinline__ bf16_t f2bf(float f) { unsigned u = __float_as_uint(f); u += 0x7FFFu + ((u >> 16) & 1u); return (bf16_t)(u >> 16); }
; __device__ __forceinline__ float bf2f(unsigned b) { return __uint_as_float(b << 16); }
; __device__ void phase_fixup(const float* FS, const bf16_t* Q, bf16_t* Y, float* sm) {
;     ...
;             qw[v] = bf2f(Q[o]);
;             __builtin_amdgcn_wave_barrier(); asm volatile("s_waitcnt lgkmcnt(0)" ::: "memory");
;             float acc = 0.f;
; #pragma unroll
;             for (int m4 = 0; m4 < 16; ++m4) { const f32x4 qq = *(const f32x4*)(qw + 4 * m4); acc += s0[4 * m4] * qq[0] + s0[4 * m4 + 1] * qq[1] + s0[4 * m4 + 2] * qq[2] + s0[4 * m4 + 3] * qq[3]; }
;             __builtin_amdgcn_wave_barrier();
;             Y[o] = f2bf(bf2f(Y[o]) + acc);
	v_fmac_f32_e32 v86, v70, v196
	v_fmac_f32_e32 v87, v54, v197
	v_fmac_f32_e32 v88, v56, v198
	v_fmac_f32_e32 v89, v68, v199
	v_fmac_f32_e32 v86, v71, v200
	v_fmac_f32_e32 v87, v55, v201
	v_fmac_f32_e32 v88, v57, v202
	v_fmac_f32_e32 v89, v69, v203
	v_fmac_f32_e32 v86, v66, v204
	v_fmac_f32_e32 v87, v50, v205
	v_fmac_f32_e32 v88, v52, v206
	v_fmac_f32_e32 v89, v64, v207
	v_fmac_f32_e32 v86, v67, v208
	v_fmac_f32_e32 v87, v51, v209
	v_fmac_f32_e32 v88, v53, v210
	v_fmac_f32_e32 v89, v65, v211
	v_add_f32_e32 v86, v86, v87
	v_add_f32_e32 v88, v88, v89
	s_waitcnt vmcnt(15)
	v_lshlrev_b32_e32 v87, 16, v166
	v_add_f32_e32 v86, v86, v88
	v_lshl_add_u64 v[170:171], s[34:35], 0, v[132:133]
	v_add_f32_e32 v86, v86, v87
	v_bfe_u32 v87, v86, 16, 1
	v_add3_u32 v86, v86, v87, s46
	global_store_short_d16_hi v[170:171], v86, off
	s_waitcnt vmcnt(31)
	v_lshlrev_b32_e32 v85, 16, v151
	ds_write_b32 v78, v85 offset:33280
	s_waitcnt lgkmcnt(0)
	ds_read_b128 v[196:199], v77 offset:33280
	ds_read_b128 v[200:203], v77 offset:33296
	ds_read_b128 v[204:207], v77 offset:33312
	ds_read_b128 v[208:211], v77 offset:33328
	ds_read_b128 v[212:215], v77 offset:33344
	ds_read_b128 v[216:219], v77 offset:33360
	ds_read_b128 v[220:223], v77 offset:33376
	ds_read_b128 v[224:227], v77 offset:33392
	s_waitcnt lgkmcnt(4)
	v_mul_f32_e32 v90, v2, v196
	v_mul_f32_e32 v91, v3, v197
	v_mul_f32_e32 v92, v4, v198
	v_mul_f32_e32 v93, v5, v199
	v_fmac_f32_e32 v90, v6, v200
	v_fmac_f32_e32 v91, v7, v201
	v_fmac_f32_e32 v92, v8, v202
	v_fmac_f32_e32 v93, v9, v203
	v_fmac_f32_e32 v90, v18, v204
	v_fmac_f32_e32 v91, v19, v205
	v_fmac_f32_e32 v92, v20, v206
	v_fmac_f32_e32 v93, v21, v207
	v_fmac_f32_e32 v90, v22, v208
	v_fmac_f32_e32 v91, v23, v209
	v_fmac_f32_e32 v92, v24, v210
	v_fmac_f32_e32 v93, v25, v211
	ds_read_b128 v[228:231], v77 offset:33408
	ds_read_b128 v[232:235], v77 offset:33424
	ds_read_b128 v[236:239], v77 offset:33440
	ds_read_b128 v[240:243], v77 offset:33456
	s_waitcnt lgkmcnt(4)
	v_fmac_f32_e32 v90, v26, v212
	v_fmac_f32_e32 v91, v27, v213
	v_fmac_f32_e32 v92, v28, v214
	v_fmac_f32_e32 v93, v29, v215
	v_fmac_f32_e32 v90, v30, v216
	v_fmac_f32_e32 v91, v31, v217
	v_fmac_f32_e32 v92, v32, v218
	v_fmac_f32_e32 v93, v33, v219
	v_fmac_f32_e32 v90, v34, v220
	v_fmac_f32_e32 v91, v35, v221
	v_fmac_f32_e32 v92, v36, v222
	v_fmac_f32_e32 v93, v37, v223
	v_fmac_f32_e32 v90, v38, v224
	v_fmac_f32_e32 v91, v39, v225
	v_fmac_f32_e32 v92, v40, v226
	v_fmac_f32_e32 v93, v41, v227
	ds_read_b128 v[196:199], v77 offset:33472
	ds_read_b128 v[200:203], v77 offset:33488
	ds_read_b128 v[204:207], v77 offset:33504
	ds_read_b128 v[208:211], v77 offset:33520
	s_waitcnt lgkmcnt(4)
	v_fmac_f32_e32 v90, v42, v228
	v_fmac_f32_e32 v91, v43, v229
	v_fmac_f32_e32 v92, v44, v230
	v_fmac_f32_e32 v93, v45, v231
	v_fmac_f32_e32 v90, v46, v232
	v_fmac_f32_e32 v91, v47, v233
	v_fmac_f32_e32 v92, v48, v234
	v_fmac_f32_e32 v93, v49, v235
	v_fmac_f32_e32 v90, v74, v236
	v_fmac_f32_e32 v91, v58, v237
	v_fmac_f32_e32 v92, v60, v238
	v_fmac_f32_e32 v93, v72, v239
	v_fmac_f32_e32 v90, v75, v240
	v_fmac_f32_e32 v91, v59, v241
	v_fmac_f32_e32 v92, v61, v242
	v_fmac_f32_e32 v93, v73, v243
	s_waitcnt lgkmcnt(0)
	v_fmac_f32_e32 v90, v70, v196
	v_fmac_f32_e32 v91, v54, v197
	v_fmac_f32_e32 v92, v56, v198
	v_fmac_f32_e32 v93, v68, v199
	v_fmac_f32_e32 v90, v71, v200
	v_fmac_f32_e32 v91, v55, v201
	v_fmac_f32_e32 v92, v57, v202
	v_fmac_f32_e32 v93, v69, v203
	v_fmac_f32_e32 v90, v66, v204
	v_fmac_f32_e32 v91, v50, v205
	v_fmac_f32_e32 v92, v52, v206
	v_fmac_f32_e32 v93, v64, v207
	v_fmac_f32_e32 v90, v67, v208
	v_fmac_f32_e32 v91, v51, v209
	v_fmac_f32_e32 v92, v53, v210
	v_fmac_f32_e32 v93, v65, v211
	v_add_f32_e32 v90, v90, v91
	v_add_f32_e32 v92, v92, v93
	s_waitcnt vmcnt(15)
	v_lshlrev_b32_e32 v91, 16, v167
	v_add_f32_e32 v90, v90, v92
	v_lshl_add_u64 v[170:171], s[34:35], 0, v[134:135]
	v_add_f32_e32 v90, v90, v91
	v_bfe_u32 v91, v90, 16, 1
	v_add3_u32 v90, v90, v91, s46
	global_store_short_d16_hi v[170:171], v90, off
	s_andn2_b64 exec, exec, s[54:55]
	s_cbranch_execnz .LBB0_40
	s_branch .LBB0_23

; __device__ __forceinline__ void scan_rows(f32x2 (&X)[8], const ScanOps& o, const f32x4 (&b)[2], const f32x4 (&kd)[2], const f32x4 (&r)[2], const bool use_v, float& yA, float& yB) {
;     f32x2 aA = X[0] * o.kk[0].xy, aB = X[4] * o.kk[0].xy;
;     aA += X[1] * o.kk[0].zw; aB += X[5] * o.kk[0].zw;
;     aA += X[2] * o.kk[1].xy; aB += X[6] * o.kk[1].xy;
;     aA += X[3] * o.kk[1].zw; aB += X[7] * o.kk[1].zw;
;     const float saA = sum8(aA.x + aA.y), saB = sum8(aB.x + aB.y);
;     const f32x2 nA = (f32x2){-saA, -saA}, nB = (f32x2){-saB, -saB}, vA = (f32x2){o.v.x, o.v.x}, vB = (f32x2){o.v.y, o.v.y};
;     f32x2 tA, tB, accA, accB;
;     tA = X[0] * o.w[0].xy; tA += nA * b[0].xy; if (use_v) tA += vA * kd[0].xy; X[0] = tA; accA = tA * r[0].xy;
;     tB = X[4] * o.w[0].xy; tB += nB * b[0].xy; if (use_v) tB += vB * kd[0].xy; X[4] = tB; accB = tB * r[0].xy;
;     tA = X[1] * o.w[0].zw; tA += nA * b[0].zw; if (use_v) tA += vA * kd[0].zw; X[1] = tA; accA += tA * r[0].zw;
;     tB = X[5] * o.w[0].zw; tB += nB * b[0].zw; if (use_v) tB += vB * kd[0].zw; X[5] = tB; accB += tB * r[0].zw;
;     tA = X[2] * o.w[1].xy; tA += nA * b[1].xy; if (use_v) tA += vA * kd[1].xy; X[2] = tA; accA += tA * r[1].xy;
;     tB = X[6] * o.w[1].xy; tB += nB * b[1].xy; if (use_v) tB += vB * kd[1].xy; X[6] = tB; accB += tB * r[1].xy;
;     tA = X[3] * o.w[1].zw; tA += nA * b[1].zw; if (use_v) tA += vA * kd[1].zw; X[3] = tA; accA += tA * r[1].zw;
;     tB = X[7] * o.w[1].zw; tB += nB * b[1].zw; if (use_v) tB += vB * kd[1].zw; X[7] = tB; accB += tB * r[1].zw;
;     yA = sum8(accA.x + accA.y); yB = sum8(accB.x + accB.y);
; __device__ void phase_scan(int c, const bf16_t* PROJ, const float* k_k, const bf16_t* Wd, const bf16_t* Bd, const float* k_a, bf16_t* Y, bf16_t* Q, float* FS, float* sm) {
;     ...
;                 const float* ob = opb + (ci & 1) * 6144 + q * 8;
;                 const float* obv = opb + (ci & 1) * 6144 + 5120 + wq * 16 + 2 * vp;
;                 ScanOps A, B;
;                 scan_ld(ob, obv, 0, A);
; #pragma unroll
;                 for (int i = 0; i < 16; i += 2) {
;                     float yA = 0.f, yB = 0.f;
;                     scan_ld(ob, obv, i + 1, B);
;                     if (roleP) A.v = (f32x2){0.f, 0.f};
;                     scan_step1(X, A, ob + i * 64, yA, yB);
;                     *(f32x2*)(obw + i * 16 + 2 * vp) = (f32x2){yA, yB};
.LBB0_75:
	s_or_b64 exec, exec, s[56:57]
	s_and_saveexec_b64 s[12:13], s[54:55]
	s_cbranch_execz .LBB0_71
	s_bitcmp1_b32 s28, 0
	s_cselect_b32 s41, 0x6000, 0
	s_add_i32 s41, s41, 0
	v_lshl_add_u32 v84, v68, 2, s41
	v_lshlrev_b32_e32 v85, 2, v66
	v_lshlrev_b32_e32 v86, 2, v67
	v_add3_u32 v85, s41, v85, v86
	ds_read_b128 v[86:89], v84 offset:0
	ds_read_b128 v[90:93], v84 offset:16
	ds_read_b128 v[94:97], v84 offset:4096
	ds_read_b128 v[98:101], v84 offset:4112
	ds_read_b128 v[102:105], v84 offset:8192
	ds_read_b128 v[106:109], v84 offset:8208
	ds_read_b128 v[110:113], v84 offset:12288
	ds_read_b128 v[114:117], v84 offset:12304
	ds_read_b128 v[118:121], v84 offset:16384
	ds_read_b128 v[122:125], v84 offset:16400
	ds_read_b64 v[126:127], v85 offset:20480
	s_waitcnt lgkmcnt(0)
	ds_read_b128 v[128:131], v84 offset:256
	ds_read_b128 v[132:135], v84 offset:272
	ds_read_b128 v[136:139], v84 offset:4352
	ds_read_b128 v[140:143], v84 offset:4368
	ds_read_b128 v[144:147], v84 offset:8448
	ds_read_b128 v[148:151], v84 offset:8464
	ds_read_b128 v[152:155], v84 offset:12544
	ds_read_b128 v[156:159], v84 offset:12560
	ds_read_b128 v[160:163], v84 offset:16640
	ds_read_b128 v[164:167], v84 offset:16656
	ds_read_b64 v[168:169], v85 offset:20736
	v_cndmask_b32_e64 v126, v126, 0, s[8:9]
	v_cndmask_b32_e64 v127, v127, 0, s[8:9]
	v_pk_mul_f32 v[212:213], v[22:23], v[94:95]
	v_pk_mul_f32 v[216:217], v[14:15], v[94:95]
	v_pk_mul_f32 v[214:215], v[18:19], v[98:99]
	v_pk_mul_f32 v[218:219], v[10:11], v[98:99]
	v_pk_fma_f32 v[212:213], v[24:25], v[96:97], v[212:213]
	v_pk_fma_f32 v[216:217], v[16:17], v[96:97], v[216:217]
	v_pk_fma_f32 v[214:215], v[20:21], v[100:101], v[214:215]
	v_pk_fma_f32 v[218:219], v[12:13], v[100:101], v[218:219]
	v_pk_add_f32 v[212:213], v[212:213], v[214:215]
	v_pk_add_f32 v[216:217], v[216:217], v[218:219]
	v_pk_mul_f32 v[196:197], v[22:23], v[86:87]
	v_pk_mul_f32 v[204:205], v[14:15], v[86:87]
	v_add_f32_e32 v220, v212, v213
	v_add_f32_e32 v221, v216, v217
	v_pk_mul_f32 v[198:199], v[24:25], v[88:89]
	v_pk_mul_f32 v[206:207], v[16:17], v[88:89]
	v_add_f32_dpp v220, v220, v220 quad_perm:[1,0,3,2] row_mask:0xf bank_mask:0xf bound_ctrl:1
	v_add_f32_dpp v221, v221, v221 quad_perm:[1,0,3,2] row_mask:0xf bank_mask:0xf bound_ctrl:1
	v_pk_mul_f32 v[200:201], v[18:19], v[90:91]
	v_pk_mul_f32 v[208:209], v[10:11], v[90:91]
	v_add_f32_dpp v220, v220, v220 quad_perm:[2,3,0,1] row_mask:0xf bank_mask:0xf bound_ctrl:1
	v_add_f32_dpp v221, v221, v221 quad_perm:[2,3,0,1] row_mask:0xf bank_mask:0xf bound_ctrl:1
	v_pk_mul_f32 v[202:203], v[20:21], v[92:93]
	v_pk_mul_f32 v[210:211], v[12:13], v[92:93]
	v_add_f32_dpp v220, v220, v220 row_half_mirror row_mask:0xf bank_mask:0xf bound_ctrl:1
	v_add_f32_dpp v221, v221, v221 row_half_mirror row_mask:0xf bank_mask:0xf bound_ctrl:1
	v_pk_fma_f32 v[196:197], v[126:127], v[110:111], v[196:197] op_sel_hi:[0,1,1]
	v_pk_fma_f32 v[204:205], v[126:127], v[110:111], v[204:205] op_sel:[1,0,0] op_sel_hi:[1,1,1]
	v_pk_fma_f32 v[198:199], v[126:127], v[112:113], v[198:199] op_sel_hi:[0,1,1]
	v_pk_fma_f32 v[206:207], v[126:127], v[112:113], v[206:207] op_sel:[1,0,0] op_sel_hi:[1,1,1]
	v_pk_fma_f32 v[200:201], v[126:127], v[114:115], v[200:201] op_sel_hi:[0,1,1]
	v_pk_fma_f32 v[208:209], v[126:127], v[114:115], v[208:209] op_sel:[1,0,0] op_sel_hi:[1,1,1]
	v_pk_fma_f32 v[202:203], v[126:127], v[116:117], v[202:203] op_sel_hi:[0,1,1]
	v_pk_fma_f32 v[210:211], v[126:127], v[116:117], v[210:211] op_sel:[1,0,0] op_sel_hi:[1,1,1]
	v_pk_fma_f32 v[22:23], v[220:221], v[102:103], v[196:197] op_sel_hi:[0,1,1] neg_lo:[1,0,0] neg_hi:[1,0,0]
	v_pk_fma_f32 v[14:15], v[220:221], v[102:103], v[204:205] op_sel:[1,0,0] op_sel_hi:[1,1,1] neg_lo:[1,0,0] neg_hi:[1,0,0]
	v_pk_fma_f32 v[24:25], v[220:221], v[104:105], v[198:199] op_sel_hi:[0,1,1] neg_lo:[1,0,0] neg_hi:[1,0,0]
	v_pk_fma_f32 v[16:17], v[220:221], v[104:105], v[206:207] op_sel:[1,0,0] op_sel_hi:[1,1,1] neg_lo:[1,0,0] neg_hi:[1,0,0]
	v_pk_fma_f32 v[18:19], v[220:221], v[106:107], v[200:201] op_sel_hi:[0,1,1] neg_lo:[1,0,0] neg_hi:[1,0,0]
	v_pk_fma_f32 v[10:11], v[220:221], v[106:107], v[208:209] op_sel:[1,0,0] op_sel_hi:[1,1,1] neg_lo:[1,0,0] neg_hi:[1,0,0]
	v_pk_fma_f32 v[20:21], v[220:221], v[108:109], v[202:203] op_sel_hi:[0,1,1] neg_lo:[1,0,0] neg_hi:[1,0,0]
	v_pk_fma_f32 v[12:13], v[220:221], v[108:109], v[210:211] op_sel:[1,0,0] op_sel_hi:[1,1,1] neg_lo:[1,0,0] neg_hi:[1,0,0]
	v_pk_mul_f32 v[222:223], v[22:23], v[118:119]
	v_pk_mul_f32 v[224:225], v[14:15], v[118:119]
	v_pk_fma_f32 v[222:223], v[24:25], v[120:121], v[222:223]
	v_pk_fma_f32 v[224:225], v[16:17], v[120:121], v[224:225]
	v_pk_fma_f32 v[222:223], v[18:19], v[122:123], v[222:223]
	v_pk_fma_f32 v[224:225], v[10:11], v[122:123], v[224:225]
	v_pk_fma_f32 v[222:223], v[20:21], v[124:125], v[222:223]
	v_pk_fma_f32 v[224:225], v[12:13], v[124:125], v[224:225]
	s_waitcnt lgkmcnt(0)
; __device__ __forceinline__ void scan_rows(f32x2 (&X)[8], const ScanOps& o, const f32x4 (&b)[2], const f32x4 (&kd)[2], const f32x4 (&r)[2], const bool use_v, float& yA, float& yB) {
;     f32x2 aA = X[0] * o.kk[0].xy, aB = X[4] * o.kk[0].xy;
;     aA += X[1] * o.kk[0].zw; aB += X[5] * o.kk[0].zw;
;     aA += X[2] * o.kk[1].xy; aB += X[6] * o.kk[1].xy;
;     aA += X[3] * o.kk[1].zw; aB += X[7] * o.kk[1].zw;
;     const float saA = sum8(aA.x + aA.y), saB = sum8(aB.x + aB.y);
;     const f32x2 nA = (f32x2){-saA, -saA}, nB = (f32x2){-saB, -saB}, vA = (f32x2){o.v.x, o.v.x}, vB = (f32x2){o.v.y, o.v.y};
;     f32x2 tA, tB, accA, accB;
;     tA = X[0] * o.w[0].xy; tA += nA * b[0].xy; if (use_v) tA += vA * kd[0].xy; X[0] = tA; accA = tA * r[0].xy;
;     tB = X[4] * o.w[0].xy; tB += nB * b[0].xy; if (use_v) tB += vB * kd[0].xy; X[4] = tB; accB = tB * r[0].xy;
;     tA = X[1] * o.w[0].zw; tA += nA * b[0].zw; if (use_v) tA += vA * kd[0].zw; X[1] = tA; accA += tA * r[0].zw;
;     tB = X[5] * o.w[0].zw; tB += nB * b[0].zw; if (use_v) tB += vB * kd[0].zw; X[5] = tB; accB += tB * r[0].zw;
;     tA = X[2] * o.w[1].xy; tA += nA * b[1].xy; if (use_v) tA += vA * kd[1].xy; X[2] = tA; accA += tA * r[1].xy;
;     tB = X[6] * o.w[1].xy; tB += nB * b[1].xy; if (use_v) tB += vB * kd[1].xy; X[6] = tB; accB += tB * r[1].xy;
;     tA = X[3] * o.w[1].zw; tA += nA * b[1].zw; if (use_v) tA += vA * kd[1].zw; X[3] = tA; accA += tA * r[1].zw;
;     tB = X[7] * o.w[1].zw; tB += nB * b[1].zw; if (use_v) tB += vB * kd[1].zw; X[7] = tB; accB += tB * r[1].zw;
;     yA = sum8(accA.x + accA.y); yB = sum8(accB.x + accB.y);
; __device__ void phase_scan(int c, const bf16_t* PROJ, const float* k_k, const bf16_t* Wd, const bf16_t* Bd, const float* k_a, bf16_t* Y, bf16_t* Q, float* FS, float* sm) {
;     ...
;                 for (int i = 0; i < 16; i += 2) {
;                     float yA = 0.f, yB = 0.f;
;                     scan_ld(ob, obv, i + 1, B);
;                     if (roleP) A.v = (f32x2){0.f, 0.f};
;                     scan_step1(X, A, ob + i * 64, yA, yB);
;                     *(f32x2*)(obw + i * 16 + 2 * vp) = (f32x2){yA, yB};
;                     if (i + 2 < 16) scan_ld(ob, obv, i + 2, A);
;                     if (roleP) B.v = (f32x2){0.f, 0.f};
;                     scan_step1(X, B, ob + (i + 1) * 64, yA, yB);
;                     *(f32x2*)(obw + (i + 1) * 16 + 2 * vp) = (f32x2){yA, yB};
	ds_read_b128 v[86:89], v84 offset:512
	ds_read_b128 v[90:93], v84 offset:528
	ds_read_b128 v[94:97], v84 offset:4608
	ds_read_b128 v[98:101], v84 offset:4624
	ds_read_b128 v[102:105], v84 offset:8704
	ds_read_b128 v[106:109], v84 offset:8720
	ds_read_b128 v[110:113], v84 offset:12800
	ds_read_b128 v[114:117], v84 offset:12816
	ds_read_b128 v[118:121], v84 offset:16896
	ds_read_b128 v[122:125], v84 offset:16912
	ds_read_b64 v[126:127], v85 offset:20992
	v_cndmask_b32_e64 v168, v168, 0, s[8:9]
	v_cndmask_b32_e64 v169, v169, 0, s[8:9]
	v_pk_mul_f32 v[212:213], v[22:23], v[136:137]
	v_pk_mul_f32 v[216:217], v[14:15], v[136:137]
	v_pk_mul_f32 v[214:215], v[18:19], v[140:141]
	v_pk_mul_f32 v[218:219], v[10:11], v[140:141]
	v_pk_fma_f32 v[212:213], v[24:25], v[138:139], v[212:213]
	v_pk_fma_f32 v[216:217], v[16:17], v[138:139], v[216:217]
	v_pk_fma_f32 v[214:215], v[20:21], v[142:143], v[214:215]
	v_pk_fma_f32 v[218:219], v[12:13], v[142:143], v[218:219]
	v_add_f32_e32 v226, v222, v223
	v_add_f32_e32 v227, v224, v225
	v_pk_add_f32 v[212:213], v[212:213], v[214:215]
	v_pk_add_f32 v[216:217], v[216:217], v[218:219]
	v_pk_mul_f32 v[196:197], v[22:23], v[128:129]
	v_pk_mul_f32 v[204:205], v[14:15], v[128:129]
	v_add_f32_e32 v220, v212, v213
	v_add_f32_e32 v221, v216, v217
	v_add_f32_dpp v226, v226, v226 quad_perm:[1,0,3,2] row_mask:0xf bank_mask:0xf bound_ctrl:1
	v_add_f32_dpp v227, v227, v227 quad_perm:[1,0,3,2] row_mask:0xf bank_mask:0xf bound_ctrl:1
	v_add_f32_dpp v220, v220, v220 quad_perm:[1,0,3,2] row_mask:0xf bank_mask:0xf bound_ctrl:1
	v_add_f32_dpp v221, v221, v221 quad_perm:[1,0,3,2] row_mask:0xf bank_mask:0xf bound_ctrl:1
	v_pk_mul_f32 v[198:199], v[24:25], v[130:131]
	v_pk_mul_f32 v[206:207], v[16:17], v[130:131]
	v_add_f32_dpp v226, v226, v226 quad_perm:[2,3,0,1] row_mask:0xf bank_mask:0xf bound_ctrl:1
	v_add_f32_dpp v227, v227, v227 quad_perm:[2,3,0,1] row_mask:0xf bank_mask:0xf bound_ctrl:1
	v_add_f32_dpp v220, v220, v220 quad_perm:[2,3,0,1] row_mask:0xf bank_mask:0xf bound_ctrl:1
	v_add_f32_dpp v221, v221, v221 quad_perm:[2,3,0,1] row_mask:0xf bank_mask:0xf bound_ctrl:1
	v_pk_mul_f32 v[200:201], v[18:19], v[132:133]
	v_pk_mul_f32 v[208:209], v[10:11], v[132:133]
	v_add_f32_dpp v226, v226, v226 row_half_mirror row_mask:0xf bank_mask:0xf bound_ctrl:1
	v_add_f32_dpp v227, v227, v227 row_half_mirror row_mask:0xf bank_mask:0xf bound_ctrl:1
	v_add_f32_dpp v220, v220, v220 row_half_mirror row_mask:0xf bank_mask:0xf bound_ctrl:1
	v_add_f32_dpp v221, v221, v221 row_half_mirror row_mask:0xf bank_mask:0xf bound_ctrl:1
	v_pk_mul_f32 v[202:203], v[20:21], v[134:135]
	v_pk_mul_f32 v[210:211], v[12:13], v[134:135]
	v_pk_fma_f32 v[196:197], v[168:169], v[152:153], v[196:197] op_sel_hi:[0,1,1]
	v_pk_fma_f32 v[204:205], v[168:169], v[152:153], v[204:205] op_sel:[1,0,0] op_sel_hi:[1,1,1]
	v_pk_fma_f32 v[198:199], v[168:169], v[154:155], v[198:199] op_sel_hi:[0,1,1]
	v_pk_fma_f32 v[206:207], v[168:169], v[154:155], v[206:207] op_sel:[1,0,0] op_sel_hi:[1,1,1]
	v_pk_fma_f32 v[200:201], v[168:169], v[156:157], v[200:201] op_sel_hi:[0,1,1]
	v_pk_fma_f32 v[208:209], v[168:169], v[156:157], v[208:209] op_sel:[1,0,0] op_sel_hi:[1,1,1]
	v_pk_fma_f32 v[202:203], v[168:169], v[158:159], v[202:203] op_sel_hi:[0,1,1]
	v_pk_fma_f32 v[210:211], v[168:169], v[158:159], v[210:211] op_sel:[1,0,0] op_sel_hi:[1,1,1]
	ds_write_b64 v70, v[226:227]
	v_pk_fma_f32 v[22:23], v[220:221], v[144:145], v[196:197] op_sel_hi:[0,1,1] neg_lo:[1,0,0] neg_hi:[1,0,0]
	v_pk_fma_f32 v[14:15], v[220:221], v[144:145], v[204:205] op_sel:[1,0,0] op_sel_hi:[1,1,1] neg_lo:[1,0,0] neg_hi:[1,0,0]
	v_pk_fma_f32 v[24:25], v[220:221], v[146:147], v[198:199] op_sel_hi:[0,1,1] neg_lo:[1,0,0] neg_hi:[1,0,0]
	v_pk_fma_f32 v[16:17], v[220:221], v[146:147], v[206:207] op_sel:[1,0,0] op_sel_hi:[1,1,1] neg_lo:[1,0,0] neg_hi:[1,0,0]
	v_pk_fma_f32 v[18:19], v[220:221], v[148:149], v[200:201] op_sel_hi:[0,1,1] neg_lo:[1,0,0] neg_hi:[1,0,0]
	v_pk_fma_f32 v[10:11], v[220:221], v[148:149], v[208:209] op_sel:[1,0,0] op_sel_hi:[1,1,1] neg_lo:[1,0,0] neg_hi:[1,0,0]
	v_pk_fma_f32 v[20:21], v[220:221], v[150:151], v[202:203] op_sel_hi:[0,1,1] neg_lo:[1,0,0] neg_hi:[1,0,0]
	v_pk_fma_f32 v[12:13], v[220:221], v[150:151], v[210:211] op_sel:[1,0,0] op_sel_hi:[1,1,1] neg_lo:[1,0,0] neg_hi:[1,0,0]
	v_pk_mul_f32 v[222:223], v[22:23], v[160:161]
	v_pk_mul_f32 v[224:225], v[14:15], v[160:161]
	v_pk_fma_f32 v[222:223], v[24:25], v[162:163], v[222:223]
	v_pk_fma_f32 v[224:225], v[16:17], v[162:163], v[224:225]
	v_pk_fma_f32 v[222:223], v[18:19], v[164:165], v[222:223]
	v_pk_fma_f32 v[224:225], v[10:11], v[164:165], v[224:225]
	v_pk_fma_f32 v[222:223], v[20:21], v[166:167], v[222:223]
	v_pk_fma_f32 v[224:225], v[12:13], v[166:167], v[224:225]
	s_waitcnt lgkmcnt(0)
; __device__ __forceinline__ void scan_rows(f32x2 (&X)[8], const ScanOps& o, const f32x4 (&b)[2], const f32x4 (&kd)[2], const f32x4 (&r)[2], const bool use_v, float& yA, float& yB) {
;     f32x2 aA = X[0] * o.kk[0].xy, aB = X[4] * o.kk[0].xy;
;     aA += X[1] * o.kk[0].zw; aB += X[5] * o.kk[0].zw;
;     aA += X[2] * o.kk[1].xy; aB += X[6] * o.kk[1].xy;
;     aA += X[3] * o.kk[1].zw; aB += X[7] * o.kk[1].zw;
;     const float saA = sum8(aA.x + aA.y), saB = sum8(aB.x + aB.y);
;     const f32x2 nA = (f32x2){-saA, -saA}, nB = (f32x2){-saB, -saB}, vA = (f32x2){o.v.x, o.v.x}, vB = (f32x2){o.v.y, o.v.y};
;     f32x2 tA, tB, accA, accB;
;     tA = X[0] * o.w[0].xy; tA += nA * b[0].xy; if (use_v) tA += vA * kd[0].xy; X[0] = tA; accA = tA * r[0].xy;
;     tB = X[4] * o.w[0].xy; tB += nB * b[0].xy; if (use_v) tB += vB * kd[0].xy; X[4] = tB; accB = tB * r[0].xy;
;     tA = X[1] * o.w[0].zw; tA += nA * b[0].zw; if (use_v) tA += vA * kd[0].zw; X[1] = tA; accA += tA * r[0].zw;
;     tB = X[5] * o.w[0].zw; tB += nB * b[0].zw; if (use_v) tB += vB * kd[0].zw; X[5] = tB; accB += tB * r[0].zw;
;     tA = X[2] * o.w[1].xy; tA += nA * b[1].xy; if (use_v) tA += vA * kd[1].xy; X[2] = tA; accA += tA * r[1].xy;
;     tB = X[6] * o.w[1].xy; tB += nB * b[1].xy; if (use_v) tB += vB * kd[1].xy; X[6] = tB; accB += tB * r[1].xy;
;     tA = X[3] * o.w[1].zw; tA += nA * b[1].zw; if (use_v) tA += vA * kd[1].zw; X[3] = tA; accA += tA * r[1].zw;
;     tB = X[7] * o.w[1].zw; tB += nB * b[1].zw; if (use_v) tB += vB * kd[1].zw; X[7] = tB; accB += tB * r[1].zw;
;     yA = sum8(accA.x + accA.y); yB = sum8(accB.x + accB.y);
; __device__ void phase_scan(int c, const bf16_t* PROJ, const float* k_k, const bf16_t* Wd, const bf16_t* Bd, const float* k_a, bf16_t* Y, bf16_t* Q, float* FS, float* sm) {
;     ...
;                 for (int i = 0; i < 16; i += 2) {
;                     float yA = 0.f, yB = 0.f;
;                     scan_ld(ob, obv, i + 1, B);
;                     if (roleP) A.v = (f32x2){0.f, 0.f};
;                     scan_step1(X, A, ob + i * 64, yA, yB);
;                     *(f32x2*)(obw + i * 16 + 2 * vp) = (f32x2){yA, yB};
;                     if (i + 2 < 16) scan_ld(ob, obv, i + 2, A);
;                     if (roleP) B.v = (f32x2){0.f, 0.f};
;                     scan_step1(X, B, ob + (i + 1) * 64, yA, yB);
;                     *(f32x2*)(obw + (i + 1) * 16 + 2 * vp) = (f32x2){yA, yB};
	ds_read_b128 v[128:131], v84 offset:768
	ds_read_b128 v[132:135], v84 offset:784
	ds_read_b128 v[136:139], v84 offset:4864
	ds_read_b128 v[140:143], v84 offset:4880
	ds_read_b128 v[144:147], v84 offset:8960
	ds_read_b128 v[148:151], v84 offset:8976
	ds_read_b128 v[152:155], v84 offset:13056
	ds_read_b128 v[156:159], v84 offset:13072
	ds_read_b128 v[160:163], v84 offset:17152
	ds_read_b128 v[164:167], v84 offset:17168
	ds_read_b64 v[168:169], v85 offset:21248
	v_cndmask_b32_e64 v126, v126, 0, s[8:9]
	v_cndmask_b32_e64 v127, v127, 0, s[8:9]
	v_pk_mul_f32 v[212:213], v[22:23], v[94:95]
	v_pk_mul_f32 v[216:217], v[14:15], v[94:95]
	v_pk_mul_f32 v[214:215], v[18:19], v[98:99]
	v_pk_mul_f32 v[218:219], v[10:11], v[98:99]
	v_pk_fma_f32 v[212:213], v[24:25], v[96:97], v[212:213]
	v_pk_fma_f32 v[216:217], v[16:17], v[96:97], v[216:217]
	v_pk_fma_f32 v[214:215], v[20:21], v[100:101], v[214:215]
	v_pk_fma_f32 v[218:219], v[12:13], v[100:101], v[218:219]
	v_add_f32_e32 v226, v222, v223
	v_add_f32_e32 v227, v224, v225
	v_pk_add_f32 v[212:213], v[212:213], v[214:215]
	v_pk_add_f32 v[216:217], v[216:217], v[218:219]
	v_pk_mul_f32 v[196:197], v[22:23], v[86:87]
	v_pk_mul_f32 v[204:205], v[14:15], v[86:87]
	v_add_f32_e32 v220, v212, v213
	v_add_f32_e32 v221, v216, v217
	v_add_f32_dpp v226, v226, v226 quad_perm:[1,0,3,2] row_mask:0xf bank_mask:0xf bound_ctrl:1
	v_add_f32_dpp v227, v227, v227 quad_perm:[1,0,3,2] row_mask:0xf bank_mask:0xf bound_ctrl:1
	v_add_f32_dpp v220, v220, v220 quad_perm:[1,0,3,2] row_mask:0xf bank_mask:0xf bound_ctrl:1
	v_add_f32_dpp v221, v221, v221 quad_perm:[1,0,3,2] row_mask:0xf bank_mask:0xf bound_ctrl:1
	v_pk_mul_f32 v[198:199], v[24:25], v[88:89]
	v_pk_mul_f32 v[206:207], v[16:17], v[88:89]
	v_add_f32_dpp v226, v226, v226 quad_perm:[2,3,0,1] row_mask:0xf bank_mask:0xf bound_ctrl:1
	v_add_f32_dpp v227, v227, v227 quad_perm:[2,3,0,1] row_mask:0xf bank_mask:0xf bound_ctrl:1
	v_add_f32_dpp v220, v220, v220 quad_perm:[2,3,0,1] row_mask:0xf bank_mask:0xf bound_ctrl:1
	v_add_f32_dpp v221, v221, v221 quad_perm:[2,3,0,1] row_mask:0xf bank_mask:0xf bound_ctrl:1
	v_pk_mul_f32 v[200:201], v[18:19], v[90:91]
	v_pk_mul_f32 v[208:209], v[10:11], v[90:91]
	v_add_f32_dpp v226, v226, v226 row_half_mirror row_mask:0xf bank_mask:0xf bound_ctrl:1
	v_add_f32_dpp v227, v227, v227 row_half_mirror row_mask:0xf bank_mask:0xf bound_ctrl:1
	v_add_f32_dpp v220, v220, v220 row_half_mirror row_mask:0xf bank_mask:0xf bound_ctrl:1
	v_add_f32_dpp v221, v221, v221 row_half_mirror row_mask:0xf bank_mask:0xf bound_ctrl:1
	v_pk_mul_f32 v[202:203], v[20:21], v[92:93]
	v_pk_mul_f32 v[210:211], v[12:13], v[92:93]
	v_pk_fma_f32 v[196:197], v[126:127], v[110:111], v[196:197] op_sel_hi:[0,1,1]
	v_pk_fma_f32 v[204:205], v[126:127], v[110:111], v[204:205] op_sel:[1,0,0] op_sel_hi:[1,1,1]
	v_pk_fma_f32 v[198:199], v[126:127], v[112:113], v[198:199] op_sel_hi:[0,1,1]
	v_pk_fma_f32 v[206:207], v[126:127], v[112:113], v[206:207] op_sel:[1,0,0] op_sel_hi:[1,1,1]
	v_pk_fma_f32 v[200:201], v[126:127], v[114:115], v[200:201] op_sel_hi:[0,1,1]
	v_pk_fma_f32 v[208:209], v[126:127], v[114:115], v[208:209] op_sel:[1,0,0] op_sel_hi:[1,1,1]
	v_pk_fma_f32 v[202:203], v[126:127], v[116:117], v[202:203] op_sel_hi:[0,1,1]
	v_pk_fma_f32 v[210:211], v[126:127], v[116:117], v[210:211] op_sel:[1,0,0] op_sel_hi:[1,1,1]
	ds_write_b64 v70, v[226:227] offset:64
	v_pk_fma_f32 v[22:23], v[220:221], v[102:103], v[196:197] op_sel_hi:[0,1,1] neg_lo:[1,0,0] neg_hi:[1,0,0]
	v_pk_fma_f32 v[14:15], v[220:221], v[102:103], v[204:205] op_sel:[1,0,0] op_sel_hi:[1,1,1] neg_lo:[1,0,0] neg_hi:[1,0,0]
	v_pk_fma_f32 v[24:25], v[220:221], v[104:105], v[198:199] op_sel_hi:[0,1,1] neg_lo:[1,0,0] neg_hi:[1,0,0]
	v_pk_fma_f32 v[16:17], v[220:221], v[104:105], v[206:207] op_sel:[1,0,0] op_sel_hi:[1,1,1] neg_lo:[1,0,0] neg_hi:[1,0,0]
	v_pk_fma_f32 v[18:19], v[220:221], v[106:107], v[200:201] op_sel_hi:[0,1,1] neg_lo:[1,0,0] neg_hi:[1,0,0]
	v_pk_fma_f32 v[10:11], v[220:221], v[106:107], v[208:209] op_sel:[1,0,0] op_sel_hi:[1,1,1] neg_lo:[1,0,0] neg_hi:[1,0,0]
	v_pk_fma_f32 v[20:21], v[220:221], v[108:109], v[202:203] op_sel_hi:[0,1,1] neg_lo:[1,0,0] neg_hi:[1,0,0]
	v_pk_fma_f32 v[12:13], v[220:221], v[108:109], v[210:211] op_sel:[1,0,0] op_sel_hi:[1,1,1] neg_lo:[1,0,0] neg_hi:[1,0,0]
	v_pk_mul_f32 v[222:223], v[22:23], v[118:119]
	v_pk_mul_f32 v[224:225], v[14:15], v[118:119]
	v_pk_fma_f32 v[222:223], v[24:25], v[120:121], v[222:223]
	v_pk_fma_f32 v[224:225], v[16:17], v[120:121], v[224:225]
	v_pk_fma_f32 v[222:223], v[18:19], v[122:123], v[222:223]
	v_pk_fma_f32 v[224:225], v[10:11], v[122:123], v[224:225]
	v_pk_fma_f32 v[222:223], v[20:21], v[124:125], v[222:223]
	v_pk_fma_f32 v[224:225], v[12:13], v[124:125], v[224:225]
	s_waitcnt lgkmcnt(0)
; __device__ __forceinline__ void scan_rows(f32x2 (&X)[8], const ScanOps& o, const f32x4 (&b)[2], const f32x4 (&kd)[2], const f32x4 (&r)[2], const bool use_v, float& yA, float& yB) {
;     f32x2 aA = X[0] * o.kk[0].xy, aB = X[4] * o.kk[0].xy;
;     aA += X[1] * o.kk[0].zw; aB += X[5] * o.kk[0].zw;
;     aA += X[2] * o.kk[1].xy; aB += X[6] * o.kk[1].xy;
;     aA += X[3] * o.kk[1].zw; aB += X[7] * o.kk[1].zw;
;     const float saA = sum8(aA.x + aA.y), saB = sum8(aB.x + aB.y);
;     const f32x2 nA = (f32x2){-saA, -saA}, nB = (f32x2){-saB, -saB}, vA = (f32x2){o.v.x, o.v.x}, vB = (f32x2){o.v.y, o.v.y};
;     f32x2 tA, tB, accA, accB;
;     tA = X[0] * o.w[0].xy; tA += nA * b[0].xy; if (use_v) tA += vA * kd[0].xy; X[0] = tA; accA = tA * r[0].xy;
;     tB = X[4] * o.w[0].xy; tB += nB * b[0].xy; if (use_v) tB += vB * kd[0].xy; X[4] = tB; accB = tB * r[0].xy;
;     tA = X[1] * o.w[0].zw; tA += nA * b[0].zw; if (use_v) tA += vA * kd[0].zw; X[1] = tA; accA += tA * r[0].zw;
;     tB = X[5] * o.w[0].zw; tB += nB * b[0].zw; if (use_v) tB += vB * kd[0].zw; X[5] = tB; accB += tB * r[0].zw;
;     tA = X[2] * o.w[1].xy; tA += nA * b[1].xy; if (use_v) tA += vA * kd[1].xy; X[2] = tA; accA += tA * r[1].xy;
;     tB = X[6] * o.w[1].xy; tB += nB * b[1].xy; if (use_v) tB += vB * kd[1].xy; X[6] = tB; accB += tB * r[1].xy;
;     tA = X[3] * o.w[1].zw; tA += nA * b[1].zw; if (use_v) tA += vA * kd[1].zw; X[3] = tA; accA += tA * r[1].zw;
;     tB = X[7] * o.w[1].zw; tB += nB * b[1].zw; if (use_v) tB += vB * kd[1].zw; X[7] = tB; accB += tB * r[1].zw;
;     yA = sum8(accA.x + accA.y); yB = sum8(accB.x + accB.y);
; __device__ void phase_scan(int c, const bf16_t* PROJ, const float* k_k, const bf16_t* Wd, const bf16_t* Bd, const float* k_a, bf16_t* Y, bf16_t* Q, float* FS, float* sm) {
;     ...
;                 for (int i = 0; i < 16; i += 2) {
;                     float yA = 0.f, yB = 0.f;
;                     scan_ld(ob, obv, i + 1, B);
;                     if (roleP) A.v = (f32x2){0.f, 0.f};
;                     scan_step1(X, A, ob + i * 64, yA, yB);
;                     *(f32x2*)(obw + i * 16 + 2 * vp) = (f32x2){yA, yB};
;                     if (i + 2 < 16) scan_ld(ob, obv, i + 2, A);
;                     if (roleP) B.v = (f32x2){0.f, 0.f};
;                     scan_step1(X, B, ob + (i + 1) * 64, yA, yB);
;                     *(f32x2*)(obw + (i + 1) * 16 + 2 * vp) = (f32x2){yA, yB};
	ds_read_b128 v[86:89], v84 offset:1024
	ds_read_b128 v[90:93], v84 offset:1040
	ds_read_b128 v[94:97], v84 offset:5120
	ds_read_b128 v[98:101], v84 offset:5136
	ds_read_b128 v[102:105], v84 offset:9216
	ds_read_b128 v[106:109], v84 offset:9232
	ds_read_b128 v[110:113], v84 offset:13312
	ds_read_b128 v[114:117], v84 offset:13328
	ds_read_b128 v[118:121], v84 offset:17408
	ds_read_b128 v[122:125], v84 offset:17424
	ds_read_b64 v[126:127], v85 offset:21504
	v_cndmask_b32_e64 v168, v168, 0, s[8:9]
	v_cndmask_b32_e64 v169, v169, 0, s[8:9]
	v_pk_mul_f32 v[212:213], v[22:23], v[136:137]
	v_pk_mul_f32 v[216:217], v[14:15], v[136:137]
	v_pk_mul_f32 v[214:215], v[18:19], v[140:141]
	v_pk_mul_f32 v[218:219], v[10:11], v[140:141]
	v_pk_fma_f32 v[212:213], v[24:25], v[138:139], v[212:213]
	v_pk_fma_f32 v[216:217], v[16:17], v[138:139], v[216:217]
	v_pk_fma_f32 v[214:215], v[20:21], v[142:143], v[214:215]
	v_pk_fma_f32 v[218:219], v[12:13], v[142:143], v[218:219]
	v_add_f32_e32 v226, v222, v223
	v_add_f32_e32 v227, v224, v225
	v_pk_add_f32 v[212:213], v[212:213], v[214:215]
	v_pk_add_f32 v[216:217], v[216:217], v[218:219]
	v_pk_mul_f32 v[196:197], v[22:23], v[128:129]
	v_pk_mul_f32 v[204:205], v[14:15], v[128:129]
	v_add_f32_e32 v220, v212, v213
	v_add_f32_e32 v221, v216, v217
	v_add_f32_dpp v226, v226, v226 quad_perm:[1,0,3,2] row_mask:0xf bank_mask:0xf bound_ctrl:1
	v_add_f32_dpp v227, v227, v227 quad_perm:[1,0,3,2] row_mask:0xf bank_mask:0xf bound_ctrl:1
	v_add_f32_dpp v220, v220, v220 quad_perm:[1,0,3,2] row_mask:0xf bank_mask:0xf bound_ctrl:1
	v_add_f32_dpp v221, v221, v221 quad_perm:[1,0,3,2] row_mask:0xf bank_mask:0xf bound_ctrl:1
	v_pk_mul_f32 v[198:199], v[24:25], v[130:131]
	v_pk_mul_f32 v[206:207], v[16:17], v[130:131]
	v_add_f32_dpp v226, v226, v226 quad_perm:[2,3,0,1] row_mask:0xf bank_mask:0xf bound_ctrl:1
	v_add_f32_dpp v227, v227, v227 quad_perm:[2,3,0,1] row_mask:0xf bank_mask:0xf bound_ctrl:1
	v_add_f32_dpp v220, v220, v220 quad_perm:[2,3,0,1] row_mask:0xf bank_mask:0xf bound_ctrl:1
	v_add_f32_dpp v221, v221, v221 quad_perm:[2,3,0,1] row_mask:0xf bank_mask:0xf bound_ctrl:1
	v_pk_mul_f32 v[200:201], v[18:19], v[132:133]
	v_pk_mul_f32 v[208:209], v[10:11], v[132:133]
	v_add_f32_dpp v226, v226, v226 row_half_mirror row_mask:0xf bank_mask:0xf bound_ctrl:1
	v_add_f32_dpp v227, v227, v227 row_half_mirror row_mask:0xf bank_mask:0xf bound_ctrl:1
	v_add_f32_dpp v220, v220, v220 row_half_mirror row_mask:0xf bank_mask:0xf bound_ctrl:1
	v_add_f32_dpp v221, v221, v221 row_half_mirror row_mask:0xf bank_mask:0xf bound_ctrl:1
	v_pk_mul_f32 v[202:203], v[20:21], v[134:135]
	v_pk_mul_f32 v[210:211], v[12:13], v[134:135]
	v_pk_fma_f32 v[196:197], v[168:169], v[152:153], v[196:197] op_sel_hi:[0,1,1]
	v_pk_fma_f32 v[204:205], v[168:169], v[152:153], v[204:205] op_sel:[1,0,0] op_sel_hi:[1,1,1]
	v_pk_fma_f32 v[198:199], v[168:169], v[154:155], v[198:199] op_sel_hi:[0,1,1]
	v_pk_fma_f32 v[206:207], v[168:169], v[154:155], v[206:207] op_sel:[1,0,0] op_sel_hi:[1,1,1]
	v_pk_fma_f32 v[200:201], v[168:169], v[156:157], v[200:201] op_sel_hi:[0,1,1]
	v_pk_fma_f32 v[208:209], v[168:169], v[156:157], v[208:209] op_sel:[1,0,0] op_sel_hi:[1,1,1]
	v_pk_fma_f32 v[202:203], v[168:169], v[158:159], v[202:203] op_sel_hi:[0,1,1]
	v_pk_fma_f32 v[210:211], v[168:169], v[158:159], v[210:211] op_sel:[1,0,0] op_sel_hi:[1,1,1]
	ds_write_b64 v70, v[226:227] offset:128
	v_pk_fma_f32 v[22:23], v[220:221], v[144:145], v[196:197] op_sel_hi:[0,1,1] neg_lo:[1,0,0] neg_hi:[1,0,0]
	v_pk_fma_f32 v[14:15], v[220:221], v[144:145], v[204:205] op_sel:[1,0,0] op_sel_hi:[1,1,1] neg_lo:[1,0,0] neg_hi:[1,0,0]
	v_pk_fma_f32 v[24:25], v[220:221], v[146:147], v[198:199] op_sel_hi:[0,1,1] neg_lo:[1,0,0] neg_hi:[1,0,0]
	v_pk_fma_f32 v[16:17], v[220:221], v[146:147], v[206:207] op_sel:[1,0,0] op_sel_hi:[1,1,1] neg_lo:[1,0,0] neg_hi:[1,0,0]
	v_pk_fma_f32 v[18:19], v[220:221], v[148:149], v[200:201] op_sel_hi:[0,1,1] neg_lo:[1,0,0] neg_hi:[1,0,0]
	v_pk_fma_f32 v[10:11], v[220:221], v[148:149], v[208:209] op_sel:[1,0,0] op_sel_hi:[1,1,1] neg_lo:[1,0,0] neg_hi:[1,0,0]
	v_pk_fma_f32 v[20:21], v[220:221], v[150:151], v[202:203] op_sel_hi:[0,1,1] neg_lo:[1,0,0] neg_hi:[1,0,0]
	v_pk_fma_f32 v[12:13], v[220:221], v[150:151], v[210:211] op_sel:[1,0,0] op_sel_hi:[1,1,1] neg_lo:[1,0,0] neg_hi:[1,0,0]
	v_pk_mul_f32 v[222:223], v[22:23], v[160:161]
	v_pk_mul_f32 v[224:225], v[14:15], v[160:161]
	v_pk_fma_f32 v[222:223], v[24:25], v[162:163], v[222:223]
	v_pk_fma_f32 v[224:225], v[16:17], v[162:163], v[224:225]
	v_pk_fma_f32 v[222:223], v[18:19], v[164:165], v[222:223]
	v_pk_fma_f32 v[224:225], v[10:11], v[164:165], v[224:225]
	v_pk_fma_f32 v[222:223], v[20:21], v[166:167], v[222:223]
	v_pk_fma_f32 v[224:225], v[12:13], v[166:167], v[224:225]
	s_waitcnt lgkmcnt(0)
; __device__ __forceinline__ void scan_rows(f32x2 (&X)[8], const ScanOps& o, const f32x4 (&b)[2], const f32x4 (&kd)[2], const f32x4 (&r)[2], const bool use_v, float& yA, float& yB) {
;     f32x2 aA = X[0] * o.kk[0].xy, aB = X[4] * o.kk[0].xy;
;     aA += X[1] * o.kk[0].zw; aB += X[5] * o.kk[0].zw;
;     aA += X[2] * o.kk[1].xy; aB += X[6] * o.kk[1].xy;
;     aA += X[3] * o.kk[1].zw; aB += X[7] * o.kk[1].zw;
;     const float saA = sum8(aA.x + aA.y), saB = sum8(aB.x + aB.y);
;     const f32x2 nA = (f32x2){-saA, -saA}, nB = (f32x2){-saB, -saB}, vA = (f32x2){o.v.x, o.v.x}, vB = (f32x2){o.v.y, o.v.y};
;     f32x2 tA, tB, accA, accB;
;     tA = X[0] * o.w[0].xy; tA += nA * b[0].xy; if (use_v) tA += vA * kd[0].xy; X[0] = tA; accA = tA * r[0].xy;
;     tB = X[4] * o.w[0].xy; tB += nB * b[0].xy; if (use_v) tB += vB * kd[0].xy; X[4] = tB; accB = tB * r[0].xy;
;     tA = X[1] * o.w[0].zw; tA += nA * b[0].zw; if (use_v) tA += vA * kd[0].zw; X[1] = tA; accA += tA * r[0].zw;
;     tB = X[5] * o.w[0].zw; tB += nB * b[0].zw; if (use_v) tB += vB * kd[0].zw; X[5] = tB; accB += tB * r[0].zw;
;     tA = X[2] * o.w[1].xy; tA += nA * b[1].xy; if (use_v) tA += vA * kd[1].xy; X[2] = tA; accA += tA * r[1].xy;
;     tB = X[6] * o.w[1].xy; tB += nB * b[1].xy; if (use_v) tB += vB * kd[1].xy; X[6] = tB; accB += tB * r[1].xy;
;     tA = X[3] * o.w[1].zw; tA += nA * b[1].zw; if (use_v) tA += vA * kd[1].zw; X[3] = tA; accA += tA * r[1].zw;
;     tB = X[7] * o.w[1].zw; tB += nB * b[1].zw; if (use_v) tB += vB * kd[1].zw; X[7] = tB; accB += tB * r[1].zw;
;     yA = sum8(accA.x + accA.y); yB = sum8(accB.x + accB.y);
; __device__ void phase_scan(int c, const bf16_t* PROJ, const float* k_k, const bf16_t* Wd, const bf16_t* Bd, const float* k_a, bf16_t* Y, bf16_t* Q, float* FS, float* sm) {
;     ...
;                 for (int i = 0; i < 16; i += 2) {
;                     float yA = 0.f, yB = 0.f;
;                     scan_ld(ob, obv, i + 1, B);
;                     if (roleP) A.v = (f32x2){0.f, 0.f};
;                     scan_step1(X, A, ob + i * 64, yA, yB);
;                     *(f32x2*)(obw + i * 16 + 2 * vp) = (f32x2){yA, yB};
;                     if (i + 2 < 16) scan_ld(ob, obv, i + 2, A);
;                     if (roleP) B.v = (f32x2){0.f, 0.f};
;                     scan_step1(X, B, ob + (i + 1) * 64, yA, yB);
;                     *(f32x2*)(obw + (i + 1) * 16 + 2 * vp) = (f32x2){yA, yB};
	ds_read_b128 v[128:131], v84 offset:1280
	ds_read_b128 v[132:135], v84 offset:1296
	ds_read_b128 v[136:139], v84 offset:5376
	ds_read_b128 v[140:143], v84 offset:5392
	ds_read_b128 v[144:147], v84 offset:9472
	ds_read_b128 v[148:151], v84 offset:9488
	ds_read_b128 v[152:155], v84 offset:13568
	ds_read_b128 v[156:159], v84 offset:13584
	ds_read_b128 v[160:163], v84 offset:17664
	ds_read_b128 v[164:167], v84 offset:17680
	ds_read_b64 v[168:169], v85 offset:21760
	v_cndmask_b32_e64 v126, v126, 0, s[8:9]
	v_cndmask_b32_e64 v127, v127, 0, s[8:9]
	v_pk_mul_f32 v[212:213], v[22:23], v[94:95]
	v_pk_mul_f32 v[216:217], v[14:15], v[94:95]
	v_pk_mul_f32 v[214:215], v[18:19], v[98:99]
	v_pk_mul_f32 v[218:219], v[10:11], v[98:99]
	v_pk_fma_f32 v[212:213], v[24:25], v[96:97], v[212:213]
	v_pk_fma_f32 v[216:217], v[16:17], v[96:97], v[216:217]
	v_pk_fma_f32 v[214:215], v[20:21], v[100:101], v[214:215]
	v_pk_fma_f32 v[218:219], v[12:13], v[100:101], v[218:219]
	v_add_f32_e32 v226, v222, v223
	v_add_f32_e32 v227, v224, v225
	v_pk_add_f32 v[212:213], v[212:213], v[214:215]
	v_pk_add_f32 v[216:217], v[216:217], v[218:219]
	v_pk_mul_f32 v[196:197], v[22:23], v[86:87]
	v_pk_mul_f32 v[204:205], v[14:15], v[86:87]
	v_add_f32_e32 v220, v212, v213
	v_add_f32_e32 v221, v216, v217
	v_add_f32_dpp v226, v226, v226 quad_perm:[1,0,3,2] row_mask:0xf bank_mask:0xf bound_ctrl:1
	v_add_f32_dpp v227, v227, v227 quad_perm:[1,0,3,2] row_mask:0xf bank_mask:0xf bound_ctrl:1
	v_add_f32_dpp v220, v220, v220 quad_perm:[1,0,3,2] row_mask:0xf bank_mask:0xf bound_ctrl:1
	v_add_f32_dpp v221, v221, v221 quad_perm:[1,0,3,2] row_mask:0xf bank_mask:0xf bound_ctrl:1
	v_pk_mul_f32 v[198:199], v[24:25], v[88:89]
	v_pk_mul_f32 v[206:207], v[16:17], v[88:89]
	v_add_f32_dpp v226, v226, v226 quad_perm:[2,3,0,1] row_mask:0xf bank_mask:0xf bound_ctrl:1
	v_add_f32_dpp v227, v227, v227 quad_perm:[2,3,0,1] row_mask:0xf bank_mask:0xf bound_ctrl:1
	v_add_f32_dpp v220, v220, v220 quad_perm:[2,3,0,1] row_mask:0xf bank_mask:0xf bound_ctrl:1
	v_add_f32_dpp v221, v221, v221 quad_perm:[2,3,0,1] row_mask:0xf bank_mask:0xf bound_ctrl:1
	v_pk_mul_f32 v[200:201], v[18:19], v[90:91]
	v_pk_mul_f32 v[208:209], v[10:11], v[90:91]
	v_add_f32_dpp v226, v226, v226 row_half_mirror row_mask:0xf bank_mask:0xf bound_ctrl:1
	v_add_f32_dpp v227, v227, v227 row_half_mirror row_mask:0xf bank_mask:0xf bound_ctrl:1
	v_add_f32_dpp v220, v220, v220 row_half_mirror row_mask:0xf bank_mask:0xf bound_ctrl:1
	v_add_f32_dpp v221, v221, v221 row_half_mirror row_mask:0xf bank_mask:0xf bound_ctrl:1
	v_pk_mul_f32 v[202:203], v[20:21], v[92:93]
	v_pk_mul_f32 v[210:211], v[12:13], v[92:93]
	v_pk_fma_f32 v[196:197], v[126:127], v[110:111], v[196:197] op_sel_hi:[0,1,1]
	v_pk_fma_f32 v[204:205], v[126:127], v[110:111], v[204:205] op_sel:[1,0,0] op_sel_hi:[1,1,1]
	v_pk_fma_f32 v[198:199], v[126:127], v[112:113], v[198:199] op_sel_hi:[0,1,1]
	v_pk_fma_f32 v[206:207], v[126:127], v[112:113], v[206:207] op_sel:[1,0,0] op_sel_hi:[1,1,1]
	v_pk_fma_f32 v[200:201], v[126:127], v[114:115], v[200:201] op_sel_hi:[0,1,1]
	v_pk_fma_f32 v[208:209], v[126:127], v[114:115], v[208:209] op_sel:[1,0,0] op_sel_hi:[1,1,1]
	v_pk_fma_f32 v[202:203], v[126:127], v[116:117], v[202:203] op_sel_hi:[0,1,1]
	v_pk_fma_f32 v[210:211], v[126:127], v[116:117], v[210:211] op_sel:[1,0,0] op_sel_hi:[1,1,1]
	ds_write_b64 v70, v[226:227] offset:192
	v_pk_fma_f32 v[22:23], v[220:221], v[102:103], v[196:197] op_sel_hi:[0,1,1] neg_lo:[1,0,0] neg_hi:[1,0,0]
	v_pk_fma_f32 v[14:15], v[220:221], v[102:103], v[204:205] op_sel:[1,0,0] op_sel_hi:[1,1,1] neg_lo:[1,0,0] neg_hi:[1,0,0]
	v_pk_fma_f32 v[24:25], v[220:221], v[104:105], v[198:199] op_sel_hi:[0,1,1] neg_lo:[1,0,0] neg_hi:[1,0,0]
	v_pk_fma_f32 v[16:17], v[220:221], v[104:105], v[206:207] op_sel:[1,0,0] op_sel_hi:[1,1,1] neg_lo:[1,0,0] neg_hi:[1,0,0]
	v_pk_fma_f32 v[18:19], v[220:221], v[106:107], v[200:201] op_sel_hi:[0,1,1] neg_lo:[1,0,0] neg_hi:[1,0,0]
	v_pk_fma_f32 v[10:11], v[220:221], v[106:107], v[208:209] op_sel:[1,0,0] op_sel_hi:[1,1,1] neg_lo:[1,0,0] neg_hi:[1,0,0]
	v_pk_fma_f32 v[20:21], v[220:221], v[108:109], v[202:203] op_sel_hi:[0,1,1] neg_lo:[1,0,0] neg_hi:[1,0,0]
	v_pk_fma_f32 v[12:13], v[220:221], v[108:109], v[210:211] op_sel:[1,0,0] op_sel_hi:[1,1,1] neg_lo:[1,0,0] neg_hi:[1,0,0]
	v_pk_mul_f32 v[222:223], v[22:23], v[118:119]
	v_pk_mul_f32 v[224:225], v[14:15], v[118:119]
	v_pk_fma_f32 v[222:223], v[24:25], v[120:121], v[222:223]
	v_pk_fma_f32 v[224:225], v[16:17], v[120:121], v[224:225]
	v_pk_fma_f32 v[222:223], v[18:19], v[122:123], v[222:223]
	v_pk_fma_f32 v[224:225], v[10:11], v[122:123], v[224:225]
	v_pk_fma_f32 v[222:223], v[20:21], v[124:125], v[222:223]
	v_pk_fma_f32 v[224:225], v[12:13], v[124:125], v[224:225]
	s_waitcnt lgkmcnt(0)
; __device__ __forceinline__ void scan_rows(f32x2 (&X)[8], const ScanOps& o, const f32x4 (&b)[2], const f32x4 (&kd)[2], const f32x4 (&r)[2], const bool use_v, float& yA, float& yB) {
;     f32x2 aA = X[0] * o.kk[0].xy, aB = X[4] * o.kk[0].xy;
;     aA += X[1] * o.kk[0].zw; aB += X[5] * o.kk[0].zw;
;     aA += X[2] * o.kk[1].xy; aB += X[6] * o.kk[1].xy;
;     aA += X[3] * o.kk[1].zw; aB += X[7] * o.kk[1].zw;
;     const float saA = sum8(aA.x + aA.y), saB = sum8(aB.x + aB.y);
;     const f32x2 nA = (f32x2){-saA, -saA}, nB = (f32x2){-saB, -saB}, vA = (f32x2){o.v.x, o.v.x}, vB = (f32x2){o.v.y, o.v.y};
;     f32x2 tA, tB, accA, accB;
;     tA = X[0] * o.w[0].xy; tA += nA * b[0].xy; if (use_v) tA += vA * kd[0].xy; X[0] = tA; accA = tA * r[0].xy;
;     tB = X[4] * o.w[0].xy; tB += nB * b[0].xy; if (use_v) tB += vB * kd[0].xy; X[4] = tB; accB = tB * r[0].xy;
;     tA = X[1] * o.w[0].zw; tA += nA * b[0].zw; if (use_v) tA += vA * kd[0].zw; X[1] = tA; accA += tA * r[0].zw;
;     tB = X[5] * o.w[0].zw; tB += nB * b[0].zw; if (use_v) tB += vB * kd[0].zw; X[5] = tB; accB += tB * r[0].zw;
;     tA = X[2] * o.w[1].xy; tA += nA * b[1].xy; if (use_v) tA += vA * kd[1].xy; X[2] = tA; accA += tA * r[1].xy;
;     tB = X[6] * o.w[1].xy; tB += nB * b[1].xy; if (use_v) tB += vB * kd[1].xy; X[6] = tB; accB += tB * r[1].xy;
;     tA = X[3] * o.w[1].zw; tA += nA * b[1].zw; if (use_v) tA += vA * kd[1].zw; X[3] = tA; accA += tA * r[1].zw;
;     tB = X[7] * o.w[1].zw; tB += nB * b[1].zw; if (use_v) tB += vB * kd[1].zw; X[7] = tB; accB += tB * r[1].zw;
;     yA = sum8(accA.x + accA.y); yB = sum8(accB.x + accB.y);
; __device__ void phase_scan(int c, const bf16_t* PROJ, const float* k_k, const bf16_t* Wd, const bf16_t* Bd, const float* k_a, bf16_t* Y, bf16_t* Q, float* FS, float* sm) {
;     ...
;                 for (int i = 0; i < 16; i += 2) {
;                     float yA = 0.f, yB = 0.f;
;                     scan_ld(ob, obv, i + 1, B);
;                     if (roleP) A.v = (f32x2){0.f, 0.f};
;                     scan_step1(X, A, ob + i * 64, yA, yB);
;                     *(f32x2*)(obw + i * 16 + 2 * vp) = (f32x2){yA, yB};
;                     if (i + 2 < 16) scan_ld(ob, obv, i + 2, A);
;                     if (roleP) B.v = (f32x2){0.f, 0.f};
;                     scan_step1(X, B, ob + (i + 1) * 64, yA, yB);
;                     *(f32x2*)(obw + (i + 1) * 16 + 2 * vp) = (f32x2){yA, yB};
	ds_read_b128 v[86:89], v84 offset:1536
	ds_read_b128 v[90:93], v84 offset:1552
	ds_read_b128 v[94:97], v84 offset:5632
	ds_read_b128 v[98:101], v84 offset:5648
	ds_read_b128 v[102:105], v84 offset:9728
	ds_read_b128 v[106:109], v84 offset:9744
	ds_read_b128 v[110:113], v84 offset:13824
	ds_read_b128 v[114:117], v84 offset:13840
	ds_read_b128 v[118:121], v84 offset:17920
	ds_read_b128 v[122:125], v84 offset:17936
	ds_read_b64 v[126:127], v85 offset:22016
	v_cndmask_b32_e64 v168, v168, 0, s[8:9]
	v_cndmask_b32_e64 v169, v169, 0, s[8:9]
	v_pk_mul_f32 v[212:213], v[22:23], v[136:137]
	v_pk_mul_f32 v[216:217], v[14:15], v[136:137]
	v_pk_mul_f32 v[214:215], v[18:19], v[140:141]
	v_pk_mul_f32 v[218:219], v[10:11], v[140:141]
	v_pk_fma_f32 v[212:213], v[24:25], v[138:139], v[212:213]
	v_pk_fma_f32 v[216:217], v[16:17], v[138:139], v[216:217]
	v_pk_fma_f32 v[214:215], v[20:21], v[142:143], v[214:215]
	v_pk_fma_f32 v[218:219], v[12:13], v[142:143], v[218:219]
	v_add_f32_e32 v226, v222, v223
	v_add_f32_e32 v227, v224, v225
	v_pk_add_f32 v[212:213], v[212:213], v[214:215]
	v_pk_add_f32 v[216:217], v[216:217], v[218:219]
	v_pk_mul_f32 v[196:197], v[22:23], v[128:129]
	v_pk_mul_f32 v[204:205], v[14:15], v[128:129]
	v_add_f32_e32 v220, v212, v213
	v_add_f32_e32 v221, v216, v217
	v_add_f32_dpp v226, v226, v226 quad_perm:[1,0,3,2] row_mask:0xf bank_mask:0xf bound_ctrl:1
	v_add_f32_dpp v227, v227, v227 quad_perm:[1,0,3,2] row_mask:0xf bank_mask:0xf bound_ctrl:1
	v_add_f32_dpp v220, v220, v220 quad_perm:[1,0,3,2] row_mask:0xf bank_mask:0xf bound_ctrl:1
	v_add_f32_dpp v221, v221, v221 quad_perm:[1,0,3,2] row_mask:0xf bank_mask:0xf bound_ctrl:1
	v_pk_mul_f32 v[198:199], v[24:25], v[130:131]
	v_pk_mul_f32 v[206:207], v[16:17], v[130:131]
	v_add_f32_dpp v226, v226, v226 quad_perm:[2,3,0,1] row_mask:0xf bank_mask:0xf bound_ctrl:1
	v_add_f32_dpp v227, v227, v227 quad_perm:[2,3,0,1] row_mask:0xf bank_mask:0xf bound_ctrl:1
	v_add_f32_dpp v220, v220, v220 quad_perm:[2,3,0,1] row_mask:0xf bank_mask:0xf bound_ctrl:1
	v_add_f32_dpp v221, v221, v221 quad_perm:[2,3,0,1] row_mask:0xf bank_mask:0xf bound_ctrl:1
	v_pk_mul_f32 v[200:201], v[18:19], v[132:133]
	v_pk_mul_f32 v[208:209], v[10:11], v[132:133]
	v_add_f32_dpp v226, v226, v226 row_half_mirror row_mask:0xf bank_mask:0xf bound_ctrl:1
	v_add_f32_dpp v227, v227, v227 row_half_mirror row_mask:0xf bank_mask:0xf bound_ctrl:1
	v_add_f32_dpp v220, v220, v220 row_half_mirror row_mask:0xf bank_mask:0xf bound_ctrl:1
	v_add_f32_dpp v221, v221, v221 row_half_mirror row_mask:0xf bank_mask:0xf bound_ctrl:1
	v_pk_mul_f32 v[202:203], v[20:21], v[134:135]
	v_pk_mul_f32 v[210:211], v[12:13], v[134:135]
	v_pk_fma_f32 v[196:197], v[168:169], v[152:153], v[196:197] op_sel_hi:[0,1,1]
	v_pk_fma_f32 v[204:205], v[168:169], v[152:153], v[204:205] op_sel:[1,0,0] op_sel_hi:[1,1,1]
	v_pk_fma_f32 v[198:199], v[168:169], v[154:155], v[198:199] op_sel_hi:[0,1,1]
	v_pk_fma_f32 v[206:207], v[168:169], v[154:155], v[206:207] op_sel:[1,0,0] op_sel_hi:[1,1,1]
	v_pk_fma_f32 v[200:201], v[168:169], v[156:157], v[200:201] op_sel_hi:[0,1,1]
	v_pk_fma_f32 v[208:209], v[168:169], v[156:157], v[208:209] op_sel:[1,0,0] op_sel_hi:[1,1,1]
	v_pk_fma_f32 v[202:203], v[168:169], v[158:159], v[202:203] op_sel_hi:[0,1,1]
	v_pk_fma_f32 v[210:211], v[168:169], v[158:159], v[210:211] op_sel:[1,0,0] op_sel_hi:[1,1,1]
	ds_write_b64 v70, v[226:227] offset:256
	v_pk_fma_f32 v[22:23], v[220:221], v[144:145], v[196:197] op_sel_hi:[0,1,1] neg_lo:[1,0,0] neg_hi:[1,0,0]
	v_pk_fma_f32 v[14:15], v[220:221], v[144:145], v[204:205] op_sel:[1,0,0] op_sel_hi:[1,1,1] neg_lo:[1,0,0] neg_hi:[1,0,0]
	v_pk_fma_f32 v[24:25], v[220:221], v[146:147], v[198:199] op_sel_hi:[0,1,1] neg_lo:[1,0,0] neg_hi:[1,0,0]
	v_pk_fma_f32 v[16:17], v[220:221], v[146:147], v[206:207] op_sel:[1,0,0] op_sel_hi:[1,1,1] neg_lo:[1,0,0] neg_hi:[1,0,0]
	v_pk_fma_f32 v[18:19], v[220:221], v[148:149], v[200:201] op_sel_hi:[0,1,1] neg_lo:[1,0,0] neg_hi:[1,0,0]
	v_pk_fma_f32 v[10:11], v[220:221], v[148:149], v[208:209] op_sel:[1,0,0] op_sel_hi:[1,1,1] neg_lo:[1,0,0] neg_hi:[1,0,0]
	v_pk_fma_f32 v[20:21], v[220:221], v[150:151], v[202:203] op_sel_hi:[0,1,1] neg_lo:[1,0,0] neg_hi:[1,0,0]
	v_pk_fma_f32 v[12:13], v[220:221], v[150:151], v[210:211] op_sel:[1,0,0] op_sel_hi:[1,1,1] neg_lo:[1,0,0] neg_hi:[1,0,0]
	v_pk_mul_f32 v[222:223], v[22:23], v[160:161]
	v_pk_mul_f32 v[224:225], v[14:15], v[160:161]
	v_pk_fma_f32 v[222:223], v[24:25], v[162:163], v[222:223]
	v_pk_fma_f32 v[224:225], v[16:17], v[162:163], v[224:225]
	v_pk_fma_f32 v[222:223], v[18:19], v[164:165], v[222:223]
	v_pk_fma_f32 v[224:225], v[10:11], v[164:165], v[224:225]
	v_pk_fma_f32 v[222:223], v[20:21], v[166:167], v[222:223]
	v_pk_fma_f32 v[224:225], v[12:13], v[166:167], v[224:225]
	s_waitcnt lgkmcnt(0)
; __device__ __forceinline__ void scan_rows(f32x2 (&X)[8], const ScanOps& o, const f32x4 (&b)[2], const f32x4 (&kd)[2], const f32x4 (&r)[2], const bool use_v, float& yA, float& yB) {
;     f32x2 aA = X[0] * o.kk[0].xy, aB = X[4] * o.kk[0].xy;
;     aA += X[1] * o.kk[0].zw; aB += X[5] * o.kk[0].zw;
;     aA += X[2] * o.kk[1].xy; aB += X[6] * o.kk[1].xy;
;     aA += X[3] * o.kk[1].zw; aB += X[7] * o.kk[1].zw;
;     const float saA = sum8(aA.x + aA.y), saB = sum8(aB.x + aB.y);
;     const f32x2 nA = (f32x2){-saA, -saA}, nB = (f32x2){-saB, -saB}, vA = (f32x2){o.v.x, o.v.x}, vB = (f32x2){o.v.y, o.v.y};
;     f32x2 tA, tB, accA, accB;
;     tA = X[0] * o.w[0].xy; tA += nA * b[0].xy; if (use_v) tA += vA * kd[0].xy; X[0] = tA; accA = tA * r[0].xy;
;     tB = X[4] * o.w[0].xy; tB += nB * b[0].xy; if (use_v) tB += vB * kd[0].xy; X[4] = tB; accB = tB * r[0].xy;
;     tA = X[1] * o.w[0].zw; tA += nA * b[0].zw; if (use_v) tA += vA * kd[0].zw; X[1] = tA; accA += tA * r[0].zw;
;     tB = X[5] * o.w[0].zw; tB += nB * b[0].zw; if (use_v) tB += vB * kd[0].zw; X[5] = tB; accB += tB * r[0].zw;
;     tA = X[2] * o.w[1].xy; tA += nA * b[1].xy; if (use_v) tA += vA * kd[1].xy; X[2] = tA; accA += tA * r[1].xy;
;     tB = X[6] * o.w[1].xy; tB += nB * b[1].xy; if (use_v) tB += vB * kd[1].xy; X[6] = tB; accB += tB * r[1].xy;
;     tA = X[3] * o.w[1].zw; tA += nA * b[1].zw; if (use_v) tA += vA * kd[1].zw; X[3] = tA; accA += tA * r[1].zw;
;     tB = X[7] * o.w[1].zw; tB += nB * b[1].zw; if (use_v) tB += vB * kd[1].zw; X[7] = tB; accB += tB * r[1].zw;
;     yA = sum8(accA.x + accA.y); yB = sum8(accB.x + accB.y);
; __device__ void phase_scan(int c, const bf16_t* PROJ, const float* k_k, const bf16_t* Wd, const bf16_t* Bd, const float* k_a, bf16_t* Y, bf16_t* Q, float* FS, float* sm) {
;     ...
;                 for (int i = 0; i < 16; i += 2) {
;                     float yA = 0.f, yB = 0.f;
;                     scan_ld(ob, obv, i + 1, B);
;                     if (roleP) A.v = (f32x2){0.f, 0.f};
;                     scan_step1(X, A, ob + i * 64, yA, yB);
;                     *(f32x2*)(obw + i * 16 + 2 * vp) = (f32x2){yA, yB};
;                     if (i + 2 < 16) scan_ld(ob, obv, i + 2, A);
;                     if (roleP) B.v = (f32x2){0.f, 0.f};
;                     scan_step1(X, B, ob + (i + 1) * 64, yA, yB);
;                     *(f32x2*)(obw + (i + 1) * 16 + 2 * vp) = (f32x2){yA, yB};
	ds_read_b128 v[128:131], v84 offset:1792
	ds_read_b128 v[132:135], v84 offset:1808
	ds_read_b128 v[136:139], v84 offset:5888
	ds_read_b128 v[140:143], v84 offset:5904
	ds_read_b128 v[144:147], v84 offset:9984
	ds_read_b128 v[148:151], v84 offset:10000
	ds_read_b128 v[152:155], v84 offset:14080
	ds_read_b128 v[156:159], v84 offset:14096
	ds_read_b128 v[160:163], v84 offset:18176
	ds_read_b128 v[164:167], v84 offset:18192
	ds_read_b64 v[168:169], v85 offset:22272
	v_cndmask_b32_e64 v126, v126, 0, s[8:9]
	v_cndmask_b32_e64 v127, v127, 0, s[8:9]
	v_pk_mul_f32 v[212:213], v[22:23], v[94:95]
	v_pk_mul_f32 v[216:217], v[14:15], v[94:95]
	v_pk_mul_f32 v[214:215], v[18:19], v[98:99]
	v_pk_mul_f32 v[218:219], v[10:11], v[98:99]
	v_pk_fma_f32 v[212:213], v[24:25], v[96:97], v[212:213]
	v_pk_fma_f32 v[216:217], v[16:17], v[96:97], v[216:217]
	v_pk_fma_f32 v[214:215], v[20:21], v[100:101], v[214:215]
	v_pk_fma_f32 v[218:219], v[12:13], v[100:101], v[218:219]
	v_add_f32_e32 v226, v222, v223
	v_add_f32_e32 v227, v224, v225
	v_pk_add_f32 v[212:213], v[212:213], v[214:215]
	v_pk_add_f32 v[216:217], v[216:217], v[218:219]
	v_pk_mul_f32 v[196:197], v[22:23], v[86:87]
	v_pk_mul_f32 v[204:205], v[14:15], v[86:87]
	v_add_f32_e32 v220, v212, v213
	v_add_f32_e32 v221, v216, v217
	v_add_f32_dpp v226, v226, v226 quad_perm:[1,0,3,2] row_mask:0xf bank_mask:0xf bound_ctrl:1
	v_add_f32_dpp v227, v227, v227 quad_perm:[1,0,3,2] row_mask:0xf bank_mask:0xf bound_ctrl:1
	v_add_f32_dpp v220, v220, v220 quad_perm:[1,0,3,2] row_mask:0xf bank_mask:0xf bound_ctrl:1
	v_add_f32_dpp v221, v221, v221 quad_perm:[1,0,3,2] row_mask:0xf bank_mask:0xf bound_ctrl:1
	v_pk_mul_f32 v[198:199], v[24:25], v[88:89]
	v_pk_mul_f32 v[206:207], v[16:17], v[88:89]
	v_add_f32_dpp v226, v226, v226 quad_perm:[2,3,0,1] row_mask:0xf bank_mask:0xf bound_ctrl:1
	v_add_f32_dpp v227, v227, v227 quad_perm:[2,3,0,1] row_mask:0xf bank_mask:0xf bound_ctrl:1
	v_add_f32_dpp v220, v220, v220 quad_perm:[2,3,0,1] row_mask:0xf bank_mask:0xf bound_ctrl:1
	v_add_f32_dpp v221, v221, v221 quad_perm:[2,3,0,1] row_mask:0xf bank_mask:0xf bound_ctrl:1
	v_pk_mul_f32 v[200:201], v[18:19], v[90:91]
	v_pk_mul_f32 v[208:209], v[10:11], v[90:91]
	v_add_f32_dpp v226, v226, v226 row_half_mirror row_mask:0xf bank_mask:0xf bound_ctrl:1
	v_add_f32_dpp v227, v227, v227 row_half_mirror row_mask:0xf bank_mask:0xf bound_ctrl:1
	v_add_f32_dpp v220, v220, v220 row_half_mirror row_mask:0xf bank_mask:0xf bound_ctrl:1
	v_add_f32_dpp v221, v221, v221 row_half_mirror row_mask:0xf bank_mask:0xf bound_ctrl:1
	v_pk_mul_f32 v[202:203], v[20:21], v[92:93]
	v_pk_mul_f32 v[210:211], v[12:13], v[92:93]
	v_pk_fma_f32 v[196:197], v[126:127], v[110:111], v[196:197] op_sel_hi:[0,1,1]
	v_pk_fma_f32 v[204:205], v[126:127], v[110:111], v[204:205] op_sel:[1,0,0] op_sel_hi:[1,1,1]
	v_pk_fma_f32 v[198:199], v[126:127], v[112:113], v[198:199] op_sel_hi:[0,1,1]
	v_pk_fma_f32 v[206:207], v[126:127], v[112:113], v[206:207] op_sel:[1,0,0] op_sel_hi:[1,1,1]
	v_pk_fma_f32 v[200:201], v[126:127], v[114:115], v[200:201] op_sel_hi:[0,1,1]
	v_pk_fma_f32 v[208:209], v[126:127], v[114:115], v[208:209] op_sel:[1,0,0] op_sel_hi:[1,1,1]
	v_pk_fma_f32 v[202:203], v[126:127], v[116:117], v[202:203] op_sel_hi:[0,1,1]
	v_pk_fma_f32 v[210:211], v[126:127], v[116:117], v[210:211] op_sel:[1,0,0] op_sel_hi:[1,1,1]
	ds_write_b64 v70, v[226:227] offset:320
	v_pk_fma_f32 v[22:23], v[220:221], v[102:103], v[196:197] op_sel_hi:[0,1,1] neg_lo:[1,0,0] neg_hi:[1,0,0]
	v_pk_fma_f32 v[14:15], v[220:221], v[102:103], v[204:205] op_sel:[1,0,0] op_sel_hi:[1,1,1] neg_lo:[1,0,0] neg_hi:[1,0,0]
	v_pk_fma_f32 v[24:25], v[220:221], v[104:105], v[198:199] op_sel_hi:[0,1,1] neg_lo:[1,0,0] neg_hi:[1,0,0]
	v_pk_fma_f32 v[16:17], v[220:221], v[104:105], v[206:207] op_sel:[1,0,0] op_sel_hi:[1,1,1] neg_lo:[1,0,0] neg_hi:[1,0,0]
	v_pk_fma_f32 v[18:19], v[220:221], v[106:107], v[200:201] op_sel_hi:[0,1,1] neg_lo:[1,0,0] neg_hi:[1,0,0]
	v_pk_fma_f32 v[10:11], v[220:221], v[106:107], v[208:209] op_sel:[1,0,0] op_sel_hi:[1,1,1] neg_lo:[1,0,0] neg_hi:[1,0,0]
	v_pk_fma_f32 v[20:21], v[220:221], v[108:109], v[202:203] op_sel_hi:[0,1,1] neg_lo:[1,0,0] neg_hi:[1,0,0]
	v_pk_fma_f32 v[12:13], v[220:221], v[108:109], v[210:211] op_sel:[1,0,0] op_sel_hi:[1,1,1] neg_lo:[1,0,0] neg_hi:[1,0,0]
	v_pk_mul_f32 v[222:223], v[22:23], v[118:119]
	v_pk_mul_f32 v[224:225], v[14:15], v[118:119]
	v_pk_fma_f32 v[222:223], v[24:25], v[120:121], v[222:223]
	v_pk_fma_f32 v[224:225], v[16:17], v[120:121], v[224:225]
	v_pk_fma_f32 v[222:223], v[18:19], v[122:123], v[222:223]
	v_pk_fma_f32 v[224:225], v[10:11], v[122:123], v[224:225]
	v_pk_fma_f32 v[222:223], v[20:21], v[124:125], v[222:223]
	v_pk_fma_f32 v[224:225], v[12:13], v[124:125], v[224:225]
	s_waitcnt lgkmcnt(0)
; __device__ __forceinline__ void scan_rows(f32x2 (&X)[8], const ScanOps& o, const f32x4 (&b)[2], const f32x4 (&kd)[2], const f32x4 (&r)[2], const bool use_v, float& yA, float& yB) {
;     f32x2 aA = X[0] * o.kk[0].xy, aB = X[4] * o.kk[0].xy;
;     aA += X[1] * o.kk[0].zw; aB += X[5] * o.kk[0].zw;
;     aA += X[2] * o.kk[1].xy; aB += X[6] * o.kk[1].xy;
;     aA += X[3] * o.kk[1].zw; aB += X[7] * o.kk[1].zw;
;     const float saA = sum8(aA.x + aA.y), saB = sum8(aB.x + aB.y);
;     const f32x2 nA = (f32x2){-saA, -saA}, nB = (f32x2){-saB, -saB}, vA = (f32x2){o.v.x, o.v.x}, vB = (f32x2){o.v.y, o.v.y};
;     f32x2 tA, tB, accA, accB;
;     tA = X[0] * o.w[0].xy; tA += nA * b[0].xy; if (use_v) tA += vA * kd[0].xy; X[0] = tA; accA = tA * r[0].xy;
;     tB = X[4] * o.w[0].xy; tB += nB * b[0].xy; if (use_v) tB += vB * kd[0].xy; X[4] = tB; accB = tB * r[0].xy;
;     tA = X[1] * o.w[0].zw; tA += nA * b[0].zw; if (use_v) tA += vA * kd[0].zw; X[1] = tA; accA += tA * r[0].zw;
;     tB = X[5] * o.w[0].zw; tB += nB * b[0].zw; if (use_v) tB += vB * kd[0].zw; X[5] = tB; accB += tB * r[0].zw;
;     tA = X[2] * o.w[1].xy; tA += nA * b[1].xy; if (use_v) tA += vA * kd[1].xy; X[2] = tA; accA += tA * r[1].xy;
;     tB = X[6] * o.w[1].xy; tB += nB * b[1].xy; if (use_v) tB += vB * kd[1].xy; X[6] = tB; accB += tB * r[1].xy;
;     tA = X[3] * o.w[1].zw; tA += nA * b[1].zw; if (use_v) tA += vA * kd[1].zw; X[3] = tA; accA += tA * r[1].zw;
;     tB = X[7] * o.w[1].zw; tB += nB * b[1].zw; if (use_v) tB += vB * kd[1].zw; X[7] = tB; accB += tB * r[1].zw;
;     yA = sum8(accA.x + accA.y); yB = sum8(accB.x + accB.y);
; __device__ void phase_scan(int c, const bf16_t* PROJ, const float* k_k, const bf16_t* Wd, const bf16_t* Bd, const float* k_a, bf16_t* Y, bf16_t* Q, float* FS, float* sm) {
;     ...
;                 for (int i = 0; i < 16; i += 2) {
;                     float yA = 0.f, yB = 0.f;
;                     scan_ld(ob, obv, i + 1, B);
;                     if (roleP) A.v = (f32x2){0.f, 0.f};
;                     scan_step1(X, A, ob + i * 64, yA, yB);
;                     *(f32x2*)(obw + i * 16 + 2 * vp) = (f32x2){yA, yB};
;                     if (i + 2 < 16) scan_ld(ob, obv, i + 2, A);
;                     if (roleP) B.v = (f32x2){0.f, 0.f};
;                     scan_step1(X, B, ob + (i + 1) * 64, yA, yB);
;                     *(f32x2*)(obw + (i + 1) * 16 + 2 * vp) = (f32x2){yA, yB};
	ds_read_b128 v[86:89], v84 offset:2048
	ds_read_b128 v[90:93], v84 offset:2064
	ds_read_b128 v[94:97], v84 offset:6144
	ds_read_b128 v[98:101], v84 offset:6160
	ds_read_b128 v[102:105], v84 offset:10240
	ds_read_b128 v[106:109], v84 offset:10256
	ds_read_b128 v[110:113], v84 offset:14336
	ds_read_b128 v[114:117], v84 offset:14352
	ds_read_b128 v[118:121], v84 offset:18432
	ds_read_b128 v[122:125], v84 offset:18448
	ds_read_b64 v[126:127], v85 offset:22528
	v_cndmask_b32_e64 v168, v168, 0, s[8:9]
	v_cndmask_b32_e64 v169, v169, 0, s[8:9]
	v_pk_mul_f32 v[212:213], v[22:23], v[136:137]
	v_pk_mul_f32 v[216:217], v[14:15], v[136:137]
	v_pk_mul_f32 v[214:215], v[18:19], v[140:141]
	v_pk_mul_f32 v[218:219], v[10:11], v[140:141]
	v_pk_fma_f32 v[212:213], v[24:25], v[138:139], v[212:213]
	v_pk_fma_f32 v[216:217], v[16:17], v[138:139], v[216:217]
	v_pk_fma_f32 v[214:215], v[20:21], v[142:143], v[214:215]
	v_pk_fma_f32 v[218:219], v[12:13], v[142:143], v[218:219]
	v_add_f32_e32 v226, v222, v223
	v_add_f32_e32 v227, v224, v225
	v_pk_add_f32 v[212:213], v[212:213], v[214:215]
	v_pk_add_f32 v[216:217], v[216:217], v[218:219]
	v_pk_mul_f32 v[196:197], v[22:23], v[128:129]
	v_pk_mul_f32 v[204:205], v[14:15], v[128:129]
	v_add_f32_e32 v220, v212, v213
	v_add_f32_e32 v221, v216, v217
	v_add_f32_dpp v226, v226, v226 quad_perm:[1,0,3,2] row_mask:0xf bank_mask:0xf bound_ctrl:1
	v_add_f32_dpp v227, v227, v227 quad_perm:[1,0,3,2] row_mask:0xf bank_mask:0xf bound_ctrl:1
	v_add_f32_dpp v220, v220, v220 quad_perm:[1,0,3,2] row_mask:0xf bank_mask:0xf bound_ctrl:1
	v_add_f32_dpp v221, v221, v221 quad_perm:[1,0,3,2] row_mask:0xf bank_mask:0xf bound_ctrl:1
	v_pk_mul_f32 v[198:199], v[24:25], v[130:131]
	v_pk_mul_f32 v[206:207], v[16:17], v[130:131]
	v_add_f32_dpp v226, v226, v226 quad_perm:[2,3,0,1] row_mask:0xf bank_mask:0xf bound_ctrl:1
	v_add_f32_dpp v227, v227, v227 quad_perm:[2,3,0,1] row_mask:0xf bank_mask:0xf bound_ctrl:1
	v_add_f32_dpp v220, v220, v220 quad_perm:[2,3,0,1] row_mask:0xf bank_mask:0xf bound_ctrl:1
	v_add_f32_dpp v221, v221, v221 quad_perm:[2,3,0,1] row_mask:0xf bank_mask:0xf bound_ctrl:1
	v_pk_mul_f32 v[200:201], v[18:19], v[132:133]
	v_pk_mul_f32 v[208:209], v[10:11], v[132:133]
	v_add_f32_dpp v226, v226, v226 row_half_mirror row_mask:0xf bank_mask:0xf bound_ctrl:1
	v_add_f32_dpp v227, v227, v227 row_half_mirror row_mask:0xf bank_mask:0xf bound_ctrl:1
	v_add_f32_dpp v220, v220, v220 row_half_mirror row_mask:0xf bank_mask:0xf bound_ctrl:1
	v_add_f32_dpp v221, v221, v221 row_half_mirror row_mask:0xf bank_mask:0xf bound_ctrl:1
	v_pk_mul_f32 v[202:203], v[20:21], v[134:135]
	v_pk_mul_f32 v[210:211], v[12:13], v[134:135]
	v_pk_fma_f32 v[196:197], v[168:169], v[152:153], v[196:197] op_sel_hi:[0,1,1]
	v_pk_fma_f32 v[204:205], v[168:169], v[152:153], v[204:205] op_sel:[1,0,0] op_sel_hi:[1,1,1]
	v_pk_fma_f32 v[198:199], v[168:169], v[154:155], v[198:199] op_sel_hi:[0,1,1]
	v_pk_fma_f32 v[206:207], v[168:169], v[154:155], v[206:207] op_sel:[1,0,0] op_sel_hi:[1,1,1]
	v_pk_fma_f32 v[200:201], v[168:169], v[156:157], v[200:201] op_sel_hi:[0,1,1]
	v_pk_fma_f32 v[208:209], v[168:169], v[156:157], v[208:209] op_sel:[1,0,0] op_sel_hi:[1,1,1]
	v_pk_fma_f32 v[202:203], v[168:169], v[158:159], v[202:203] op_sel_hi:[0,1,1]
	v_pk_fma_f32 v[210:211], v[168:169], v[158:159], v[210:211] op_sel:[1,0,0] op_sel_hi:[1,1,1]
	ds_write_b64 v70, v[226:227] offset:384
	v_pk_fma_f32 v[22:23], v[220:221], v[144:145], v[196:197] op_sel_hi:[0,1,1] neg_lo:[1,0,0] neg_hi:[1,0,0]
	v_pk_fma_f32 v[14:15], v[220:221], v[144:145], v[204:205] op_sel:[1,0,0] op_sel_hi:[1,1,1] neg_lo:[1,0,0] neg_hi:[1,0,0]
	v_pk_fma_f32 v[24:25], v[220:221], v[146:147], v[198:199] op_sel_hi:[0,1,1] neg_lo:[1,0,0] neg_hi:[1,0,0]
	v_pk_fma_f32 v[16:17], v[220:221], v[146:147], v[206:207] op_sel:[1,0,0] op_sel_hi:[1,1,1] neg_lo:[1,0,0] neg_hi:[1,0,0]
	v_pk_fma_f32 v[18:19], v[220:221], v[148:149], v[200:201] op_sel_hi:[0,1,1] neg_lo:[1,0,0] neg_hi:[1,0,0]
	v_pk_fma_f32 v[10:11], v[220:221], v[148:149], v[208:209] op_sel:[1,0,0] op_sel_hi:[1,1,1] neg_lo:[1,0,0] neg_hi:[1,0,0]
	v_pk_fma_f32 v[20:21], v[220:221], v[150:151], v[202:203] op_sel_hi:[0,1,1] neg_lo:[1,0,0] neg_hi:[1,0,0]
	v_pk_fma_f32 v[12:13], v[220:221], v[150:151], v[210:211] op_sel:[1,0,0] op_sel_hi:[1,1,1] neg_lo:[1,0,0] neg_hi:[1,0,0]
	v_pk_mul_f32 v[222:223], v[22:23], v[160:161]
	v_pk_mul_f32 v[224:225], v[14:15], v[160:161]
	v_pk_fma_f32 v[222:223], v[24:25], v[162:163], v[222:223]
	v_pk_fma_f32 v[224:225], v[16:17], v[162:163], v[224:225]
	v_pk_fma_f32 v[222:223], v[18:19], v[164:165], v[222:223]
	v_pk_fma_f32 v[224:225], v[10:11], v[164:165], v[224:225]
	v_pk_fma_f32 v[222:223], v[20:21], v[166:167], v[222:223]
	v_pk_fma_f32 v[224:225], v[12:13], v[166:167], v[224:225]
	s_waitcnt lgkmcnt(0)
; __device__ __forceinline__ void scan_rows(f32x2 (&X)[8], const ScanOps& o, const f32x4 (&b)[2], const f32x4 (&kd)[2], const f32x4 (&r)[2], const bool use_v, float& yA, float& yB) {
;     f32x2 aA = X[0] * o.kk[0].xy, aB = X[4] * o.kk[0].xy;
;     aA += X[1] * o.kk[0].zw; aB += X[5] * o.kk[0].zw;
;     aA += X[2] * o.kk[1].xy; aB += X[6] * o.kk[1].xy;
;     aA += X[3] * o.kk[1].zw; aB += X[7] * o.kk[1].zw;
;     const float saA = sum8(aA.x + aA.y), saB = sum8(aB.x + aB.y);
;     const f32x2 nA = (f32x2){-saA, -saA}, nB = (f32x2){-saB, -saB}, vA = (f32x2){o.v.x, o.v.x}, vB = (f32x2){o.v.y, o.v.y};
;     f32x2 tA, tB, accA, accB;
;     tA = X[0] * o.w[0].xy; tA += nA * b[0].xy; if (use_v) tA += vA * kd[0].xy; X[0] = tA; accA = tA * r[0].xy;
;     tB = X[4] * o.w[0].xy; tB += nB * b[0].xy; if (use_v) tB += vB * kd[0].xy; X[4] = tB; accB = tB * r[0].xy;
;     tA = X[1] * o.w[0].zw; tA += nA * b[0].zw; if (use_v) tA += vA * kd[0].zw; X[1] = tA; accA += tA * r[0].zw;
;     tB = X[5] * o.w[0].zw; tB += nB * b[0].zw; if (use_v) tB += vB * kd[0].zw; X[5] = tB; accB += tB * r[0].zw;
;     tA = X[2] * o.w[1].xy; tA += nA * b[1].xy; if (use_v) tA += vA * kd[1].xy; X[2] = tA; accA += tA * r[1].xy;
;     tB = X[6] * o.w[1].xy; tB += nB * b[1].xy; if (use_v) tB += vB * kd[1].xy; X[6] = tB; accB += tB * r[1].xy;
;     tA = X[3] * o.w[1].zw; tA += nA * b[1].zw; if (use_v) tA += vA * kd[1].zw; X[3] = tA; accA += tA * r[1].zw;
;     tB = X[7] * o.w[1].zw; tB += nB * b[1].zw; if (use_v) tB += vB * kd[1].zw; X[7] = tB; accB += tB * r[1].zw;
;     yA = sum8(accA.x + accA.y); yB = sum8(accB.x + accB.y);
; __device__ void phase_scan(int c, const bf16_t* PROJ, const float* k_k, const bf16_t* Wd, const bf16_t* Bd, const float* k_a, bf16_t* Y, bf16_t* Q, float* FS, float* sm) {
;     ...
;                 for (int i = 0; i < 16; i += 2) {
;                     float yA = 0.f, yB = 0.f;
;                     scan_ld(ob, obv, i + 1, B);
;                     if (roleP) A.v = (f32x2){0.f, 0.f};
;                     scan_step1(X, A, ob + i * 64, yA, yB);
;                     *(f32x2*)(obw + i * 16 + 2 * vp) = (f32x2){yA, yB};
;                     if (i + 2 < 16) scan_ld(ob, obv, i + 2, A);
;                     if (roleP) B.v = (f32x2){0.f, 0.f};
;                     scan_step1(X, B, ob + (i + 1) * 64, yA, yB);
;                     *(f32x2*)(obw + (i + 1) * 16 + 2 * vp) = (f32x2){yA, yB};
	ds_read_b128 v[128:131], v84 offset:2304
	ds_read_b128 v[132:135], v84 offset:2320
	ds_read_b128 v[136:139], v84 offset:6400
	ds_read_b128 v[140:143], v84 offset:6416
	ds_read_b128 v[144:147], v84 offset:10496
	ds_read_b128 v[148:151], v84 offset:10512
	ds_read_b128 v[152:155], v84 offset:14592
	ds_read_b128 v[156:159], v84 offset:14608
	ds_read_b128 v[160:163], v84 offset:18688
	ds_read_b128 v[164:167], v84 offset:18704
	ds_read_b64 v[168:169], v85 offset:22784
	v_cndmask_b32_e64 v126, v126, 0, s[8:9]
	v_cndmask_b32_e64 v127, v127, 0, s[8:9]
	v_pk_mul_f32 v[212:213], v[22:23], v[94:95]
	v_pk_mul_f32 v[216:217], v[14:15], v[94:95]
	v_pk_mul_f32 v[214:215], v[18:19], v[98:99]
	v_pk_mul_f32 v[218:219], v[10:11], v[98:99]
	v_pk_fma_f32 v[212:213], v[24:25], v[96:97], v[212:213]
	v_pk_fma_f32 v[216:217], v[16:17], v[96:97], v[216:217]
	v_pk_fma_f32 v[214:215], v[20:21], v[100:101], v[214:215]
	v_pk_fma_f32 v[218:219], v[12:13], v[100:101], v[218:219]
	v_add_f32_e32 v226, v222, v223
	v_add_f32_e32 v227, v224, v225
	v_pk_add_f32 v[212:213], v[212:213], v[214:215]
	v_pk_add_f32 v[216:217], v[216:217], v[218:219]
	v_pk_mul_f32 v[196:197], v[22:23], v[86:87]
	v_pk_mul_f32 v[204:205], v[14:15], v[86:87]
	v_add_f32_e32 v220, v212, v213
	v_add_f32_e32 v221, v216, v217
	v_add_f32_dpp v226, v226, v226 quad_perm:[1,0,3,2] row_mask:0xf bank_mask:0xf bound_ctrl:1
	v_add_f32_dpp v227, v227, v227 quad_perm:[1,0,3,2] row_mask:0xf bank_mask:0xf bound_ctrl:1
	v_add_f32_dpp v220, v220, v220 quad_perm:[1,0,3,2] row_mask:0xf bank_mask:0xf bound_ctrl:1
	v_add_f32_dpp v221, v221, v221 quad_perm:[1,0,3,2] row_mask:0xf bank_mask:0xf bound_ctrl:1
	v_pk_mul_f32 v[198:199], v[24:25], v[88:89]
	v_pk_mul_f32 v[206:207], v[16:17], v[88:89]
	v_add_f32_dpp v226, v226, v226 quad_perm:[2,3,0,1] row_mask:0xf bank_mask:0xf bound_ctrl:1
	v_add_f32_dpp v227, v227, v227 quad_perm:[2,3,0,1] row_mask:0xf bank_mask:0xf bound_ctrl:1
	v_add_f32_dpp v220, v220, v220 quad_perm:[2,3,0,1] row_mask:0xf bank_mask:0xf bound_ctrl:1
	v_add_f32_dpp v221, v221, v221 quad_perm:[2,3,0,1] row_mask:0xf bank_mask:0xf bound_ctrl:1
	v_pk_mul_f32 v[200:201], v[18:19], v[90:91]
	v_pk_mul_f32 v[208:209], v[10:11], v[90:91]
	v_add_f32_dpp v226, v226, v226 row_half_mirror row_mask:0xf bank_mask:0xf bound_ctrl:1
	v_add_f32_dpp v227, v227, v227 row_half_mirror row_mask:0xf bank_mask:0xf bound_ctrl:1
	v_add_f32_dpp v220, v220, v220 row_half_mirror row_mask:0xf bank_mask:0xf bound_ctrl:1
	v_add_f32_dpp v221, v221, v221 row_half_mirror row_mask:0xf bank_mask:0xf bound_ctrl:1
	v_pk_mul_f32 v[202:203], v[20:21], v[92:93]
	v_pk_mul_f32 v[210:211], v[12:13], v[92:93]
	v_pk_fma_f32 v[196:197], v[126:127], v[110:111], v[196:197] op_sel_hi:[0,1,1]
	v_pk_fma_f32 v[204:205], v[126:127], v[110:111], v[204:205] op_sel:[1,0,0] op_sel_hi:[1,1,1]
	v_pk_fma_f32 v[198:199], v[126:127], v[112:113], v[198:199] op_sel_hi:[0,1,1]
	v_pk_fma_f32 v[206:207], v[126:127], v[112:113], v[206:207] op_sel:[1,0,0] op_sel_hi:[1,1,1]
	v_pk_fma_f32 v[200:201], v[126:127], v[114:115], v[200:201] op_sel_hi:[0,1,1]
	v_pk_fma_f32 v[208:209], v[126:127], v[114:115], v[208:209] op_sel:[1,0,0] op_sel_hi:[1,1,1]
	v_pk_fma_f32 v[202:203], v[126:127], v[116:117], v[202:203] op_sel_hi:[0,1,1]
	v_pk_fma_f32 v[210:211], v[126:127], v[116:117], v[210:211] op_sel:[1,0,0] op_sel_hi:[1,1,1]
	ds_write_b64 v70, v[226:227] offset:448
	v_pk_fma_f32 v[22:23], v[220:221], v[102:103], v[196:197] op_sel_hi:[0,1,1] neg_lo:[1,0,0] neg_hi:[1,0,0]
	v_pk_fma_f32 v[14:15], v[220:221], v[102:103], v[204:205] op_sel:[1,0,0] op_sel_hi:[1,1,1] neg_lo:[1,0,0] neg_hi:[1,0,0]
	v_pk_fma_f32 v[24:25], v[220:221], v[104:105], v[198:199] op_sel_hi:[0,1,1] neg_lo:[1,0,0] neg_hi:[1,0,0]
	v_pk_fma_f32 v[16:17], v[220:221], v[104:105], v[206:207] op_sel:[1,0,0] op_sel_hi:[1,1,1] neg_lo:[1,0,0] neg_hi:[1,0,0]
	v_pk_fma_f32 v[18:19], v[220:221], v[106:107], v[200:201] op_sel_hi:[0,1,1] neg_lo:[1,0,0] neg_hi:[1,0,0]
	v_pk_fma_f32 v[10:11], v[220:221], v[106:107], v[208:209] op_sel:[1,0,0] op_sel_hi:[1,1,1] neg_lo:[1,0,0] neg_hi:[1,0,0]
	v_pk_fma_f32 v[20:21], v[220:221], v[108:109], v[202:203] op_sel_hi:[0,1,1] neg_lo:[1,0,0] neg_hi:[1,0,0]
	v_pk_fma_f32 v[12:13], v[220:221], v[108:109], v[210:211] op_sel:[1,0,0] op_sel_hi:[1,1,1] neg_lo:[1,0,0] neg_hi:[1,0,0]
	v_pk_mul_f32 v[222:223], v[22:23], v[118:119]
	v_pk_mul_f32 v[224:225], v[14:15], v[118:119]
	v_pk_fma_f32 v[222:223], v[24:25], v[120:121], v[222:223]
	v_pk_fma_f32 v[224:225], v[16:17], v[120:121], v[224:225]
	v_pk_fma_f32 v[222:223], v[18:19], v[122:123], v[222:223]
	v_pk_fma_f32 v[224:225], v[10:11], v[122:123], v[224:225]
	v_pk_fma_f32 v[222:223], v[20:21], v[124:125], v[222:223]
	v_pk_fma_f32 v[224:225], v[12:13], v[124:125], v[224:225]
	s_waitcnt lgkmcnt(0)
; __device__ __forceinline__ void scan_rows(f32x2 (&X)[8], const ScanOps& o, const f32x4 (&b)[2], const f32x4 (&kd)[2], const f32x4 (&r)[2], const bool use_v, float& yA, float& yB) {
;     f32x2 aA = X[0] * o.kk[0].xy, aB = X[4] * o.kk[0].xy;
;     aA += X[1] * o.kk[0].zw; aB += X[5] * o.kk[0].zw;
;     aA += X[2] * o.kk[1].xy; aB += X[6] * o.kk[1].xy;
;     aA += X[3] * o.kk[1].zw; aB += X[7] * o.kk[1].zw;
;     const float saA = sum8(aA.x + aA.y), saB = sum8(aB.x + aB.y);
;     const f32x2 nA = (f32x2){-saA, -saA}, nB = (f32x2){-saB, -saB}, vA = (f32x2){o.v.x, o.v.x}, vB = (f32x2){o.v.y, o.v.y};
;     f32x2 tA, tB, accA, accB;
;     tA = X[0] * o.w[0].xy; tA += nA * b[0].xy; if (use_v) tA += vA * kd[0].xy; X[0] = tA; accA = tA * r[0].xy;
;     tB = X[4] * o.w[0].xy; tB += nB * b[0].xy; if (use_v) tB += vB * kd[0].xy; X[4] = tB; accB = tB * r[0].xy;
;     tA = X[1] * o.w[0].zw; tA += nA * b[0].zw; if (use_v) tA += vA * kd[0].zw; X[1] = tA; accA += tA * r[0].zw;
;     tB = X[5] * o.w[0].zw; tB += nB * b[0].zw; if (use_v) tB += vB * kd[0].zw; X[5] = tB; accB += tB * r[0].zw;
;     tA = X[2] * o.w[1].xy; tA += nA * b[1].xy; if (use_v) tA += vA * kd[1].xy; X[2] = tA; accA += tA * r[1].xy;
;     tB = X[6] * o.w[1].xy; tB += nB * b[1].xy; if (use_v) tB += vB * kd[1].xy; X[6] = tB; accB += tB * r[1].xy;
;     tA = X[3] * o.w[1].zw; tA += nA * b[1].zw; if (use_v) tA += vA * kd[1].zw; X[3] = tA; accA += tA * r[1].zw;
;     tB = X[7] * o.w[1].zw; tB += nB * b[1].zw; if (use_v) tB += vB * kd[1].zw; X[7] = tB; accB += tB * r[1].zw;
;     yA = sum8(accA.x + accA.y); yB = sum8(accB.x + accB.y);
; __device__ void phase_scan(int c, const bf16_t* PROJ, const float* k_k, const bf16_t* Wd, const bf16_t* Bd, const float* k_a, bf16_t* Y, bf16_t* Q, float* FS, float* sm) {
;     ...
;                 for (int i = 0; i < 16; i += 2) {
;                     float yA = 0.f, yB = 0.f;
;                     scan_ld(ob, obv, i + 1, B);
;                     if (roleP) A.v = (f32x2){0.f, 0.f};
;                     scan_step1(X, A, ob + i * 64, yA, yB);
;                     *(f32x2*)(obw + i * 16 + 2 * vp) = (f32x2){yA, yB};
;                     if (i + 2 < 16) scan_ld(ob, obv, i + 2, A);
;                     if (roleP) B.v = (f32x2){0.f, 0.f};
;                     scan_step1(X, B, ob + (i + 1) * 64, yA, yB);
;                     *(f32x2*)(obw + (i + 1) * 16 + 2 * vp) = (f32x2){yA, yB};
	ds_read_b128 v[86:89], v84 offset:2560
	ds_read_b128 v[90:93], v84 offset:2576
	ds_read_b128 v[94:97], v84 offset:6656
	ds_read_b128 v[98:101], v84 offset:6672
	ds_read_b128 v[102:105], v84 offset:10752
	ds_read_b128 v[106:109], v84 offset:10768
	ds_read_b128 v[110:113], v84 offset:14848
	ds_read_b128 v[114:117], v84 offset:14864
	ds_read_b128 v[118:121], v84 offset:18944
	ds_read_b128 v[122:125], v84 offset:18960
	ds_read_b64 v[126:127], v85 offset:23040
	v_cndmask_b32_e64 v168, v168, 0, s[8:9]
	v_cndmask_b32_e64 v169, v169, 0, s[8:9]
	v_pk_mul_f32 v[212:213], v[22:23], v[136:137]
	v_pk_mul_f32 v[216:217], v[14:15], v[136:137]
	v_pk_mul_f32 v[214:215], v[18:19], v[140:141]
	v_pk_mul_f32 v[218:219], v[10:11], v[140:141]
	v_pk_fma_f32 v[212:213], v[24:25], v[138:139], v[212:213]
	v_pk_fma_f32 v[216:217], v[16:17], v[138:139], v[216:217]
	v_pk_fma_f32 v[214:215], v[20:21], v[142:143], v[214:215]
	v_pk_fma_f32 v[218:219], v[12:13], v[142:143], v[218:219]
	v_add_f32_e32 v226, v222, v223
	v_add_f32_e32 v227, v224, v225
	v_pk_add_f32 v[212:213], v[212:213], v[214:215]
	v_pk_add_f32 v[216:217], v[216:217], v[218:219]
	v_pk_mul_f32 v[196:197], v[22:23], v[128:129]
	v_pk_mul_f32 v[204:205], v[14:15], v[128:129]
	v_add_f32_e32 v220, v212, v213
	v_add_f32_e32 v221, v216, v217
	v_add_f32_dpp v226, v226, v226 quad_perm:[1,0,3,2] row_mask:0xf bank_mask:0xf bound_ctrl:1
	v_add_f32_dpp v227, v227, v227 quad_perm:[1,0,3,2] row_mask:0xf bank_mask:0xf bound_ctrl:1
	v_add_f32_dpp v220, v220, v220 quad_perm:[1,0,3,2] row_mask:0xf bank_mask:0xf bound_ctrl:1
	v_add_f32_dpp v221, v221, v221 quad_perm:[1,0,3,2] row_mask:0xf bank_mask:0xf bound_ctrl:1
	v_pk_mul_f32 v[198:199], v[24:25], v[130:131]
	v_pk_mul_f32 v[206:207], v[16:17], v[130:131]
	v_add_f32_dpp v226, v226, v226 quad_perm:[2,3,0,1] row_mask:0xf bank_mask:0xf bound_ctrl:1
	v_add_f32_dpp v227, v227, v227 quad_perm:[2,3,0,1] row_mask:0xf bank_mask:0xf bound_ctrl:1
	v_add_f32_dpp v220, v220, v220 quad_perm:[2,3,0,1] row_mask:0xf bank_mask:0xf bound_ctrl:1
	v_add_f32_dpp v221, v221, v221 quad_perm:[2,3,0,1] row_mask:0xf bank_mask:0xf bound_ctrl:1
	v_pk_mul_f32 v[200:201], v[18:19], v[132:133]
	v_pk_mul_f32 v[208:209], v[10:11], v[132:133]
	v_add_f32_dpp v226, v226, v226 row_half_mirror row_mask:0xf bank_mask:0xf bound_ctrl:1
	v_add_f32_dpp v227, v227, v227 row_half_mirror row_mask:0xf bank_mask:0xf bound_ctrl:1
	v_add_f32_dpp v220, v220, v220 row_half_mirror row_mask:0xf bank_mask:0xf bound_ctrl:1
	v_add_f32_dpp v221, v221, v221 row_half_mirror row_mask:0xf bank_mask:0xf bound_ctrl:1
	v_pk_mul_f32 v[202:203], v[20:21], v[134:135]
	v_pk_mul_f32 v[210:211], v[12:13], v[134:135]
	v_pk_fma_f32 v[196:197], v[168:169], v[152:153], v[196:197] op_sel_hi:[0,1,1]
	v_pk_fma_f32 v[204:205], v[168:169], v[152:153], v[204:205] op_sel:[1,0,0] op_sel_hi:[1,1,1]
	v_pk_fma_f32 v[198:199], v[168:169], v[154:155], v[198:199] op_sel_hi:[0,1,1]
	v_pk_fma_f32 v[206:207], v[168:169], v[154:155], v[206:207] op_sel:[1,0,0] op_sel_hi:[1,1,1]
	v_pk_fma_f32 v[200:201], v[168:169], v[156:157], v[200:201] op_sel_hi:[0,1,1]
	v_pk_fma_f32 v[208:209], v[168:169], v[156:157], v[208:209] op_sel:[1,0,0] op_sel_hi:[1,1,1]
	v_pk_fma_f32 v[202:203], v[168:169], v[158:159], v[202:203] op_sel_hi:[0,1,1]
	v_pk_fma_f32 v[210:211], v[168:169], v[158:159], v[210:211] op_sel:[1,0,0] op_sel_hi:[1,1,1]
	ds_write_b64 v70, v[226:227] offset:512
	v_pk_fma_f32 v[22:23], v[220:221], v[144:145], v[196:197] op_sel_hi:[0,1,1] neg_lo:[1,0,0] neg_hi:[1,0,0]
	v_pk_fma_f32 v[14:15], v[220:221], v[144:145], v[204:205] op_sel:[1,0,0] op_sel_hi:[1,1,1] neg_lo:[1,0,0] neg_hi:[1,0,0]
	v_pk_fma_f32 v[24:25], v[220:221], v[146:147], v[198:199] op_sel_hi:[0,1,1] neg_lo:[1,0,0] neg_hi:[1,0,0]
	v_pk_fma_f32 v[16:17], v[220:221], v[146:147], v[206:207] op_sel:[1,0,0] op_sel_hi:[1,1,1] neg_lo:[1,0,0] neg_hi:[1,0,0]
	v_pk_fma_f32 v[18:19], v[220:221], v[148:149], v[200:201] op_sel_hi:[0,1,1] neg_lo:[1,0,0] neg_hi:[1,0,0]
	v_pk_fma_f32 v[10:11], v[220:221], v[148:149], v[208:209] op_sel:[1,0,0] op_sel_hi:[1,1,1] neg_lo:[1,0,0] neg_hi:[1,0,0]
	v_pk_fma_f32 v[20:21], v[220:221], v[150:151], v[202:203] op_sel_hi:[0,1,1] neg_lo:[1,0,0] neg_hi:[1,0,0]
	v_pk_fma_f32 v[12:13], v[220:221], v[150:151], v[210:211] op_sel:[1,0,0] op_sel_hi:[1,1,1] neg_lo:[1,0,0] neg_hi:[1,0,0]
	v_pk_mul_f32 v[222:223], v[22:23], v[160:161]
	v_pk_mul_f32 v[224:225], v[14:15], v[160:161]
	v_pk_fma_f32 v[222:223], v[24:25], v[162:163], v[222:223]
	v_pk_fma_f32 v[224:225], v[16:17], v[162:163], v[224:225]
	v_pk_fma_f32 v[222:223], v[18:19], v[164:165], v[222:223]
	v_pk_fma_f32 v[224:225], v[10:11], v[164:165], v[224:225]
	v_pk_fma_f32 v[222:223], v[20:21], v[166:167], v[222:223]
	v_pk_fma_f32 v[224:225], v[12:13], v[166:167], v[224:225]
	s_waitcnt lgkmcnt(0)
; __device__ __forceinline__ void scan_rows(f32x2 (&X)[8], const ScanOps& o, const f32x4 (&b)[2], const f32x4 (&kd)[2], const f32x4 (&r)[2], const bool use_v, float& yA, float& yB) {
;     f32x2 aA = X[0] * o.kk[0].xy, aB = X[4] * o.kk[0].xy;
;     aA += X[1] * o.kk[0].zw; aB += X[5] * o.kk[0].zw;
;     aA += X[2] * o.kk[1].xy; aB += X[6] * o.kk[1].xy;
;     aA += X[3] * o.kk[1].zw; aB += X[7] * o.kk[1].zw;
;     const float saA = sum8(aA.x + aA.y), saB = sum8(aB.x + aB.y);
;     const f32x2 nA = (f32x2){-saA, -saA}, nB = (f32x2){-saB, -saB}, vA = (f32x2){o.v.x, o.v.x}, vB = (f32x2){o.v.y, o.v.y};
;     f32x2 tA, tB, accA, accB;
;     tA = X[0] * o.w[0].xy; tA += nA * b[0].xy; if (use_v) tA += vA * kd[0].xy; X[0] = tA; accA = tA * r[0].xy;
;     tB = X[4] * o.w[0].xy; tB += nB * b[0].xy; if (use_v) tB += vB * kd[0].xy; X[4] = tB; accB = tB * r[0].xy;
;     tA = X[1] * o.w[0].zw; tA += nA * b[0].zw; if (use_v) tA += vA * kd[0].zw; X[1] = tA; accA += tA * r[0].zw;
;     tB = X[5] * o.w[0].zw; tB += nB * b[0].zw; if (use_v) tB += vB * kd[0].zw; X[5] = tB; accB += tB * r[0].zw;
;     tA = X[2] * o.w[1].xy; tA += nA * b[1].xy; if (use_v) tA += vA * kd[1].xy; X[2] = tA; accA += tA * r[1].xy;
;     tB = X[6] * o.w[1].xy; tB += nB * b[1].xy; if (use_v) tB += vB * kd[1].xy; X[6] = tB; accB += tB * r[1].xy;
;     tA = X[3] * o.w[1].zw; tA += nA * b[1].zw; if (use_v) tA += vA * kd[1].zw; X[3] = tA; accA += tA * r[1].zw;
;     tB = X[7] * o.w[1].zw; tB += nB * b[1].zw; if (use_v) tB += vB * kd[1].zw; X[7] = tB; accB += tB * r[1].zw;
;     yA = sum8(accA.x + accA.y); yB = sum8(accB.x + accB.y);
; __device__ void phase_scan(int c, const bf16_t* PROJ, const float* k_k, const bf16_t* Wd, const bf16_t* Bd, const float* k_a, bf16_t* Y, bf16_t* Q, float* FS, float* sm) {
;     ...
;                 for (int i = 0; i < 16; i += 2) {
;                     float yA = 0.f, yB = 0.f;
;                     scan_ld(ob, obv, i + 1, B);
;                     if (roleP) A.v = (f32x2){0.f, 0.f};
;                     scan_step1(X, A, ob + i * 64, yA, yB);
;                     *(f32x2*)(obw + i * 16 + 2 * vp) = (f32x2){yA, yB};
;                     if (i + 2 < 16) scan_ld(ob, obv, i + 2, A);
;                     if (roleP) B.v = (f32x2){0.f, 0.f};
;                     scan_step1(X, B, ob + (i + 1) * 64, yA, yB);
;                     *(f32x2*)(obw + (i + 1) * 16 + 2 * vp) = (f32x2){yA, yB};
	ds_read_b128 v[128:131], v84 offset:2816
	ds_read_b128 v[132:135], v84 offset:2832
	ds_read_b128 v[136:139], v84 offset:6912
	ds_read_b128 v[140:143], v84 offset:6928
	ds_read_b128 v[144:147], v84 offset:11008
	ds_read_b128 v[148:151], v84 offset:11024
	ds_read_b128 v[152:155], v84 offset:15104
	ds_read_b128 v[156:159], v84 offset:15120
	ds_read_b128 v[160:163], v84 offset:19200
	ds_read_b128 v[164:167], v84 offset:19216
	ds_read_b64 v[168:169], v85 offset:23296
	v_cndmask_b32_e64 v126, v126, 0, s[8:9]
	v_cndmask_b32_e64 v127, v127, 0, s[8:9]
	v_pk_mul_f32 v[212:213], v[22:23], v[94:95]
	v_pk_mul_f32 v[216:217], v[14:15], v[94:95]
	v_pk_mul_f32 v[214:215], v[18:19], v[98:99]
	v_pk_mul_f32 v[218:219], v[10:11], v[98:99]
	v_pk_fma_f32 v[212:213], v[24:25], v[96:97], v[212:213]
	v_pk_fma_f32 v[216:217], v[16:17], v[96:97], v[216:217]
	v_pk_fma_f32 v[214:215], v[20:21], v[100:101], v[214:215]
	v_pk_fma_f32 v[218:219], v[12:13], v[100:101], v[218:219]
	v_add_f32_e32 v226, v222, v223
	v_add_f32_e32 v227, v224, v225
	v_pk_add_f32 v[212:213], v[212:213], v[214:215]
	v_pk_add_f32 v[216:217], v[216:217], v[218:219]
	v_pk_mul_f32 v[196:197], v[22:23], v[86:87]
	v_pk_mul_f32 v[204:205], v[14:15], v[86:87]
	v_add_f32_e32 v220, v212, v213
	v_add_f32_e32 v221, v216, v217
	v_add_f32_dpp v226, v226, v226 quad_perm:[1,0,3,2] row_mask:0xf bank_mask:0xf bound_ctrl:1
	v_add_f32_dpp v227, v227, v227 quad_perm:[1,0,3,2] row_mask:0xf bank_mask:0xf bound_ctrl:1
	v_add_f32_dpp v220, v220, v220 quad_perm:[1,0,3,2] row_mask:0xf bank_mask:0xf bound_ctrl:1
	v_add_f32_dpp v221, v221, v221 quad_perm:[1,0,3,2] row_mask:0xf bank_mask:0xf bound_ctrl:1
	v_pk_mul_f32 v[198:199], v[24:25], v[88:89]
	v_pk_mul_f32 v[206:207], v[16:17], v[88:89]
	v_add_f32_dpp v226, v226, v226 quad_perm:[2,3,0,1] row_mask:0xf bank_mask:0xf bound_ctrl:1
	v_add_f32_dpp v227, v227, v227 quad_perm:[2,3,0,1] row_mask:0xf bank_mask:0xf bound_ctrl:1
	v_add_f32_dpp v220, v220, v220 quad_perm:[2,3,0,1] row_mask:0xf bank_mask:0xf bound_ctrl:1
	v_add_f32_dpp v221, v221, v221 quad_perm:[2,3,0,1] row_mask:0xf bank_mask:0xf bound_ctrl:1
	v_pk_mul_f32 v[200:201], v[18:19], v[90:91]
	v_pk_mul_f32 v[208:209], v[10:11], v[90:91]
	v_add_f32_dpp v226, v226, v226 row_half_mirror row_mask:0xf bank_mask:0xf bound_ctrl:1
	v_add_f32_dpp v227, v227, v227 row_half_mirror row_mask:0xf bank_mask:0xf bound_ctrl:1
	v_add_f32_dpp v220, v220, v220 row_half_mirror row_mask:0xf bank_mask:0xf bound_ctrl:1
	v_add_f32_dpp v221, v221, v221 row_half_mirror row_mask:0xf bank_mask:0xf bound_ctrl:1
	v_pk_mul_f32 v[202:203], v[20:21], v[92:93]
	v_pk_mul_f32 v[210:211], v[12:13], v[92:93]
	v_pk_fma_f32 v[196:197], v[126:127], v[110:111], v[196:197] op_sel_hi:[0,1,1]
	v_pk_fma_f32 v[204:205], v[126:127], v[110:111], v[204:205] op_sel:[1,0,0] op_sel_hi:[1,1,1]
	v_pk_fma_f32 v[198:199], v[126:127], v[112:113], v[198:199] op_sel_hi:[0,1,1]
	v_pk_fma_f32 v[206:207], v[126:127], v[112:113], v[206:207] op_sel:[1,0,0] op_sel_hi:[1,1,1]
	v_pk_fma_f32 v[200:201], v[126:127], v[114:115], v[200:201] op_sel_hi:[0,1,1]
	v_pk_fma_f32 v[208:209], v[126:127], v[114:115], v[208:209] op_sel:[1,0,0] op_sel_hi:[1,1,1]
	v_pk_fma_f32 v[202:203], v[126:127], v[116:117], v[202:203] op_sel_hi:[0,1,1]
	v_pk_fma_f32 v[210:211], v[126:127], v[116:117], v[210:211] op_sel:[1,0,0] op_sel_hi:[1,1,1]
	ds_write_b64 v70, v[226:227] offset:576
	v_pk_fma_f32 v[22:23], v[220:221], v[102:103], v[196:197] op_sel_hi:[0,1,1] neg_lo:[1,0,0] neg_hi:[1,0,0]
	v_pk_fma_f32 v[14:15], v[220:221], v[102:103], v[204:205] op_sel:[1,0,0] op_sel_hi:[1,1,1] neg_lo:[1,0,0] neg_hi:[1,0,0]
	v_pk_fma_f32 v[24:25], v[220:221], v[104:105], v[198:199] op_sel_hi:[0,1,1] neg_lo:[1,0,0] neg_hi:[1,0,0]
	v_pk_fma_f32 v[16:17], v[220:221], v[104:105], v[206:207] op_sel:[1,0,0] op_sel_hi:[1,1,1] neg_lo:[1,0,0] neg_hi:[1,0,0]
	v_pk_fma_f32 v[18:19], v[220:221], v[106:107], v[200:201] op_sel_hi:[0,1,1] neg_lo:[1,0,0] neg_hi:[1,0,0]
	v_pk_fma_f32 v[10:11], v[220:221], v[106:107], v[208:209] op_sel:[1,0,0] op_sel_hi:[1,1,1] neg_lo:[1,0,0] neg_hi:[1,0,0]
	v_pk_fma_f32 v[20:21], v[220:221], v[108:109], v[202:203] op_sel_hi:[0,1,1] neg_lo:[1,0,0] neg_hi:[1,0,0]
	v_pk_fma_f32 v[12:13], v[220:221], v[108:109], v[210:211] op_sel:[1,0,0] op_sel_hi:[1,1,1] neg_lo:[1,0,0] neg_hi:[1,0,0]
	v_pk_mul_f32 v[222:223], v[22:23], v[118:119]
	v_pk_mul_f32 v[224:225], v[14:15], v[118:119]
	v_pk_fma_f32 v[222:223], v[24:25], v[120:121], v[222:223]
	v_pk_fma_f32 v[224:225], v[16:17], v[120:121], v[224:225]
	v_pk_fma_f32 v[222:223], v[18:19], v[122:123], v[222:223]
	v_pk_fma_f32 v[224:225], v[10:11], v[122:123], v[224:225]
	v_pk_fma_f32 v[222:223], v[20:21], v[124:125], v[222:223]
	v_pk_fma_f32 v[224:225], v[12:13], v[124:125], v[224:225]
	s_waitcnt lgkmcnt(0)
; __device__ __forceinline__ void scan_rows(f32x2 (&X)[8], const ScanOps& o, const f32x4 (&b)[2], const f32x4 (&kd)[2], const f32x4 (&r)[2], const bool use_v, float& yA, float& yB) {
;     f32x2 aA = X[0] * o.kk[0].xy, aB = X[4] * o.kk[0].xy;
;     aA += X[1] * o.kk[0].zw; aB += X[5] * o.kk[0].zw;
;     aA += X[2] * o.kk[1].xy; aB += X[6] * o.kk[1].xy;
;     aA += X[3] * o.kk[1].zw; aB += X[7] * o.kk[1].zw;
;     const float saA = sum8(aA.x + aA.y), saB = sum8(aB.x + aB.y);
;     const f32x2 nA = (f32x2){-saA, -saA}, nB = (f32x2){-saB, -saB}, vA = (f32x2){o.v.x, o.v.x}, vB = (f32x2){o.v.y, o.v.y};
;     f32x2 tA, tB, accA, accB;
;     tA = X[0] * o.w[0].xy; tA += nA * b[0].xy; if (use_v) tA += vA * kd[0].xy; X[0] = tA; accA = tA * r[0].xy;
;     tB = X[4] * o.w[0].xy; tB += nB * b[0].xy; if (use_v) tB += vB * kd[0].xy; X[4] = tB; accB = tB * r[0].xy;
;     tA = X[1] * o.w[0].zw; tA += nA * b[0].zw; if (use_v) tA += vA * kd[0].zw; X[1] = tA; accA += tA * r[0].zw;
;     tB = X[5] * o.w[0].zw; tB += nB * b[0].zw; if (use_v) tB += vB * kd[0].zw; X[5] = tB; accB += tB * r[0].zw;
;     tA = X[2] * o.w[1].xy; tA += nA * b[1].xy; if (use_v) tA += vA * kd[1].xy; X[2] = tA; accA += tA * r[1].xy;
;     tB = X[6] * o.w[1].xy; tB += nB * b[1].xy; if (use_v) tB += vB * kd[1].xy; X[6] = tB; accB += tB * r[1].xy;
;     tA = X[3] * o.w[1].zw; tA += nA * b[1].zw; if (use_v) tA += vA * kd[1].zw; X[3] = tA; accA += tA * r[1].zw;
;     tB = X[7] * o.w[1].zw; tB += nB * b[1].zw; if (use_v) tB += vB * kd[1].zw; X[7] = tB; accB += tB * r[1].zw;
;     yA = sum8(accA.x + accA.y); yB = sum8(accB.x + accB.y);
; __device__ void phase_scan(int c, const bf16_t* PROJ, const float* k_k, const bf16_t* Wd, const bf16_t* Bd, const float* k_a, bf16_t* Y, bf16_t* Q, float* FS, float* sm) {
;     ...
;                 for (int i = 0; i < 16; i += 2) {
;                     float yA = 0.f, yB = 0.f;
;                     scan_ld(ob, obv, i + 1, B);
;                     if (roleP) A.v = (f32x2){0.f, 0.f};
;                     scan_step1(X, A, ob + i * 64, yA, yB);
;                     *(f32x2*)(obw + i * 16 + 2 * vp) = (f32x2){yA, yB};
;                     if (i + 2 < 16) scan_ld(ob, obv, i + 2, A);
;                     if (roleP) B.v = (f32x2){0.f, 0.f};
;                     scan_step1(X, B, ob + (i + 1) * 64, yA, yB);
;                     *(f32x2*)(obw + (i + 1) * 16 + 2 * vp) = (f32x2){yA, yB};
	ds_read_b128 v[86:89], v84 offset:3072
	ds_read_b128 v[90:93], v84 offset:3088
	ds_read_b128 v[94:97], v84 offset:7168
	ds_read_b128 v[98:101], v84 offset:7184
	ds_read_b128 v[102:105], v84 offset:11264
	ds_read_b128 v[106:109], v84 offset:11280
	ds_read_b128 v[110:113], v84 offset:15360
	ds_read_b128 v[114:117], v84 offset:15376
	ds_read_b128 v[118:121], v84 offset:19456
	ds_read_b128 v[122:125], v84 offset:19472
	ds_read_b64 v[126:127], v85 offset:23552
	v_cndmask_b32_e64 v168, v168, 0, s[8:9]
	v_cndmask_b32_e64 v169, v169, 0, s[8:9]
	v_pk_mul_f32 v[212:213], v[22:23], v[136:137]
	v_pk_mul_f32 v[216:217], v[14:15], v[136:137]
	v_pk_mul_f32 v[214:215], v[18:19], v[140:141]
	v_pk_mul_f32 v[218:219], v[10:11], v[140:141]
	v_pk_fma_f32 v[212:213], v[24:25], v[138:139], v[212:213]
	v_pk_fma_f32 v[216:217], v[16:17], v[138:139], v[216:217]
	v_pk_fma_f32 v[214:215], v[20:21], v[142:143], v[214:215]
	v_pk_fma_f32 v[218:219], v[12:13], v[142:143], v[218:219]
	v_add_f32_e32 v226, v222, v223
	v_add_f32_e32 v227, v224, v225
	v_pk_add_f32 v[212:213], v[212:213], v[214:215]
	v_pk_add_f32 v[216:217], v[216:217], v[218:219]
	v_pk_mul_f32 v[196:197], v[22:23], v[128:129]
	v_pk_mul_f32 v[204:205], v[14:15], v[128:129]
	v_add_f32_e32 v220, v212, v213
	v_add_f32_e32 v221, v216, v217
	v_add_f32_dpp v226, v226, v226 quad_perm:[1,0,3,2] row_mask:0xf bank_mask:0xf bound_ctrl:1
	v_add_f32_dpp v227, v227, v227 quad_perm:[1,0,3,2] row_mask:0xf bank_mask:0xf bound_ctrl:1
	v_add_f32_dpp v220, v220, v220 quad_perm:[1,0,3,2] row_mask:0xf bank_mask:0xf bound_ctrl:1
	v_add_f32_dpp v221, v221, v221 quad_perm:[1,0,3,2] row_mask:0xf bank_mask:0xf bound_ctrl:1
	v_pk_mul_f32 v[198:199], v[24:25], v[130:131]
	v_pk_mul_f32 v[206:207], v[16:17], v[130:131]
	v_add_f32_dpp v226, v226, v226 quad_perm:[2,3,0,1] row_mask:0xf bank_mask:0xf bound_ctrl:1
	v_add_f32_dpp v227, v227, v227 quad_perm:[2,3,0,1] row_mask:0xf bank_mask:0xf bound_ctrl:1
	v_add_f32_dpp v220, v220, v220 quad_perm:[2,3,0,1] row_mask:0xf bank_mask:0xf bound_ctrl:1
	v_add_f32_dpp v221, v221, v221 quad_perm:[2,3,0,1] row_mask:0xf bank_mask:0xf bound_ctrl:1
	v_pk_mul_f32 v[200:201], v[18:19], v[132:133]
	v_pk_mul_f32 v[208:209], v[10:11], v[132:133]
	v_add_f32_dpp v226, v226, v226 row_half_mirror row_mask:0xf bank_mask:0xf bound_ctrl:1
	v_add_f32_dpp v227, v227, v227 row_half_mirror row_mask:0xf bank_mask:0xf bound_ctrl:1
	v_add_f32_dpp v220, v220, v220 row_half_mirror row_mask:0xf bank_mask:0xf bound_ctrl:1
	v_add_f32_dpp v221, v221, v221 row_half_mirror row_mask:0xf bank_mask:0xf bound_ctrl:1
	v_pk_mul_f32 v[202:203], v[20:21], v[134:135]
	v_pk_mul_f32 v[210:211], v[12:13], v[134:135]
	v_pk_fma_f32 v[196:197], v[168:169], v[152:153], v[196:197] op_sel_hi:[0,1,1]
	v_pk_fma_f32 v[204:205], v[168:169], v[152:153], v[204:205] op_sel:[1,0,0] op_sel_hi:[1,1,1]
	v_pk_fma_f32 v[198:199], v[168:169], v[154:155], v[198:199] op_sel_hi:[0,1,1]
	v_pk_fma_f32 v[206:207], v[168:169], v[154:155], v[206:207] op_sel:[1,0,0] op_sel_hi:[1,1,1]
	v_pk_fma_f32 v[200:201], v[168:169], v[156:157], v[200:201] op_sel_hi:[0,1,1]
	v_pk_fma_f32 v[208:209], v[168:169], v[156:157], v[208:209] op_sel:[1,0,0] op_sel_hi:[1,1,1]
	v_pk_fma_f32 v[202:203], v[168:169], v[158:159], v[202:203] op_sel_hi:[0,1,1]
	v_pk_fma_f32 v[210:211], v[168:169], v[158:159], v[210:211] op_sel:[1,0,0] op_sel_hi:[1,1,1]
	ds_write_b64 v70, v[226:227] offset:640
	v_pk_fma_f32 v[22:23], v[220:221], v[144:145], v[196:197] op_sel_hi:[0,1,1] neg_lo:[1,0,0] neg_hi:[1,0,0]
	v_pk_fma_f32 v[14:15], v[220:221], v[144:145], v[204:205] op_sel:[1,0,0] op_sel_hi:[1,1,1] neg_lo:[1,0,0] neg_hi:[1,0,0]
	v_pk_fma_f32 v[24:25], v[220:221], v[146:147], v[198:199] op_sel_hi:[0,1,1] neg_lo:[1,0,0] neg_hi:[1,0,0]
	v_pk_fma_f32 v[16:17], v[220:221], v[146:147], v[206:207] op_sel:[1,0,0] op_sel_hi:[1,1,1] neg_lo:[1,0,0] neg_hi:[1,0,0]
	v_pk_fma_f32 v[18:19], v[220:221], v[148:149], v[200:201] op_sel_hi:[0,1,1] neg_lo:[1,0,0] neg_hi:[1,0,0]
	v_pk_fma_f32 v[10:11], v[220:221], v[148:149], v[208:209] op_sel:[1,0,0] op_sel_hi:[1,1,1] neg_lo:[1,0,0] neg_hi:[1,0,0]
	v_pk_fma_f32 v[20:21], v[220:221], v[150:151], v[202:203] op_sel_hi:[0,1,1] neg_lo:[1,0,0] neg_hi:[1,0,0]
	v_pk_fma_f32 v[12:13], v[220:221], v[150:151], v[210:211] op_sel:[1,0,0] op_sel_hi:[1,1,1] neg_lo:[1,0,0] neg_hi:[1,0,0]
	v_pk_mul_f32 v[222:223], v[22:23], v[160:161]
	v_pk_mul_f32 v[224:225], v[14:15], v[160:161]
	v_pk_fma_f32 v[222:223], v[24:25], v[162:163], v[222:223]
	v_pk_fma_f32 v[224:225], v[16:17], v[162:163], v[224:225]
	v_pk_fma_f32 v[222:223], v[18:19], v[164:165], v[222:223]
	v_pk_fma_f32 v[224:225], v[10:11], v[164:165], v[224:225]
	v_pk_fma_f32 v[222:223], v[20:21], v[166:167], v[222:223]
	v_pk_fma_f32 v[224:225], v[12:13], v[166:167], v[224:225]
	s_waitcnt lgkmcnt(0)
; __device__ __forceinline__ void scan_rows(f32x2 (&X)[8], const ScanOps& o, const f32x4 (&b)[2], const f32x4 (&kd)[2], const f32x4 (&r)[2], const bool use_v, float& yA, float& yB) {
;     f32x2 aA = X[0] * o.kk[0].xy, aB = X[4] * o.kk[0].xy;
;     aA += X[1] * o.kk[0].zw; aB += X[5] * o.kk[0].zw;
;     aA += X[2] * o.kk[1].xy; aB += X[6] * o.kk[1].xy;
;     aA += X[3] * o.kk[1].zw; aB += X[7] * o.kk[1].zw;
;     const float saA = sum8(aA.x + aA.y), saB = sum8(aB.x + aB.y);
;     const f32x2 nA = (f32x2){-saA, -saA}, nB = (f32x2){-saB, -saB}, vA = (f32x2){o.v.x, o.v.x}, vB = (f32x2){o.v.y, o.v.y};
;     f32x2 tA, tB, accA, accB;
;     tA = X[0] * o.w[0].xy; tA += nA * b[0].xy; if (use_v) tA += vA * kd[0].xy; X[0] = tA; accA = tA * r[0].xy;
;     tB = X[4] * o.w[0].xy; tB += nB * b[0].xy; if (use_v) tB += vB * kd[0].xy; X[4] = tB; accB = tB * r[0].xy;
;     tA = X[1] * o.w[0].zw; tA += nA * b[0].zw; if (use_v) tA += vA * kd[0].zw; X[1] = tA; accA += tA * r[0].zw;
;     tB = X[5] * o.w[0].zw; tB += nB * b[0].zw; if (use_v) tB += vB * kd[0].zw; X[5] = tB; accB += tB * r[0].zw;
;     tA = X[2] * o.w[1].xy; tA += nA * b[1].xy; if (use_v) tA += vA * kd[1].xy; X[2] = tA; accA += tA * r[1].xy;
;     tB = X[6] * o.w[1].xy; tB += nB * b[1].xy; if (use_v) tB += vB * kd[1].xy; X[6] = tB; accB += tB * r[1].xy;
;     tA = X[3] * o.w[1].zw; tA += nA * b[1].zw; if (use_v) tA += vA * kd[1].zw; X[3] = tA; accA += tA * r[1].zw;
;     tB = X[7] * o.w[1].zw; tB += nB * b[1].zw; if (use_v) tB += vB * kd[1].zw; X[7] = tB; accB += tB * r[1].zw;
;     yA = sum8(accA.x + accA.y); yB = sum8(accB.x + accB.y);
; __device__ void phase_scan(int c, const bf16_t* PROJ, const float* k_k, const bf16_t* Wd, const bf16_t* Bd, const float* k_a, bf16_t* Y, bf16_t* Q, float* FS, float* sm) {
;     ...
;                 for (int i = 0; i < 16; i += 2) {
;                     float yA = 0.f, yB = 0.f;
;                     scan_ld(ob, obv, i + 1, B);
;                     if (roleP) A.v = (f32x2){0.f, 0.f};
;                     scan_step1(X, A, ob + i * 64, yA, yB);
;                     *(f32x2*)(obw + i * 16 + 2 * vp) = (f32x2){yA, yB};
;                     if (i + 2 < 16) scan_ld(ob, obv, i + 2, A);
;                     if (roleP) B.v = (f32x2){0.f, 0.f};
;                     scan_step1(X, B, ob + (i + 1) * 64, yA, yB);
;                     *(f32x2*)(obw + (i + 1) * 16 + 2 * vp) = (f32x2){yA, yB};
	ds_read_b128 v[128:131], v84 offset:3328
	ds_read_b128 v[132:135], v84 offset:3344
	ds_read_b128 v[136:139], v84 offset:7424
	ds_read_b128 v[140:143], v84 offset:7440
	ds_read_b128 v[144:147], v84 offset:11520
	ds_read_b128 v[148:151], v84 offset:11536
	ds_read_b128 v[152:155], v84 offset:15616
	ds_read_b128 v[156:159], v84 offset:15632
	ds_read_b128 v[160:163], v84 offset:19712
	ds_read_b128 v[164:167], v84 offset:19728
	ds_read_b64 v[168:169], v85 offset:23808
	v_cndmask_b32_e64 v126, v126, 0, s[8:9]
	v_cndmask_b32_e64 v127, v127, 0, s[8:9]
	v_pk_mul_f32 v[212:213], v[22:23], v[94:95]
	v_pk_mul_f32 v[216:217], v[14:15], v[94:95]
	v_pk_mul_f32 v[214:215], v[18:19], v[98:99]
	v_pk_mul_f32 v[218:219], v[10:11], v[98:99]
	v_pk_fma_f32 v[212:213], v[24:25], v[96:97], v[212:213]
	v_pk_fma_f32 v[216:217], v[16:17], v[96:97], v[216:217]
	v_pk_fma_f32 v[214:215], v[20:21], v[100:101], v[214:215]
	v_pk_fma_f32 v[218:219], v[12:13], v[100:101], v[218:219]
	v_add_f32_e32 v226, v222, v223
	v_add_f32_e32 v227, v224, v225
	v_pk_add_f32 v[212:213], v[212:213], v[214:215]
	v_pk_add_f32 v[216:217], v[216:217], v[218:219]
	v_pk_mul_f32 v[196:197], v[22:23], v[86:87]
	v_pk_mul_f32 v[204:205], v[14:15], v[86:87]
	v_add_f32_e32 v220, v212, v213
	v_add_f32_e32 v221, v216, v217
	v_add_f32_dpp v226, v226, v226 quad_perm:[1,0,3,2] row_mask:0xf bank_mask:0xf bound_ctrl:1
	v_add_f32_dpp v227, v227, v227 quad_perm:[1,0,3,2] row_mask:0xf bank_mask:0xf bound_ctrl:1
	v_add_f32_dpp v220, v220, v220 quad_perm:[1,0,3,2] row_mask:0xf bank_mask:0xf bound_ctrl:1
	v_add_f32_dpp v221, v221, v221 quad_perm:[1,0,3,2] row_mask:0xf bank_mask:0xf bound_ctrl:1
	v_pk_mul_f32 v[198:199], v[24:25], v[88:89]
	v_pk_mul_f32 v[206:207], v[16:17], v[88:89]
	v_add_f32_dpp v226, v226, v226 quad_perm:[2,3,0,1] row_mask:0xf bank_mask:0xf bound_ctrl:1
	v_add_f32_dpp v227, v227, v227 quad_perm:[2,3,0,1] row_mask:0xf bank_mask:0xf bound_ctrl:1
	v_add_f32_dpp v220, v220, v220 quad_perm:[2,3,0,1] row_mask:0xf bank_mask:0xf bound_ctrl:1
	v_add_f32_dpp v221, v221, v221 quad_perm:[2,3,0,1] row_mask:0xf bank_mask:0xf bound_ctrl:1
	v_pk_mul_f32 v[200:201], v[18:19], v[90:91]
	v_pk_mul_f32 v[208:209], v[10:11], v[90:91]
	v_add_f32_dpp v226, v226, v226 row_half_mirror row_mask:0xf bank_mask:0xf bound_ctrl:1
	v_add_f32_dpp v227, v227, v227 row_half_mirror row_mask:0xf bank_mask:0xf bound_ctrl:1
	v_add_f32_dpp v220, v220, v220 row_half_mirror row_mask:0xf bank_mask:0xf bound_ctrl:1
	v_add_f32_dpp v221, v221, v221 row_half_mirror row_mask:0xf bank_mask:0xf bound_ctrl:1
	v_pk_mul_f32 v[202:203], v[20:21], v[92:93]
	v_pk_mul_f32 v[210:211], v[12:13], v[92:93]
	v_pk_fma_f32 v[196:197], v[126:127], v[110:111], v[196:197] op_sel_hi:[0,1,1]
	v_pk_fma_f32 v[204:205], v[126:127], v[110:111], v[204:205] op_sel:[1,0,0] op_sel_hi:[1,1,1]
	v_pk_fma_f32 v[198:199], v[126:127], v[112:113], v[198:199] op_sel_hi:[0,1,1]
	v_pk_fma_f32 v[206:207], v[126:127], v[112:113], v[206:207] op_sel:[1,0,0] op_sel_hi:[1,1,1]
	v_pk_fma_f32 v[200:201], v[126:127], v[114:115], v[200:201] op_sel_hi:[0,1,1]
	v_pk_fma_f32 v[208:209], v[126:127], v[114:115], v[208:209] op_sel:[1,0,0] op_sel_hi:[1,1,1]
	v_pk_fma_f32 v[202:203], v[126:127], v[116:117], v[202:203] op_sel_hi:[0,1,1]
	v_pk_fma_f32 v[210:211], v[126:127], v[116:117], v[210:211] op_sel:[1,0,0] op_sel_hi:[1,1,1]
	ds_write_b64 v70, v[226:227] offset:704
	v_pk_fma_f32 v[22:23], v[220:221], v[102:103], v[196:197] op_sel_hi:[0,1,1] neg_lo:[1,0,0] neg_hi:[1,0,0]
	v_pk_fma_f32 v[14:15], v[220:221], v[102:103], v[204:205] op_sel:[1,0,0] op_sel_hi:[1,1,1] neg_lo:[1,0,0] neg_hi:[1,0,0]
	v_pk_fma_f32 v[24:25], v[220:221], v[104:105], v[198:199] op_sel_hi:[0,1,1] neg_lo:[1,0,0] neg_hi:[1,0,0]
	v_pk_fma_f32 v[16:17], v[220:221], v[104:105], v[206:207] op_sel:[1,0,0] op_sel_hi:[1,1,1] neg_lo:[1,0,0] neg_hi:[1,0,0]
	v_pk_fma_f32 v[18:19], v[220:221], v[106:107], v[200:201] op_sel_hi:[0,1,1] neg_lo:[1,0,0] neg_hi:[1,0,0]
	v_pk_fma_f32 v[10:11], v[220:221], v[106:107], v[208:209] op_sel:[1,0,0] op_sel_hi:[1,1,1] neg_lo:[1,0,0] neg_hi:[1,0,0]
	v_pk_fma_f32 v[20:21], v[220:221], v[108:109], v[202:203] op_sel_hi:[0,1,1] neg_lo:[1,0,0] neg_hi:[1,0,0]
	v_pk_fma_f32 v[12:13], v[220:221], v[108:109], v[210:211] op_sel:[1,0,0] op_sel_hi:[1,1,1] neg_lo:[1,0,0] neg_hi:[1,0,0]
	v_pk_mul_f32 v[222:223], v[22:23], v[118:119]
	v_pk_mul_f32 v[224:225], v[14:15], v[118:119]
	v_pk_fma_f32 v[222:223], v[24:25], v[120:121], v[222:223]
	v_pk_fma_f32 v[224:225], v[16:17], v[120:121], v[224:225]
	v_pk_fma_f32 v[222:223], v[18:19], v[122:123], v[222:223]
	v_pk_fma_f32 v[224:225], v[10:11], v[122:123], v[224:225]
	v_pk_fma_f32 v[222:223], v[20:21], v[124:125], v[222:223]
	v_pk_fma_f32 v[224:225], v[12:13], v[124:125], v[224:225]
	s_waitcnt lgkmcnt(0)
; __device__ __forceinline__ void scan_rows(f32x2 (&X)[8], const ScanOps& o, const f32x4 (&b)[2], const f32x4 (&kd)[2], const f32x4 (&r)[2], const bool use_v, float& yA, float& yB) {
;     f32x2 aA = X[0] * o.kk[0].xy, aB = X[4] * o.kk[0].xy;
;     aA += X[1] * o.kk[0].zw; aB += X[5] * o.kk[0].zw;
;     aA += X[2] * o.kk[1].xy; aB += X[6] * o.kk[1].xy;
;     aA += X[3] * o.kk[1].zw; aB += X[7] * o.kk[1].zw;
;     const float saA = sum8(aA.x + aA.y), saB = sum8(aB.x + aB.y);
;     const f32x2 nA = (f32x2){-saA, -saA}, nB = (f32x2){-saB, -saB}, vA = (f32x2){o.v.x, o.v.x}, vB = (f32x2){o.v.y, o.v.y};
;     f32x2 tA, tB, accA, accB;
;     tA = X[0] * o.w[0].xy; tA += nA * b[0].xy; if (use_v) tA += vA * kd[0].xy; X[0] = tA; accA = tA * r[0].xy;
;     tB = X[4] * o.w[0].xy; tB += nB * b[0].xy; if (use_v) tB += vB * kd[0].xy; X[4] = tB; accB = tB * r[0].xy;
;     tA = X[1] * o.w[0].zw; tA += nA * b[0].zw; if (use_v) tA += vA * kd[0].zw; X[1] = tA; accA += tA * r[0].zw;
;     tB = X[5] * o.w[0].zw; tB += nB * b[0].zw; if (use_v) tB += vB * kd[0].zw; X[5] = tB; accB += tB * r[0].zw;
;     tA = X[2] * o.w[1].xy; tA += nA * b[1].xy; if (use_v) tA += vA * kd[1].xy; X[2] = tA; accA += tA * r[1].xy;
;     tB = X[6] * o.w[1].xy; tB += nB * b[1].xy; if (use_v) tB += vB * kd[1].xy; X[6] = tB; accB += tB * r[1].xy;
;     tA = X[3] * o.w[1].zw; tA += nA * b[1].zw; if (use_v) tA += vA * kd[1].zw; X[3] = tA; accA += tA * r[1].zw;
;     tB = X[7] * o.w[1].zw; tB += nB * b[1].zw; if (use_v) tB += vB * kd[1].zw; X[7] = tB; accB += tB * r[1].zw;
;     yA = sum8(accA.x + accA.y); yB = sum8(accB.x + accB.y);
; __device__ void phase_scan(int c, const bf16_t* PROJ, const float* k_k, const bf16_t* Wd, const bf16_t* Bd, const float* k_a, bf16_t* Y, bf16_t* Q, float* FS, float* sm) {
;     ...
;                 for (int i = 0; i < 16; i += 2) {
;                     float yA = 0.f, yB = 0.f;
;                     scan_ld(ob, obv, i + 1, B);
;                     if (roleP) A.v = (f32x2){0.f, 0.f};
;                     scan_step1(X, A, ob + i * 64, yA, yB);
;                     *(f32x2*)(obw + i * 16 + 2 * vp) = (f32x2){yA, yB};
;                     if (i + 2 < 16) scan_ld(ob, obv, i + 2, A);
;                     if (roleP) B.v = (f32x2){0.f, 0.f};
;                     scan_step1(X, B, ob + (i + 1) * 64, yA, yB);
;                     *(f32x2*)(obw + (i + 1) * 16 + 2 * vp) = (f32x2){yA, yB};
	ds_read_b128 v[86:89], v84 offset:3584
	ds_read_b128 v[90:93], v84 offset:3600
	ds_read_b128 v[94:97], v84 offset:7680
	ds_read_b128 v[98:101], v84 offset:7696
	ds_read_b128 v[102:105], v84 offset:11776
	ds_read_b128 v[106:109], v84 offset:11792
	ds_read_b128 v[110:113], v84 offset:15872
	ds_read_b128 v[114:117], v84 offset:15888
	ds_read_b128 v[118:121], v84 offset:19968
	ds_read_b128 v[122:125], v84 offset:19984
	ds_read_b64 v[126:127], v85 offset:24064
	v_cndmask_b32_e64 v168, v168, 0, s[8:9]
	v_cndmask_b32_e64 v169, v169, 0, s[8:9]
	v_pk_mul_f32 v[212:213], v[22:23], v[136:137]
	v_pk_mul_f32 v[216:217], v[14:15], v[136:137]
	v_pk_mul_f32 v[214:215], v[18:19], v[140:141]
	v_pk_mul_f32 v[218:219], v[10:11], v[140:141]
	v_pk_fma_f32 v[212:213], v[24:25], v[138:139], v[212:213]
	v_pk_fma_f32 v[216:217], v[16:17], v[138:139], v[216:217]
	v_pk_fma_f32 v[214:215], v[20:21], v[142:143], v[214:215]
	v_pk_fma_f32 v[218:219], v[12:13], v[142:143], v[218:219]
	v_add_f32_e32 v226, v222, v223
	v_add_f32_e32 v227, v224, v225
	v_pk_add_f32 v[212:213], v[212:213], v[214:215]
	v_pk_add_f32 v[216:217], v[216:217], v[218:219]
	v_pk_mul_f32 v[196:197], v[22:23], v[128:129]
	v_pk_mul_f32 v[204:205], v[14:15], v[128:129]
	v_add_f32_e32 v220, v212, v213
	v_add_f32_e32 v221, v216, v217
	v_add_f32_dpp v226, v226, v226 quad_perm:[1,0,3,2] row_mask:0xf bank_mask:0xf bound_ctrl:1
	v_add_f32_dpp v227, v227, v227 quad_perm:[1,0,3,2] row_mask:0xf bank_mask:0xf bound_ctrl:1
	v_add_f32_dpp v220, v220, v220 quad_perm:[1,0,3,2] row_mask:0xf bank_mask:0xf bound_ctrl:1
	v_add_f32_dpp v221, v221, v221 quad_perm:[1,0,3,2] row_mask:0xf bank_mask:0xf bound_ctrl:1
	v_pk_mul_f32 v[198:199], v[24:25], v[130:131]
	v_pk_mul_f32 v[206:207], v[16:17], v[130:131]
	v_add_f32_dpp v226, v226, v226 quad_perm:[2,3,0,1] row_mask:0xf bank_mask:0xf bound_ctrl:1
	v_add_f32_dpp v227, v227, v227 quad_perm:[2,3,0,1] row_mask:0xf bank_mask:0xf bound_ctrl:1
	v_add_f32_dpp v220, v220, v220 quad_perm:[2,3,0,1] row_mask:0xf bank_mask:0xf bound_ctrl:1
	v_add_f32_dpp v221, v221, v221 quad_perm:[2,3,0,1] row_mask:0xf bank_mask:0xf bound_ctrl:1
	v_pk_mul_f32 v[200:201], v[18:19], v[132:133]
	v_pk_mul_f32 v[208:209], v[10:11], v[132:133]
	v_add_f32_dpp v226, v226, v226 row_half_mirror row_mask:0xf bank_mask:0xf bound_ctrl:1
	v_add_f32_dpp v227, v227, v227 row_half_mirror row_mask:0xf bank_mask:0xf bound_ctrl:1
	v_add_f32_dpp v220, v220, v220 row_half_mirror row_mask:0xf bank_mask:0xf bound_ctrl:1
	v_add_f32_dpp v221, v221, v221 row_half_mirror row_mask:0xf bank_mask:0xf bound_ctrl:1
	v_pk_mul_f32 v[202:203], v[20:21], v[134:135]
	v_pk_mul_f32 v[210:211], v[12:13], v[134:135]
	v_pk_fma_f32 v[196:197], v[168:169], v[152:153], v[196:197] op_sel_hi:[0,1,1]
	v_pk_fma_f32 v[204:205], v[168:169], v[152:153], v[204:205] op_sel:[1,0,0] op_sel_hi:[1,1,1]
	v_pk_fma_f32 v[198:199], v[168:169], v[154:155], v[198:199] op_sel_hi:[0,1,1]
	v_pk_fma_f32 v[206:207], v[168:169], v[154:155], v[206:207] op_sel:[1,0,0] op_sel_hi:[1,1,1]
	v_pk_fma_f32 v[200:201], v[168:169], v[156:157], v[200:201] op_sel_hi:[0,1,1]
	v_pk_fma_f32 v[208:209], v[168:169], v[156:157], v[208:209] op_sel:[1,0,0] op_sel_hi:[1,1,1]
	v_pk_fma_f32 v[202:203], v[168:169], v[158:159], v[202:203] op_sel_hi:[0,1,1]
	v_pk_fma_f32 v[210:211], v[168:169], v[158:159], v[210:211] op_sel:[1,0,0] op_sel_hi:[1,1,1]
	ds_write_b64 v70, v[226:227] offset:768
	v_pk_fma_f32 v[22:23], v[220:221], v[144:145], v[196:197] op_sel_hi:[0,1,1] neg_lo:[1,0,0] neg_hi:[1,0,0]
	v_pk_fma_f32 v[14:15], v[220:221], v[144:145], v[204:205] op_sel:[1,0,0] op_sel_hi:[1,1,1] neg_lo:[1,0,0] neg_hi:[1,0,0]
	v_pk_fma_f32 v[24:25], v[220:221], v[146:147], v[198:199] op_sel_hi:[0,1,1] neg_lo:[1,0,0] neg_hi:[1,0,0]
	v_pk_fma_f32 v[16:17], v[220:221], v[146:147], v[206:207] op_sel:[1,0,0] op_sel_hi:[1,1,1] neg_lo:[1,0,0] neg_hi:[1,0,0]
	v_pk_fma_f32 v[18:19], v[220:221], v[148:149], v[200:201] op_sel_hi:[0,1,1] neg_lo:[1,0,0] neg_hi:[1,0,0]
	v_pk_fma_f32 v[10:11], v[220:221], v[148:149], v[208:209] op_sel:[1,0,0] op_sel_hi:[1,1,1] neg_lo:[1,0,0] neg_hi:[1,0,0]
	v_pk_fma_f32 v[20:21], v[220:221], v[150:151], v[202:203] op_sel_hi:[0,1,1] neg_lo:[1,0,0] neg_hi:[1,0,0]
	v_pk_fma_f32 v[12:13], v[220:221], v[150:151], v[210:211] op_sel:[1,0,0] op_sel_hi:[1,1,1] neg_lo:[1,0,0] neg_hi:[1,0,0]
	v_pk_mul_f32 v[222:223], v[22:23], v[160:161]
	v_pk_mul_f32 v[224:225], v[14:15], v[160:161]
	v_pk_fma_f32 v[222:223], v[24:25], v[162:163], v[222:223]
	v_pk_fma_f32 v[224:225], v[16:17], v[162:163], v[224:225]
	v_pk_fma_f32 v[222:223], v[18:19], v[164:165], v[222:223]
	v_pk_fma_f32 v[224:225], v[10:11], v[164:165], v[224:225]
	v_pk_fma_f32 v[222:223], v[20:21], v[166:167], v[222:223]
	v_pk_fma_f32 v[224:225], v[12:13], v[166:167], v[224:225]
	s_waitcnt lgkmcnt(0)
; __device__ __forceinline__ void scan_rows(f32x2 (&X)[8], const ScanOps& o, const f32x4 (&b)[2], const f32x4 (&kd)[2], const f32x4 (&r)[2], const bool use_v, float& yA, float& yB) {
;     f32x2 aA = X[0] * o.kk[0].xy, aB = X[4] * o.kk[0].xy;
;     aA += X[1] * o.kk[0].zw; aB += X[5] * o.kk[0].zw;
;     aA += X[2] * o.kk[1].xy; aB += X[6] * o.kk[1].xy;
;     aA += X[3] * o.kk[1].zw; aB += X[7] * o.kk[1].zw;
;     const float saA = sum8(aA.x + aA.y), saB = sum8(aB.x + aB.y);
;     const f32x2 nA = (f32x2){-saA, -saA}, nB = (f32x2){-saB, -saB}, vA = (f32x2){o.v.x, o.v.x}, vB = (f32x2){o.v.y, o.v.y};
;     f32x2 tA, tB, accA, accB;
;     tA = X[0] * o.w[0].xy; tA += nA * b[0].xy; if (use_v) tA += vA * kd[0].xy; X[0] = tA; accA = tA * r[0].xy;
;     tB = X[4] * o.w[0].xy; tB += nB * b[0].xy; if (use_v) tB += vB * kd[0].xy; X[4] = tB; accB = tB * r[0].xy;
;     tA = X[1] * o.w[0].zw; tA += nA * b[0].zw; if (use_v) tA += vA * kd[0].zw; X[1] = tA; accA += tA * r[0].zw;
;     tB = X[5] * o.w[0].zw; tB += nB * b[0].zw; if (use_v) tB += vB * kd[0].zw; X[5] = tB; accB += tB * r[0].zw;
;     tA = X[2] * o.w[1].xy; tA += nA * b[1].xy; if (use_v) tA += vA * kd[1].xy; X[2] = tA; accA += tA * r[1].xy;
;     tB = X[6] * o.w[1].xy; tB += nB * b[1].xy; if (use_v) tB += vB * kd[1].xy; X[6] = tB; accB += tB * r[1].xy;
;     tA = X[3] * o.w[1].zw; tA += nA * b[1].zw; if (use_v) tA += vA * kd[1].zw; X[3] = tA; accA += tA * r[1].zw;
;     tB = X[7] * o.w[1].zw; tB += nB * b[1].zw; if (use_v) tB += vB * kd[1].zw; X[7] = tB; accB += tB * r[1].zw;
;     yA = sum8(accA.x + accA.y); yB = sum8(accB.x + accB.y);
; __device__ void phase_scan(int c, const bf16_t* PROJ, const float* k_k, const bf16_t* Wd, const bf16_t* Bd, const float* k_a, bf16_t* Y, bf16_t* Q, float* FS, float* sm) {
;     ...
;                 for (int i = 0; i < 16; i += 2) {
;                     float yA = 0.f, yB = 0.f;
;                     scan_ld(ob, obv, i + 1, B);
;                     if (roleP) A.v = (f32x2){0.f, 0.f};
;                     scan_step1(X, A, ob + i * 64, yA, yB);
;                     *(f32x2*)(obw + i * 16 + 2 * vp) = (f32x2){yA, yB};
;                     if (i + 2 < 16) scan_ld(ob, obv, i + 2, A);
;                     if (roleP) B.v = (f32x2){0.f, 0.f};
;                     scan_step1(X, B, ob + (i + 1) * 64, yA, yB);
;                     *(f32x2*)(obw + (i + 1) * 16 + 2 * vp) = (f32x2){yA, yB};
	ds_read_b128 v[128:131], v84 offset:3840
	ds_read_b128 v[132:135], v84 offset:3856
	ds_read_b128 v[136:139], v84 offset:7936
	ds_read_b128 v[140:143], v84 offset:7952
	ds_read_b128 v[144:147], v84 offset:12032
	ds_read_b128 v[148:151], v84 offset:12048
	ds_read_b128 v[152:155], v84 offset:16128
	ds_read_b128 v[156:159], v84 offset:16144
	ds_read_b128 v[160:163], v84 offset:20224
	ds_read_b128 v[164:167], v84 offset:20240
	ds_read_b64 v[168:169], v85 offset:24320
	v_cndmask_b32_e64 v126, v126, 0, s[8:9]
	v_cndmask_b32_e64 v127, v127, 0, s[8:9]
	v_pk_mul_f32 v[212:213], v[22:23], v[94:95]
	v_pk_mul_f32 v[216:217], v[14:15], v[94:95]
	v_pk_mul_f32 v[214:215], v[18:19], v[98:99]
	v_pk_mul_f32 v[218:219], v[10:11], v[98:99]
	v_pk_fma_f32 v[212:213], v[24:25], v[96:97], v[212:213]
	v_pk_fma_f32 v[216:217], v[16:17], v[96:97], v[216:217]
	v_pk_fma_f32 v[214:215], v[20:21], v[100:101], v[214:215]
	v_pk_fma_f32 v[218:219], v[12:13], v[100:101], v[218:219]
	v_add_f32_e32 v226, v222, v223
	v_add_f32_e32 v227, v224, v225
	v_pk_add_f32 v[212:213], v[212:213], v[214:215]
	v_pk_add_f32 v[216:217], v[216:217], v[218:219]
	v_pk_mul_f32 v[196:197], v[22:23], v[86:87]
	v_pk_mul_f32 v[204:205], v[14:15], v[86:87]
	v_add_f32_e32 v220, v212, v213
	v_add_f32_e32 v221, v216, v217
	v_add_f32_dpp v226, v226, v226 quad_perm:[1,0,3,2] row_mask:0xf bank_mask:0xf bound_ctrl:1
	v_add_f32_dpp v227, v227, v227 quad_perm:[1,0,3,2] row_mask:0xf bank_mask:0xf bound_ctrl:1
	v_add_f32_dpp v220, v220, v220 quad_perm:[1,0,3,2] row_mask:0xf bank_mask:0xf bound_ctrl:1
	v_add_f32_dpp v221, v221, v221 quad_perm:[1,0,3,2] row_mask:0xf bank_mask:0xf bound_ctrl:1
	v_pk_mul_f32 v[198:199], v[24:25], v[88:89]
	v_pk_mul_f32 v[206:207], v[16:17], v[88:89]
	v_add_f32_dpp v226, v226, v226 quad_perm:[2,3,0,1] row_mask:0xf bank_mask:0xf bound_ctrl:1
	v_add_f32_dpp v227, v227, v227 quad_perm:[2,3,0,1] row_mask:0xf bank_mask:0xf bound_ctrl:1
	v_add_f32_dpp v220, v220, v220 quad_perm:[2,3,0,1] row_mask:0xf bank_mask:0xf bound_ctrl:1
	v_add_f32_dpp v221, v221, v221 quad_perm:[2,3,0,1] row_mask:0xf bank_mask:0xf bound_ctrl:1
	v_pk_mul_f32 v[200:201], v[18:19], v[90:91]
	v_pk_mul_f32 v[208:209], v[10:11], v[90:91]
	v_add_f32_dpp v226, v226, v226 row_half_mirror row_mask:0xf bank_mask:0xf bound_ctrl:1
	v_add_f32_dpp v227, v227, v227 row_half_mirror row_mask:0xf bank_mask:0xf bound_ctrl:1
	v_add_f32_dpp v220, v220, v220 row_half_mirror row_mask:0xf bank_mask:0xf bound_ctrl:1
	v_add_f32_dpp v221, v221, v221 row_half_mirror row_mask:0xf bank_mask:0xf bound_ctrl:1
	v_pk_mul_f32 v[202:203], v[20:21], v[92:93]
	v_pk_mul_f32 v[210:211], v[12:13], v[92:93]
	v_pk_fma_f32 v[196:197], v[126:127], v[110:111], v[196:197] op_sel_hi:[0,1,1]
	v_pk_fma_f32 v[204:205], v[126:127], v[110:111], v[204:205] op_sel:[1,0,0] op_sel_hi:[1,1,1]
	v_pk_fma_f32 v[198:199], v[126:127], v[112:113], v[198:199] op_sel_hi:[0,1,1]
	v_pk_fma_f32 v[206:207], v[126:127], v[112:113], v[206:207] op_sel:[1,0,0] op_sel_hi:[1,1,1]
	v_pk_fma_f32 v[200:201], v[126:127], v[114:115], v[200:201] op_sel_hi:[0,1,1]
	v_pk_fma_f32 v[208:209], v[126:127], v[114:115], v[208:209] op_sel:[1,0,0] op_sel_hi:[1,1,1]
	v_pk_fma_f32 v[202:203], v[126:127], v[116:117], v[202:203] op_sel_hi:[0,1,1]
	v_pk_fma_f32 v[210:211], v[126:127], v[116:117], v[210:211] op_sel:[1,0,0] op_sel_hi:[1,1,1]
	ds_write_b64 v70, v[226:227] offset:832
	v_pk_fma_f32 v[22:23], v[220:221], v[102:103], v[196:197] op_sel_hi:[0,1,1] neg_lo:[1,0,0] neg_hi:[1,0,0]
	v_pk_fma_f32 v[14:15], v[220:221], v[102:103], v[204:205] op_sel:[1,0,0] op_sel_hi:[1,1,1] neg_lo:[1,0,0] neg_hi:[1,0,0]
	v_pk_fma_f32 v[24:25], v[220:221], v[104:105], v[198:199] op_sel_hi:[0,1,1] neg_lo:[1,0,0] neg_hi:[1,0,0]
	v_pk_fma_f32 v[16:17], v[220:221], v[104:105], v[206:207] op_sel:[1,0,0] op_sel_hi:[1,1,1] neg_lo:[1,0,0] neg_hi:[1,0,0]
	v_pk_fma_f32 v[18:19], v[220:221], v[106:107], v[200:201] op_sel_hi:[0,1,1] neg_lo:[1,0,0] neg_hi:[1,0,0]
	v_pk_fma_f32 v[10:11], v[220:221], v[106:107], v[208:209] op_sel:[1,0,0] op_sel_hi:[1,1,1] neg_lo:[1,0,0] neg_hi:[1,0,0]
	v_pk_fma_f32 v[20:21], v[220:221], v[108:109], v[202:203] op_sel_hi:[0,1,1] neg_lo:[1,0,0] neg_hi:[1,0,0]
	v_pk_fma_f32 v[12:13], v[220:221], v[108:109], v[210:211] op_sel:[1,0,0] op_sel_hi:[1,1,1] neg_lo:[1,0,0] neg_hi:[1,0,0]
	v_pk_mul_f32 v[222:223], v[22:23], v[118:119]
	v_pk_mul_f32 v[224:225], v[14:15], v[118:119]
	v_pk_fma_f32 v[222:223], v[24:25], v[120:121], v[222:223]
	v_pk_fma_f32 v[224:225], v[16:17], v[120:121], v[224:225]
	v_pk_fma_f32 v[222:223], v[18:19], v[122:123], v[222:223]
	v_pk_fma_f32 v[224:225], v[10:11], v[122:123], v[224:225]
	v_pk_fma_f32 v[222:223], v[20:21], v[124:125], v[222:223]
	v_pk_fma_f32 v[224:225], v[12:13], v[124:125], v[224:225]
	s_waitcnt lgkmcnt(0)
; __device__ __forceinline__ void scan_rows(f32x2 (&X)[8], const ScanOps& o, const f32x4 (&b)[2], const f32x4 (&kd)[2], const f32x4 (&r)[2], const bool use_v, float& yA, float& yB) {
;     f32x2 aA = X[0] * o.kk[0].xy, aB = X[4] * o.kk[0].xy;
;     aA += X[1] * o.kk[0].zw; aB += X[5] * o.kk[0].zw;
;     aA += X[2] * o.kk[1].xy; aB += X[6] * o.kk[1].xy;
;     aA += X[3] * o.kk[1].zw; aB += X[7] * o.kk[1].zw;
;     const float saA = sum8(aA.x + aA.y), saB = sum8(aB.x + aB.y);
;     const f32x2 nA = (f32x2){-saA, -saA}, nB = (f32x2){-saB, -saB}, vA = (f32x2){o.v.x, o.v.x}, vB = (f32x2){o.v.y, o.v.y};
;     f32x2 tA, tB, accA, accB;
;     tA = X[0] * o.w[0].xy; tA += nA * b[0].xy; if (use_v) tA += vA * kd[0].xy; X[0] = tA; accA = tA * r[0].xy;
;     tB = X[4] * o.w[0].xy; tB += nB * b[0].xy; if (use_v) tB += vB * kd[0].xy; X[4] = tB; accB = tB * r[0].xy;
;     tA = X[1] * o.w[0].zw; tA += nA * b[0].zw; if (use_v) tA += vA * kd[0].zw; X[1] = tA; accA += tA * r[0].zw;
;     tB = X[5] * o.w[0].zw; tB += nB * b[0].zw; if (use_v) tB += vB * kd[0].zw; X[5] = tB; accB += tB * r[0].zw;
;     tA = X[2] * o.w[1].xy; tA += nA * b[1].xy; if (use_v) tA += vA * kd[1].xy; X[2] = tA; accA += tA * r[1].xy;
;     tB = X[6] * o.w[1].xy; tB += nB * b[1].xy; if (use_v) tB += vB * kd[1].xy; X[6] = tB; accB += tB * r[1].xy;
;     tA = X[3] * o.w[1].zw; tA += nA * b[1].zw; if (use_v) tA += vA * kd[1].zw; X[3] = tA; accA += tA * r[1].zw;
;     tB = X[7] * o.w[1].zw; tB += nB * b[1].zw; if (use_v) tB += vB * kd[1].zw; X[7] = tB; accB += tB * r[1].zw;
;     yA = sum8(accA.x + accA.y); yB = sum8(accB.x + accB.y);
; __device__ void phase_scan(int c, const bf16_t* PROJ, const float* k_k, const bf16_t* Wd, const bf16_t* Bd, const float* k_a, bf16_t* Y, bf16_t* Q, float* FS, float* sm) {
;     ...
;                 __builtin_amdgcn_wave_barrier(); asm volatile("s_waitcnt lgkmcnt(0)" ::: "memory");
;                 { const int st = lane >> 2, v4 = (lane & 3) * 4;
;                   const int g = g0 + ci * 16 + st; const int t = dir ? (L - 1 - g) : g;
;                   const size_t o = ((size_t)dir * TCH + (size_t)seq * L + t) * 512 + h * 64 + wq * 16 + v4;
;                   const f32x4 yv = *(const f32x4*)(obw + st * 16 + v4);
;                   uint2 pk; pk.x = pack2(yv[0], yv[1]); pk.y = pack2(yv[2], yv[3]); *(uint2*)(gout + o) = pk; }
;                 __builtin_amdgcn_wave_barrier();
	v_cndmask_b32_e64 v168, v168, 0, s[8:9]
	v_cndmask_b32_e64 v169, v169, 0, s[8:9]
	v_pk_mul_f32 v[212:213], v[22:23], v[136:137]
	v_pk_mul_f32 v[216:217], v[14:15], v[136:137]
	v_pk_mul_f32 v[214:215], v[18:19], v[140:141]
	v_pk_mul_f32 v[218:219], v[10:11], v[140:141]
	v_pk_fma_f32 v[212:213], v[24:25], v[138:139], v[212:213]
	v_pk_fma_f32 v[216:217], v[16:17], v[138:139], v[216:217]
	v_pk_fma_f32 v[214:215], v[20:21], v[142:143], v[214:215]
	v_pk_fma_f32 v[218:219], v[12:13], v[142:143], v[218:219]
	v_add_f32_e32 v226, v222, v223
	v_add_f32_e32 v227, v224, v225
	v_pk_add_f32 v[212:213], v[212:213], v[214:215]
	v_pk_add_f32 v[216:217], v[216:217], v[218:219]
	v_pk_mul_f32 v[196:197], v[22:23], v[128:129]
	v_pk_mul_f32 v[204:205], v[14:15], v[128:129]
	v_add_f32_e32 v220, v212, v213
	v_add_f32_e32 v221, v216, v217
	v_add_f32_dpp v226, v226, v226 quad_perm:[1,0,3,2] row_mask:0xf bank_mask:0xf bound_ctrl:1
	v_add_f32_dpp v227, v227, v227 quad_perm:[1,0,3,2] row_mask:0xf bank_mask:0xf bound_ctrl:1
	v_add_f32_dpp v220, v220, v220 quad_perm:[1,0,3,2] row_mask:0xf bank_mask:0xf bound_ctrl:1
	v_add_f32_dpp v221, v221, v221 quad_perm:[1,0,3,2] row_mask:0xf bank_mask:0xf bound_ctrl:1
	v_pk_mul_f32 v[198:199], v[24:25], v[130:131]
	v_pk_mul_f32 v[206:207], v[16:17], v[130:131]
	v_add_f32_dpp v226, v226, v226 quad_perm:[2,3,0,1] row_mask:0xf bank_mask:0xf bound_ctrl:1
	v_add_f32_dpp v227, v227, v227 quad_perm:[2,3,0,1] row_mask:0xf bank_mask:0xf bound_ctrl:1
	v_add_f32_dpp v220, v220, v220 quad_perm:[2,3,0,1] row_mask:0xf bank_mask:0xf bound_ctrl:1
	v_add_f32_dpp v221, v221, v221 quad_perm:[2,3,0,1] row_mask:0xf bank_mask:0xf bound_ctrl:1
	v_pk_mul_f32 v[200:201], v[18:19], v[132:133]
	v_pk_mul_f32 v[208:209], v[10:11], v[132:133]
	v_add_f32_dpp v226, v226, v226 row_half_mirror row_mask:0xf bank_mask:0xf bound_ctrl:1
	v_add_f32_dpp v227, v227, v227 row_half_mirror row_mask:0xf bank_mask:0xf bound_ctrl:1
	v_add_f32_dpp v220, v220, v220 row_half_mirror row_mask:0xf bank_mask:0xf bound_ctrl:1
	v_add_f32_dpp v221, v221, v221 row_half_mirror row_mask:0xf bank_mask:0xf bound_ctrl:1
	v_pk_mul_f32 v[202:203], v[20:21], v[134:135]
	v_pk_mul_f32 v[210:211], v[12:13], v[134:135]
	v_pk_fma_f32 v[196:197], v[168:169], v[152:153], v[196:197] op_sel_hi:[0,1,1]
	v_pk_fma_f32 v[204:205], v[168:169], v[152:153], v[204:205] op_sel:[1,0,0] op_sel_hi:[1,1,1]
	v_pk_fma_f32 v[198:199], v[168:169], v[154:155], v[198:199] op_sel_hi:[0,1,1]
	v_pk_fma_f32 v[206:207], v[168:169], v[154:155], v[206:207] op_sel:[1,0,0] op_sel_hi:[1,1,1]
	v_pk_fma_f32 v[200:201], v[168:169], v[156:157], v[200:201] op_sel_hi:[0,1,1]
	v_pk_fma_f32 v[208:209], v[168:169], v[156:157], v[208:209] op_sel:[1,0,0] op_sel_hi:[1,1,1]
	v_pk_fma_f32 v[202:203], v[168:169], v[158:159], v[202:203] op_sel_hi:[0,1,1]
	v_pk_fma_f32 v[210:211], v[168:169], v[158:159], v[210:211] op_sel:[1,0,0] op_sel_hi:[1,1,1]
	ds_write_b64 v70, v[226:227] offset:896
	v_pk_fma_f32 v[22:23], v[220:221], v[144:145], v[196:197] op_sel_hi:[0,1,1] neg_lo:[1,0,0] neg_hi:[1,0,0]
	v_pk_fma_f32 v[14:15], v[220:221], v[144:145], v[204:205] op_sel:[1,0,0] op_sel_hi:[1,1,1] neg_lo:[1,0,0] neg_hi:[1,0,0]
	v_pk_fma_f32 v[24:25], v[220:221], v[146:147], v[198:199] op_sel_hi:[0,1,1] neg_lo:[1,0,0] neg_hi:[1,0,0]
	v_pk_fma_f32 v[16:17], v[220:221], v[146:147], v[206:207] op_sel:[1,0,0] op_sel_hi:[1,1,1] neg_lo:[1,0,0] neg_hi:[1,0,0]
	v_pk_fma_f32 v[18:19], v[220:221], v[148:149], v[200:201] op_sel_hi:[0,1,1] neg_lo:[1,0,0] neg_hi:[1,0,0]
	v_pk_fma_f32 v[10:11], v[220:221], v[148:149], v[208:209] op_sel:[1,0,0] op_sel_hi:[1,1,1] neg_lo:[1,0,0] neg_hi:[1,0,0]
	v_pk_fma_f32 v[20:21], v[220:221], v[150:151], v[202:203] op_sel_hi:[0,1,1] neg_lo:[1,0,0] neg_hi:[1,0,0]
	v_pk_fma_f32 v[12:13], v[220:221], v[150:151], v[210:211] op_sel:[1,0,0] op_sel_hi:[1,1,1] neg_lo:[1,0,0] neg_hi:[1,0,0]
	v_pk_mul_f32 v[222:223], v[22:23], v[160:161]
	v_pk_mul_f32 v[224:225], v[14:15], v[160:161]
	v_pk_fma_f32 v[222:223], v[24:25], v[162:163], v[222:223]
	v_pk_fma_f32 v[224:225], v[16:17], v[162:163], v[224:225]
	v_pk_fma_f32 v[222:223], v[18:19], v[164:165], v[222:223]
	v_pk_fma_f32 v[224:225], v[10:11], v[164:165], v[224:225]
	v_pk_fma_f32 v[222:223], v[20:21], v[166:167], v[222:223]
	v_pk_fma_f32 v[224:225], v[12:13], v[166:167], v[224:225]
	v_add_f32_e32 v226, v222, v223
	v_add_f32_e32 v227, v224, v225
	s_nop 0
	v_add_f32_dpp v226, v226, v226 quad_perm:[1,0,3,2] row_mask:0xf bank_mask:0xf bound_ctrl:1
	v_add_f32_dpp v227, v227, v227 quad_perm:[1,0,3,2] row_mask:0xf bank_mask:0xf bound_ctrl:1
	s_nop 0
	v_add_f32_dpp v226, v226, v226 quad_perm:[2,3,0,1] row_mask:0xf bank_mask:0xf bound_ctrl:1
	v_add_f32_dpp v227, v227, v227 quad_perm:[2,3,0,1] row_mask:0xf bank_mask:0xf bound_ctrl:1
	s_nop 0
	v_add_f32_dpp v226, v226, v226 row_half_mirror row_mask:0xf bank_mask:0xf bound_ctrl:1
	v_add_f32_dpp v227, v227, v227 row_half_mirror row_mask:0xf bank_mask:0xf bound_ctrl:1
	ds_write_b64 v70, v[226:227] offset:960
	s_waitcnt lgkmcnt(0)
	v_add_u32_e32 v84, s40, v82
	v_cndmask_b32_e64 v88, v83, v84, s[10:11]
	ds_read_b128 v[84:87], v72
	v_ashrrev_i32_e32 v89, 31, v88
	v_lshl_add_u64 v[88:89], v[60:61], 0, v[88:89]
	v_lshlrev_b64 v[88:89], 10, v[88:89]
	v_lshl_add_u64 v[88:89], v[62:63], 0, v[88:89]
	s_waitcnt lgkmcnt(0)
	v_and_b32_sdwa v90, v86, v185 dst_sel:DWORD dst_unused:UNUSED_PAD src0_sel:WORD_1 src1_sel:DWORD
	v_and_b32_sdwa v91, v84, v185 dst_sel:DWORD dst_unused:UNUSED_PAD src0_sel:WORD_1 src1_sel:DWORD
	v_add3_u32 v84, v84, v91, s46
	v_add3_u32 v86, v86, v90, s46
	v_and_b32_sdwa v90, v87, v185 dst_sel:DWORD dst_unused:UNUSED_PAD src0_sel:WORD_1 src1_sel:DWORD
	v_and_b32_sdwa v91, v85, v185 dst_sel:DWORD dst_unused:UNUSED_PAD src0_sel:WORD_1 src1_sel:DWORD
	v_add3_u32 v87, v87, v90, s46
	v_add3_u32 v85, v85, v91, s46
	v_and_b32_e32 v87, 0xffff0000, v87
	v_and_b32_e32 v90, 0xffff0000, v85
	v_or_b32_sdwa v85, v87, v86 dst_sel:DWORD dst_unused:UNUSED_PAD src0_sel:DWORD src1_sel:WORD_1
	v_or_b32_sdwa v84, v90, v84 dst_sel:DWORD dst_unused:UNUSED_PAD src0_sel:DWORD src1_sel:WORD_1
	global_store_dwordx2 v[88:89], v[84:85], off
	s_branch .LBB0_71
